# v5 + GEMM K-loops: LDS-DMA issues converted from 64-bit VGPR addresses to saddr + 32-bit offset (80 VALU 64-bit adds removed)
# baseline (speedup 1.0000x reference)
.LBB0_172:
	ds_read_b128 v[148:151], v165
	ds_read_b128 v[152:155], v165 offset:1024
	ds_read_b128 v[156:159], v165 offset:2048
	ds_read_b128 v[168:171], v165 offset:3072
	ds_read_b128 v[172:175], v166
	ds_read_b128 v[176:179], v166 offset:1024
	ds_read_b128 v[180:183], v166 offset:2048
	ds_read_b128 v[184:187], v166 offset:3072
	s_add_u32 s30, s28, 0xfff00080
	s_addc_u32 s31, s29, -1
	s_cmp_eq_u32 s56, 60
	s_cselect_b32 s35, s21, s31
	s_cselect_b32 s34, s27, s30
	s_cselect_b32 s31, s19, s55
	s_cselect_b32 s30, s53, s54
	s_add_i32 m0, s38, 0xc000
	ds_read_b128 v[188:191], v167
	ds_read_b128 v[192:195], v167 offset:1024
	ds_read_b128 v[196:199], v167 offset:2048
	ds_read_b128 v[200:203], v167 offset:3072
	ds_read_b128 v[204:207], v167 offset:4096
	ds_read_b128 v[208:211], v167 offset:5120
	ds_read_b128 v[212:215], v167 offset:6144
	ds_read_b128 v[216:219], v167 offset:7168
	s_cmp_lg_u32 s32, 0
	s_cbranch_scc0 .Lrebal_skip_172
	s_mov_b32 m0, s43
	s_nop 0
	global_load_lds_dwordx4 v[222:223], off
	s_mov_b32 m0, s44
	s_nop 0
	global_load_lds_dwordx4 v[224:225], off
.Lrebal_skip_172:
	s_add_i32 m0, s38, 0xc000
	s_nop 0
	global_load_lds_dwordx4 v140, s[28:29]
	s_add_i32 m0, s38, 0xe000
	s_nop 0
	global_load_lds_dwordx4 v142, s[28:29]
	s_waitcnt vmcnt(8)
	s_waitcnt lgkmcnt(0)
	s_setprio 1
	s_barrier
	v_mfma_f32_16x16x32_bf16 v[126:129], v[148:151], v[188:191], v[126:129]
	v_mfma_f32_16x16x32_bf16 v[122:125], v[156:159], v[188:191], v[122:125]
	v_mfma_f32_16x16x32_bf16 v[110:113], v[148:151], v[196:199], v[110:113]
	v_mfma_f32_16x16x32_bf16 v[106:109], v[156:159], v[196:199], v[106:109]
	v_mfma_f32_16x16x32_bf16 v[94:97], v[148:151], v[204:207], v[94:97]
	v_mfma_f32_16x16x32_bf16 v[90:93], v[156:159], v[204:207], v[90:93]
	v_mfma_f32_16x16x32_bf16 v[86:89], v[148:151], v[212:215], v[86:89]
	v_mfma_f32_16x16x32_bf16 v[78:81], v[156:159], v[212:215], v[78:81]
	v_mfma_f32_16x16x32_bf16 v[126:129], v[152:155], v[192:195], v[126:129]
	v_mfma_f32_16x16x32_bf16 v[122:125], v[168:171], v[192:195], v[122:125]
	v_mfma_f32_16x16x32_bf16 v[110:113], v[152:155], v[200:203], v[110:113]
	v_mfma_f32_16x16x32_bf16 v[106:109], v[168:171], v[200:203], v[106:109]
	v_mfma_f32_16x16x32_bf16 v[94:97], v[152:155], v[208:211], v[94:97]
	v_mfma_f32_16x16x32_bf16 v[90:93], v[168:171], v[208:211], v[90:93]
	v_mfma_f32_16x16x32_bf16 v[86:89], v[152:155], v[216:219], v[86:89]
	v_mfma_f32_16x16x32_bf16 v[78:81], v[168:171], v[216:219], v[78:81]
	v_mfma_f32_16x16x32_bf16 v[118:121], v[172:175], v[188:191], v[118:121]
	v_mfma_f32_16x16x32_bf16 v[114:117], v[180:183], v[188:191], v[114:117]
	v_mfma_f32_16x16x32_bf16 v[102:105], v[172:175], v[196:199], v[102:105]
	v_mfma_f32_16x16x32_bf16 v[98:101], v[180:183], v[196:199], v[98:101]
	v_mfma_f32_16x16x32_bf16 v[82:85], v[172:175], v[204:207], v[82:85]
	v_mfma_f32_16x16x32_bf16 v[74:77], v[180:183], v[204:207], v[74:77]
	v_mfma_f32_16x16x32_bf16 v[70:73], v[172:175], v[212:215], v[70:73]
	v_mfma_f32_16x16x32_bf16 v[66:69], v[180:183], v[212:215], v[66:69]
	v_mfma_f32_16x16x32_bf16 v[118:121], v[176:179], v[192:195], v[118:121]
	v_mfma_f32_16x16x32_bf16 v[114:117], v[184:187], v[192:195], v[114:117]
	v_mfma_f32_16x16x32_bf16 v[102:105], v[176:179], v[200:203], v[102:105]
	v_mfma_f32_16x16x32_bf16 v[98:101], v[184:187], v[200:203], v[98:101]
	v_mfma_f32_16x16x32_bf16 v[82:85], v[176:179], v[208:211], v[82:85]
	v_mfma_f32_16x16x32_bf16 v[74:77], v[184:187], v[208:211], v[74:77]
	v_mfma_f32_16x16x32_bf16 v[70:73], v[176:179], v[216:219], v[70:73]
	v_mfma_f32_16x16x32_bf16 v[66:69], v[184:187], v[216:219], v[66:69]
	s_setprio 0
	s_barrier
	s_add_i32 s57, s46, s33
	v_lshl_add_u64 v[160:161], s[30:31], 0, v[134:135]
	s_mov_b32 m0, s57
	ds_read_b128 v[188:191], v167 offset:16384
	ds_read_b128 v[192:195], v167 offset:17408
	ds_read_b128 v[196:199], v167 offset:18432
	ds_read_b128 v[200:203], v167 offset:19456
	ds_read_b128 v[204:207], v167 offset:20480
	ds_read_b128 v[208:211], v167 offset:21504
	ds_read_b128 v[212:215], v167 offset:22528
	ds_read_b128 v[216:219], v167 offset:23552
	global_load_lds_dwordx4 v134, s[30:31]
	s_add_i32 m0, s57, 0x2000
	s_add_u32 s58, s30, 0x100000
	v_lshl_add_u64 v[220:221], s[30:31], 0, v[130:131]
	s_addc_u32 s59, s31, 0
	s_add_i32 s57, s47, s33
	global_load_lds_dwordx4 v130, s[30:31]
	s_mov_b32 m0, s57
	v_lshl_add_u64 v[224:225], s[34:35], 0, v[132:133]
	global_load_lds_dwordx4 v134, s[58:59]
	s_add_i32 m0, s57, 0x2000
	s_nop 0
	global_load_lds_dwordx4 v130, s[58:59]
	v_lshl_add_u64 v[222:223], s[34:35], 0, v[136:137]
	s_waitcnt vmcnt(6)
	s_waitcnt lgkmcnt(0)
	s_setprio 1
	s_barrier
	v_mfma_f32_16x16x32_bf16 v[62:65], v[148:151], v[188:191], v[62:65]
	v_mfma_f32_16x16x32_bf16 v[58:61], v[156:159], v[188:191], v[58:61]
	v_mfma_f32_16x16x32_bf16 v[46:49], v[148:151], v[196:199], v[46:49]
	v_mfma_f32_16x16x32_bf16 v[42:45], v[156:159], v[196:199], v[42:45]
	v_mfma_f32_16x16x32_bf16 v[30:33], v[148:151], v[204:207], v[30:33]
	v_mfma_f32_16x16x32_bf16 v[26:29], v[156:159], v[204:207], v[26:29]
	v_mfma_f32_16x16x32_bf16 v[14:17], v[148:151], v[212:215], v[14:17]
	v_mfma_f32_16x16x32_bf16 v[10:13], v[156:159], v[212:215], v[10:13]
	v_mfma_f32_16x16x32_bf16 v[62:65], v[152:155], v[192:195], v[62:65]
	v_mfma_f32_16x16x32_bf16 v[58:61], v[168:171], v[192:195], v[58:61]
	v_mfma_f32_16x16x32_bf16 v[46:49], v[152:155], v[200:203], v[46:49]
	v_mfma_f32_16x16x32_bf16 v[42:45], v[168:171], v[200:203], v[42:45]
	v_mfma_f32_16x16x32_bf16 v[30:33], v[152:155], v[208:211], v[30:33]
	v_mfma_f32_16x16x32_bf16 v[26:29], v[168:171], v[208:211], v[26:29]
	v_mfma_f32_16x16x32_bf16 v[14:17], v[152:155], v[216:219], v[14:17]
	v_mfma_f32_16x16x32_bf16 v[10:13], v[168:171], v[216:219], v[10:13]
	v_mfma_f32_16x16x32_bf16 v[54:57], v[172:175], v[188:191], v[54:57]
	v_mfma_f32_16x16x32_bf16 v[50:53], v[180:183], v[188:191], v[50:53]
	v_mfma_f32_16x16x32_bf16 v[38:41], v[172:175], v[196:199], v[38:41]
	v_mfma_f32_16x16x32_bf16 v[34:37], v[180:183], v[196:199], v[34:37]
	v_mfma_f32_16x16x32_bf16 v[22:25], v[172:175], v[204:207], v[22:25]
	v_mfma_f32_16x16x32_bf16 v[18:21], v[180:183], v[204:207], v[18:21]
	v_mfma_f32_16x16x32_bf16 v[6:9], v[172:175], v[212:215], v[6:9]
	v_mfma_f32_16x16x32_bf16 v[2:5], v[180:183], v[212:215], v[2:5]
	v_mfma_f32_16x16x32_bf16 v[54:57], v[176:179], v[192:195], v[54:57]
	v_mfma_f32_16x16x32_bf16 v[50:53], v[184:187], v[192:195], v[50:53]
	v_mfma_f32_16x16x32_bf16 v[38:41], v[176:179], v[200:203], v[38:41]
	v_mfma_f32_16x16x32_bf16 v[34:37], v[184:187], v[200:203], v[34:37]
	v_mfma_f32_16x16x32_bf16 v[22:25], v[176:179], v[208:211], v[22:25]
	v_mfma_f32_16x16x32_bf16 v[18:21], v[184:187], v[208:211], v[18:21]
	v_mfma_f32_16x16x32_bf16 v[6:9], v[176:179], v[216:219], v[6:9]
	v_mfma_f32_16x16x32_bf16 v[2:5], v[184:187], v[216:219], v[2:5]
	s_setprio 0
	s_barrier
	s_add_i32 s57, 0, 0x18000
	s_add_i32 s58, 0, 0x1c000
	v_add_u32_e32 v168, s57, v163
	v_add_u32_e32 v184, s58, v163
	ds_read_b128 v[148:151], v168
	ds_read_b128 v[152:155], v168 offset:1024
	ds_read_b128 v[156:159], v168 offset:2048
	ds_read_b128 v[168:171], v168 offset:3072
	ds_read_b128 v[172:175], v184
	ds_read_b128 v[176:179], v184 offset:1024
	ds_read_b128 v[180:183], v184 offset:2048
	ds_read_b128 v[184:187], v184 offset:3072
	s_add_u32 s34, s34, 0x100000
	s_addc_u32 s35, s35, 0
	s_mov_b32 m0, s40
	ds_read_b128 v[188:191], v167 offset:32768
	ds_read_b128 v[192:195], v167 offset:33792
	ds_read_b128 v[196:199], v167 offset:34816
	ds_read_b128 v[200:203], v167 offset:35840
	ds_read_b128 v[204:207], v167 offset:36864
	ds_read_b128 v[208:211], v167 offset:37888
	ds_read_b128 v[212:215], v167 offset:38912
	ds_read_b128 v[216:219], v167 offset:39936
	s_mov_b32 m0, s38
	s_nop 0
	global_load_lds_dwordx4 v[222:223], off
	s_mov_b32 m0, s39
	s_nop 0
	global_load_lds_dwordx4 v[224:225], off
	s_mov_b32 m0, s40
	s_nop 0
	global_load_lds_dwordx4 v136, s[34:35]
	s_mov_b32 m0, s41
	s_nop 0
	global_load_lds_dwordx4 v132, s[34:35]
	s_waitcnt vmcnt(8)
	s_waitcnt lgkmcnt(0)
	s_setprio 1
	s_barrier
	v_mfma_f32_16x16x32_bf16 v[126:129], v[148:151], v[188:191], v[126:129]
	v_mfma_f32_16x16x32_bf16 v[122:125], v[156:159], v[188:191], v[122:125]
	v_mfma_f32_16x16x32_bf16 v[110:113], v[148:151], v[196:199], v[110:113]
	v_mfma_f32_16x16x32_bf16 v[106:109], v[156:159], v[196:199], v[106:109]
	v_mfma_f32_16x16x32_bf16 v[94:97], v[148:151], v[204:207], v[94:97]
	v_mfma_f32_16x16x32_bf16 v[90:93], v[156:159], v[204:207], v[90:93]
	v_mfma_f32_16x16x32_bf16 v[86:89], v[148:151], v[212:215], v[86:89]
	v_mfma_f32_16x16x32_bf16 v[78:81], v[156:159], v[212:215], v[78:81]
	v_mfma_f32_16x16x32_bf16 v[126:129], v[152:155], v[192:195], v[126:129]
	v_mfma_f32_16x16x32_bf16 v[122:125], v[168:171], v[192:195], v[122:125]
	v_mfma_f32_16x16x32_bf16 v[110:113], v[152:155], v[200:203], v[110:113]
	v_mfma_f32_16x16x32_bf16 v[106:109], v[168:171], v[200:203], v[106:109]
	v_mfma_f32_16x16x32_bf16 v[94:97], v[152:155], v[208:211], v[94:97]
	v_mfma_f32_16x16x32_bf16 v[90:93], v[168:171], v[208:211], v[90:93]
	v_mfma_f32_16x16x32_bf16 v[86:89], v[152:155], v[216:219], v[86:89]
	v_mfma_f32_16x16x32_bf16 v[78:81], v[168:171], v[216:219], v[78:81]
	v_mfma_f32_16x16x32_bf16 v[118:121], v[172:175], v[188:191], v[118:121]
	v_mfma_f32_16x16x32_bf16 v[114:117], v[180:183], v[188:191], v[114:117]
	v_mfma_f32_16x16x32_bf16 v[102:105], v[172:175], v[196:199], v[102:105]
	v_mfma_f32_16x16x32_bf16 v[98:101], v[180:183], v[196:199], v[98:101]
	v_mfma_f32_16x16x32_bf16 v[82:85], v[172:175], v[204:207], v[82:85]
	v_mfma_f32_16x16x32_bf16 v[74:77], v[180:183], v[204:207], v[74:77]
	v_mfma_f32_16x16x32_bf16 v[70:73], v[172:175], v[212:215], v[70:73]
	v_mfma_f32_16x16x32_bf16 v[66:69], v[180:183], v[212:215], v[66:69]
	v_mfma_f32_16x16x32_bf16 v[118:121], v[176:179], v[192:195], v[118:121]
	v_mfma_f32_16x16x32_bf16 v[114:117], v[184:187], v[192:195], v[114:117]
	v_mfma_f32_16x16x32_bf16 v[102:105], v[176:179], v[200:203], v[102:105]
	v_mfma_f32_16x16x32_bf16 v[98:101], v[184:187], v[200:203], v[98:101]
	v_mfma_f32_16x16x32_bf16 v[82:85], v[176:179], v[208:211], v[82:85]
	v_mfma_f32_16x16x32_bf16 v[74:77], v[184:187], v[208:211], v[74:77]
	v_mfma_f32_16x16x32_bf16 v[70:73], v[176:179], v[216:219], v[70:73]
	v_mfma_f32_16x16x32_bf16 v[66:69], v[184:187], v[216:219], v[66:69]
	s_setprio 0
	s_barrier
	s_add_i32 s34, s57, s33
	v_lshl_add_u64 v[160:161], v[160:161], 0, s[8:9]
	s_mov_b32 m0, s34
	ds_read_b128 v[188:191], v167 offset:49152
	ds_read_b128 v[192:195], v167 offset:50176
	ds_read_b128 v[196:199], v167 offset:51200
	ds_read_b128 v[200:203], v167 offset:52224
	ds_read_b128 v[204:207], v167 offset:53248
	ds_read_b128 v[208:211], v167 offset:54272
	ds_read_b128 v[212:215], v167 offset:55296
	ds_read_b128 v[216:219], v167 offset:56320
	global_load_lds_dwordx4 v[160:161], off
	s_add_i32 m0, s34, 0x2000
	s_add_u32 s30, s30, 0x100080
	v_lshl_add_u64 v[160:161], v[220:221], 0, s[8:9]
	s_addc_u32 s31, s31, 0
	s_add_i32 s34, s58, s33
	global_load_lds_dwordx4 v[160:161], off
	s_mov_b32 m0, s34
	s_nop 0
	global_load_lds_dwordx4 v134, s[30:31]
	s_add_i32 m0, s34, 0x2000
	s_nop 0
	global_load_lds_dwordx4 v130, s[30:31]
	v_lshl_add_u64 v[222:223], v[222:223], 0, s[8:9]
	v_lshl_add_u64 v[224:225], v[224:225], 0, s[8:9]
	s_waitcnt vmcnt(6)
	s_waitcnt lgkmcnt(0)
	s_setprio 1
	s_barrier
	v_mfma_f32_16x16x32_bf16 v[62:65], v[148:151], v[188:191], v[62:65]
	v_mfma_f32_16x16x32_bf16 v[58:61], v[156:159], v[188:191], v[58:61]
	v_mfma_f32_16x16x32_bf16 v[46:49], v[148:151], v[196:199], v[46:49]
	v_mfma_f32_16x16x32_bf16 v[42:45], v[156:159], v[196:199], v[42:45]
	v_mfma_f32_16x16x32_bf16 v[30:33], v[148:151], v[204:207], v[30:33]
	v_mfma_f32_16x16x32_bf16 v[26:29], v[156:159], v[204:207], v[26:29]
	v_mfma_f32_16x16x32_bf16 v[14:17], v[148:151], v[212:215], v[14:17]
	v_mfma_f32_16x16x32_bf16 v[10:13], v[156:159], v[212:215], v[10:13]
	v_mfma_f32_16x16x32_bf16 v[62:65], v[152:155], v[192:195], v[62:65]
	v_mfma_f32_16x16x32_bf16 v[58:61], v[168:171], v[192:195], v[58:61]
	v_mfma_f32_16x16x32_bf16 v[46:49], v[152:155], v[200:203], v[46:49]
	v_mfma_f32_16x16x32_bf16 v[42:45], v[168:171], v[200:203], v[42:45]
	v_mfma_f32_16x16x32_bf16 v[30:33], v[152:155], v[208:211], v[30:33]
	v_mfma_f32_16x16x32_bf16 v[26:29], v[168:171], v[208:211], v[26:29]
	v_mfma_f32_16x16x32_bf16 v[14:17], v[152:155], v[216:219], v[14:17]
	v_mfma_f32_16x16x32_bf16 v[10:13], v[168:171], v[216:219], v[10:13]
	v_mfma_f32_16x16x32_bf16 v[54:57], v[172:175], v[188:191], v[54:57]
	v_mfma_f32_16x16x32_bf16 v[50:53], v[180:183], v[188:191], v[50:53]
	v_mfma_f32_16x16x32_bf16 v[38:41], v[172:175], v[196:199], v[38:41]
	v_mfma_f32_16x16x32_bf16 v[34:37], v[180:183], v[196:199], v[34:37]
	v_mfma_f32_16x16x32_bf16 v[22:25], v[172:175], v[204:207], v[22:25]
	v_mfma_f32_16x16x32_bf16 v[18:21], v[180:183], v[204:207], v[18:21]
	v_mfma_f32_16x16x32_bf16 v[6:9], v[172:175], v[212:215], v[6:9]
	v_mfma_f32_16x16x32_bf16 v[2:5], v[180:183], v[212:215], v[2:5]
	v_mfma_f32_16x16x32_bf16 v[54:57], v[176:179], v[192:195], v[54:57]
	v_mfma_f32_16x16x32_bf16 v[50:53], v[184:187], v[192:195], v[50:53]
	v_mfma_f32_16x16x32_bf16 v[38:41], v[176:179], v[200:203], v[38:41]
	v_mfma_f32_16x16x32_bf16 v[34:37], v[184:187], v[200:203], v[34:37]
	v_mfma_f32_16x16x32_bf16 v[22:25], v[176:179], v[208:211], v[22:25]
	v_mfma_f32_16x16x32_bf16 v[18:21], v[184:187], v[208:211], v[18:21]
	v_mfma_f32_16x16x32_bf16 v[6:9], v[176:179], v[216:219], v[6:9]
	v_mfma_f32_16x16x32_bf16 v[2:5], v[184:187], v[216:219], v[2:5]
	s_setprio 0
	s_barrier
	s_add_i32 s56, s56, 2
	s_mov_b32 s32, 1
	s_add_u32 s28, s28, 0x100
	s_addc_u32 s29, s29, 0
	s_add_u32 s54, s54, 0x100
	s_addc_u32 s55, s55, 0
	s_cmp_gt_u32 s56, 61
	s_cbranch_scc0 .LBB0_172
	s_and_b64 vcc, exec, s[10:11]
	s_cbranch_vccz .LBB0_175
	s_barrier

.LBB0_696:
	ds_read_b128 v[154:157], v150
	ds_read_b128 v[158:161], v150 offset:1024
	ds_read_b128 v[164:167], v150 offset:2048
	ds_read_b128 v[168:171], v150 offset:3072
	ds_read_b128 v[172:175], v151
	ds_read_b128 v[176:179], v151 offset:1024
	ds_read_b128 v[180:183], v151 offset:2048
	ds_read_b128 v[184:187], v151 offset:3072
	s_add_u32 s24, s22, 0xfff00080
	s_addc_u32 s25, s23, -1
	s_cmp_eq_u32 s47, 60
	s_cselect_b32 s27, s15, s25
	s_cselect_b32 s26, s43, s24
	s_cselect_b32 s25, s13, s46
	s_cselect_b32 s24, s44, s45
	s_add_i32 m0, s21, 0xc000
	ds_read_b128 v[188:191], v152
	ds_read_b128 v[192:195], v152 offset:1024
	ds_read_b128 v[196:199], v152 offset:2048
	ds_read_b128 v[200:203], v152 offset:3072
	ds_read_b128 v[204:207], v152 offset:4096
	ds_read_b128 v[208:211], v152 offset:5120
	ds_read_b128 v[212:215], v152 offset:6144
	ds_read_b128 v[216:219], v152 offset:7168
	s_cmp_lg_u32 s32, 0
	s_cbranch_scc0 .Lrebal_skip_696
	s_mov_b32 m0, s35
	s_nop 0
	global_load_lds_dwordx4 v[222:223], off
	s_mov_b32 m0, s36
	s_nop 0
	global_load_lds_dwordx4 v[224:225], off
.Lrebal_skip_696:
	s_add_i32 m0, s21, 0xc000
	s_nop 0
	global_load_lds_dwordx4 v138, s[22:23]
	s_add_i32 m0, s21, 0xe000
	s_nop 0
	global_load_lds_dwordx4 v140, s[22:23]
	s_waitcnt vmcnt(8)
	s_waitcnt lgkmcnt(0)
	s_setprio 1
	s_barrier
	v_mfma_f32_16x16x32_bf16 v[126:129], v[154:157], v[188:191], v[126:129]
	v_mfma_f32_16x16x32_bf16 v[122:125], v[164:167], v[188:191], v[122:125]
	v_mfma_f32_16x16x32_bf16 v[118:121], v[154:157], v[196:199], v[118:121]
	v_mfma_f32_16x16x32_bf16 v[110:113], v[164:167], v[196:199], v[110:113]
	v_mfma_f32_16x16x32_bf16 v[102:105], v[154:157], v[204:207], v[102:105]
	v_mfma_f32_16x16x32_bf16 v[94:97], v[164:167], v[204:207], v[94:97]
	v_mfma_f32_16x16x32_bf16 v[82:85], v[154:157], v[212:215], v[82:85]
	v_mfma_f32_16x16x32_bf16 v[74:77], v[164:167], v[212:215], v[74:77]
	v_mfma_f32_16x16x32_bf16 v[126:129], v[158:161], v[192:195], v[126:129]
	v_mfma_f32_16x16x32_bf16 v[122:125], v[168:171], v[192:195], v[122:125]
	v_mfma_f32_16x16x32_bf16 v[118:121], v[158:161], v[200:203], v[118:121]
	v_mfma_f32_16x16x32_bf16 v[110:113], v[168:171], v[200:203], v[110:113]
	v_mfma_f32_16x16x32_bf16 v[102:105], v[158:161], v[208:211], v[102:105]
	v_mfma_f32_16x16x32_bf16 v[94:97], v[168:171], v[208:211], v[94:97]
	v_mfma_f32_16x16x32_bf16 v[82:85], v[158:161], v[216:219], v[82:85]
	v_mfma_f32_16x16x32_bf16 v[74:77], v[168:171], v[216:219], v[74:77]
	v_mfma_f32_16x16x32_bf16 v[114:117], v[172:175], v[188:191], v[114:117]
	v_mfma_f32_16x16x32_bf16 v[106:109], v[180:183], v[188:191], v[106:109]
	v_mfma_f32_16x16x32_bf16 v[98:101], v[172:175], v[196:199], v[98:101]
	v_mfma_f32_16x16x32_bf16 v[90:93], v[180:183], v[196:199], v[90:93]
	v_mfma_f32_16x16x32_bf16 v[86:89], v[172:175], v[204:207], v[86:89]
	v_mfma_f32_16x16x32_bf16 v[78:81], v[180:183], v[204:207], v[78:81]
	v_mfma_f32_16x16x32_bf16 v[70:73], v[172:175], v[212:215], v[70:73]
	v_mfma_f32_16x16x32_bf16 v[66:69], v[180:183], v[212:215], v[66:69]
	v_mfma_f32_16x16x32_bf16 v[114:117], v[176:179], v[192:195], v[114:117]
	v_mfma_f32_16x16x32_bf16 v[106:109], v[184:187], v[192:195], v[106:109]
	v_mfma_f32_16x16x32_bf16 v[98:101], v[176:179], v[200:203], v[98:101]
	v_mfma_f32_16x16x32_bf16 v[90:93], v[184:187], v[200:203], v[90:93]
	v_mfma_f32_16x16x32_bf16 v[86:89], v[176:179], v[208:211], v[86:89]
	v_mfma_f32_16x16x32_bf16 v[78:81], v[184:187], v[208:211], v[78:81]
	v_mfma_f32_16x16x32_bf16 v[70:73], v[176:179], v[216:219], v[70:73]
	v_mfma_f32_16x16x32_bf16 v[66:69], v[184:187], v[216:219], v[66:69]
	s_setprio 0
	s_barrier
	s_add_i32 s48, s38, s29
	v_lshl_add_u64 v[146:147], s[24:25], 0, v[132:133]
	s_mov_b32 m0, s48
	ds_read_b128 v[188:191], v152 offset:16384
	ds_read_b128 v[192:195], v152 offset:17408
	ds_read_b128 v[196:199], v152 offset:18432
	ds_read_b128 v[200:203], v152 offset:19456
	ds_read_b128 v[204:207], v152 offset:20480
	ds_read_b128 v[208:211], v152 offset:21504
	ds_read_b128 v[212:215], v152 offset:22528
	ds_read_b128 v[216:219], v152 offset:23552
	global_load_lds_dwordx4 v132, s[24:25]
	s_add_i32 m0, s48, 0x2000
	s_add_u32 s48, s24, 0x100000
	v_lshl_add_u64 v[220:221], s[24:25], 0, v[136:137]
	s_addc_u32 s49, s25, 0
	s_add_i32 s50, s39, s29
	global_load_lds_dwordx4 v136, s[24:25]
	s_mov_b32 m0, s50
	v_lshl_add_u64 v[224:225], s[26:27], 0, v[134:135]
	global_load_lds_dwordx4 v132, s[48:49]
	s_add_i32 m0, s50, 0x2000
	s_nop 0
	global_load_lds_dwordx4 v136, s[48:49]
	v_lshl_add_u64 v[222:223], s[26:27], 0, v[130:131]
	s_waitcnt vmcnt(6)
	s_waitcnt lgkmcnt(0)
	s_setprio 1
	s_barrier
	v_mfma_f32_16x16x32_bf16 v[62:65], v[154:157], v[188:191], v[62:65]
	v_mfma_f32_16x16x32_bf16 v[58:61], v[164:167], v[188:191], v[58:61]
	v_mfma_f32_16x16x32_bf16 v[54:57], v[154:157], v[196:199], v[54:57]
	v_mfma_f32_16x16x32_bf16 v[46:49], v[164:167], v[196:199], v[46:49]
	v_mfma_f32_16x16x32_bf16 v[38:41], v[154:157], v[204:207], v[38:41]
	v_mfma_f32_16x16x32_bf16 v[30:33], v[164:167], v[204:207], v[30:33]
	v_mfma_f32_16x16x32_bf16 v[22:25], v[154:157], v[212:215], v[22:25]
	v_mfma_f32_16x16x32_bf16 v[14:17], v[164:167], v[212:215], v[14:17]
	v_mfma_f32_16x16x32_bf16 v[62:65], v[158:161], v[192:195], v[62:65]
	v_mfma_f32_16x16x32_bf16 v[58:61], v[168:171], v[192:195], v[58:61]
	v_mfma_f32_16x16x32_bf16 v[54:57], v[158:161], v[200:203], v[54:57]
	v_mfma_f32_16x16x32_bf16 v[46:49], v[168:171], v[200:203], v[46:49]
	v_mfma_f32_16x16x32_bf16 v[38:41], v[158:161], v[208:211], v[38:41]
	v_mfma_f32_16x16x32_bf16 v[30:33], v[168:171], v[208:211], v[30:33]
	v_mfma_f32_16x16x32_bf16 v[22:25], v[158:161], v[216:219], v[22:25]
	v_mfma_f32_16x16x32_bf16 v[14:17], v[168:171], v[216:219], v[14:17]
	v_mfma_f32_16x16x32_bf16 v[50:53], v[172:175], v[188:191], v[50:53]
	v_mfma_f32_16x16x32_bf16 v[42:45], v[180:183], v[188:191], v[42:45]
	v_mfma_f32_16x16x32_bf16 v[34:37], v[172:175], v[196:199], v[34:37]
	v_mfma_f32_16x16x32_bf16 v[26:29], v[180:183], v[196:199], v[26:29]
	v_mfma_f32_16x16x32_bf16 v[18:21], v[172:175], v[204:207], v[18:21]
	v_mfma_f32_16x16x32_bf16 v[10:13], v[180:183], v[204:207], v[10:13]
	v_mfma_f32_16x16x32_bf16 v[6:9], v[172:175], v[212:215], v[6:9]
	v_mfma_f32_16x16x32_bf16 v[2:5], v[180:183], v[212:215], v[2:5]
	v_mfma_f32_16x16x32_bf16 v[50:53], v[176:179], v[192:195], v[50:53]
	v_mfma_f32_16x16x32_bf16 v[42:45], v[184:187], v[192:195], v[42:45]
	v_mfma_f32_16x16x32_bf16 v[34:37], v[176:179], v[200:203], v[34:37]
	v_mfma_f32_16x16x32_bf16 v[26:29], v[184:187], v[200:203], v[26:29]
	v_mfma_f32_16x16x32_bf16 v[18:21], v[176:179], v[208:211], v[18:21]
	v_mfma_f32_16x16x32_bf16 v[10:13], v[184:187], v[208:211], v[10:13]
	v_mfma_f32_16x16x32_bf16 v[6:9], v[176:179], v[216:219], v[6:9]
	v_mfma_f32_16x16x32_bf16 v[2:5], v[184:187], v[216:219], v[2:5]
	s_setprio 0
	s_barrier
	s_add_i32 s48, 0, 0x18000
	v_add_u32_e32 v153, s48, v148
	s_add_i32 s49, 0, 0x1c000
	ds_read_b128 v[154:157], v153
	ds_read_b128 v[158:161], v153 offset:1024
	ds_read_b128 v[164:167], v153 offset:2048
	ds_read_b128 v[168:171], v153 offset:3072
	v_add_u32_e32 v153, s49, v148
	ds_read_b128 v[172:175], v153
	ds_read_b128 v[176:179], v153 offset:1024
	ds_read_b128 v[180:183], v153 offset:2048
	ds_read_b128 v[184:187], v153 offset:3072
	s_add_u32 s26, s26, 0x100000
	s_addc_u32 s27, s27, 0
	s_mov_b32 m0, s31
	ds_read_b128 v[188:191], v152 offset:32768
	ds_read_b128 v[192:195], v152 offset:33792
	ds_read_b128 v[196:199], v152 offset:34816
	ds_read_b128 v[200:203], v152 offset:35840
	ds_read_b128 v[204:207], v152 offset:36864
	ds_read_b128 v[208:211], v152 offset:37888
	ds_read_b128 v[212:215], v152 offset:38912
	ds_read_b128 v[216:219], v152 offset:39936
	s_mov_b32 m0, s21
	s_nop 0
	global_load_lds_dwordx4 v[222:223], off
	s_mov_b32 m0, s30
	s_nop 0
	global_load_lds_dwordx4 v[224:225], off
	s_mov_b32 m0, s31
	s_nop 0
	global_load_lds_dwordx4 v130, s[26:27]
	s_mov_b32 m0, s33
	s_nop 0
	global_load_lds_dwordx4 v134, s[26:27]
	s_waitcnt vmcnt(8)
	s_waitcnt lgkmcnt(0)
	s_setprio 1
	s_barrier
	v_mfma_f32_16x16x32_bf16 v[126:129], v[154:157], v[188:191], v[126:129]
	v_mfma_f32_16x16x32_bf16 v[122:125], v[164:167], v[188:191], v[122:125]
	v_mfma_f32_16x16x32_bf16 v[118:121], v[154:157], v[196:199], v[118:121]
	v_mfma_f32_16x16x32_bf16 v[110:113], v[164:167], v[196:199], v[110:113]
	v_mfma_f32_16x16x32_bf16 v[102:105], v[154:157], v[204:207], v[102:105]
	v_mfma_f32_16x16x32_bf16 v[94:97], v[164:167], v[204:207], v[94:97]
	v_mfma_f32_16x16x32_bf16 v[82:85], v[154:157], v[212:215], v[82:85]
	v_mfma_f32_16x16x32_bf16 v[74:77], v[164:167], v[212:215], v[74:77]
	v_mfma_f32_16x16x32_bf16 v[126:129], v[158:161], v[192:195], v[126:129]
	v_mfma_f32_16x16x32_bf16 v[122:125], v[168:171], v[192:195], v[122:125]
	v_mfma_f32_16x16x32_bf16 v[118:121], v[158:161], v[200:203], v[118:121]
	v_mfma_f32_16x16x32_bf16 v[110:113], v[168:171], v[200:203], v[110:113]
	v_mfma_f32_16x16x32_bf16 v[102:105], v[158:161], v[208:211], v[102:105]
	v_mfma_f32_16x16x32_bf16 v[94:97], v[168:171], v[208:211], v[94:97]
	v_mfma_f32_16x16x32_bf16 v[82:85], v[158:161], v[216:219], v[82:85]
	v_mfma_f32_16x16x32_bf16 v[74:77], v[168:171], v[216:219], v[74:77]
	v_mfma_f32_16x16x32_bf16 v[114:117], v[172:175], v[188:191], v[114:117]
	v_mfma_f32_16x16x32_bf16 v[106:109], v[180:183], v[188:191], v[106:109]
	v_mfma_f32_16x16x32_bf16 v[98:101], v[172:175], v[196:199], v[98:101]
	v_mfma_f32_16x16x32_bf16 v[90:93], v[180:183], v[196:199], v[90:93]
	v_mfma_f32_16x16x32_bf16 v[86:89], v[172:175], v[204:207], v[86:89]
	v_mfma_f32_16x16x32_bf16 v[78:81], v[180:183], v[204:207], v[78:81]
	v_mfma_f32_16x16x32_bf16 v[70:73], v[172:175], v[212:215], v[70:73]
	v_mfma_f32_16x16x32_bf16 v[66:69], v[180:183], v[212:215], v[66:69]
	v_mfma_f32_16x16x32_bf16 v[114:117], v[176:179], v[192:195], v[114:117]
	v_mfma_f32_16x16x32_bf16 v[106:109], v[184:187], v[192:195], v[106:109]
	v_mfma_f32_16x16x32_bf16 v[98:101], v[176:179], v[200:203], v[98:101]
	v_mfma_f32_16x16x32_bf16 v[90:93], v[184:187], v[200:203], v[90:93]
	v_mfma_f32_16x16x32_bf16 v[86:89], v[176:179], v[208:211], v[86:89]
	v_mfma_f32_16x16x32_bf16 v[78:81], v[184:187], v[208:211], v[78:81]
	v_mfma_f32_16x16x32_bf16 v[70:73], v[176:179], v[216:219], v[70:73]
	v_mfma_f32_16x16x32_bf16 v[66:69], v[184:187], v[216:219], v[66:69]
	s_setprio 0
	s_barrier
	s_add_i32 s26, s48, s29
	v_lshl_add_u64 v[146:147], v[146:147], 0, s[6:7]
	s_mov_b32 m0, s26
	ds_read_b128 v[188:191], v152 offset:49152
	ds_read_b128 v[192:195], v152 offset:50176
	ds_read_b128 v[196:199], v152 offset:51200
	ds_read_b128 v[200:203], v152 offset:52224
	ds_read_b128 v[204:207], v152 offset:53248
	ds_read_b128 v[208:211], v152 offset:54272
	ds_read_b128 v[212:215], v152 offset:55296
	ds_read_b128 v[216:219], v152 offset:56320
	global_load_lds_dwordx4 v[146:147], off
	s_add_i32 m0, s26, 0x2000
	s_add_u32 s24, s24, 0x100080
	v_lshl_add_u64 v[146:147], v[220:221], 0, s[6:7]
	s_addc_u32 s25, s25, 0
	s_add_i32 s26, s49, s29
	global_load_lds_dwordx4 v[146:147], off
	s_mov_b32 m0, s26
	s_nop 0
	global_load_lds_dwordx4 v132, s[24:25]
	s_add_i32 m0, s26, 0x2000
	s_nop 0
	global_load_lds_dwordx4 v136, s[24:25]
	v_lshl_add_u64 v[222:223], v[222:223], 0, s[6:7]
	v_lshl_add_u64 v[224:225], v[224:225], 0, s[6:7]
	s_waitcnt vmcnt(6)
	s_waitcnt lgkmcnt(0)
	s_setprio 1
	s_barrier
	v_mfma_f32_16x16x32_bf16 v[62:65], v[154:157], v[188:191], v[62:65]
	v_mfma_f32_16x16x32_bf16 v[58:61], v[164:167], v[188:191], v[58:61]
	v_mfma_f32_16x16x32_bf16 v[54:57], v[154:157], v[196:199], v[54:57]
	v_mfma_f32_16x16x32_bf16 v[46:49], v[164:167], v[196:199], v[46:49]
	v_mfma_f32_16x16x32_bf16 v[38:41], v[154:157], v[204:207], v[38:41]
	v_mfma_f32_16x16x32_bf16 v[30:33], v[164:167], v[204:207], v[30:33]
	v_mfma_f32_16x16x32_bf16 v[22:25], v[154:157], v[212:215], v[22:25]
	v_mfma_f32_16x16x32_bf16 v[14:17], v[164:167], v[212:215], v[14:17]
	v_mfma_f32_16x16x32_bf16 v[62:65], v[158:161], v[192:195], v[62:65]
	v_mfma_f32_16x16x32_bf16 v[58:61], v[168:171], v[192:195], v[58:61]
	v_mfma_f32_16x16x32_bf16 v[54:57], v[158:161], v[200:203], v[54:57]
	v_mfma_f32_16x16x32_bf16 v[46:49], v[168:171], v[200:203], v[46:49]
	v_mfma_f32_16x16x32_bf16 v[38:41], v[158:161], v[208:211], v[38:41]
	v_mfma_f32_16x16x32_bf16 v[30:33], v[168:171], v[208:211], v[30:33]
	v_mfma_f32_16x16x32_bf16 v[22:25], v[158:161], v[216:219], v[22:25]
	v_mfma_f32_16x16x32_bf16 v[14:17], v[168:171], v[216:219], v[14:17]
	v_mfma_f32_16x16x32_bf16 v[50:53], v[172:175], v[188:191], v[50:53]
	v_mfma_f32_16x16x32_bf16 v[42:45], v[180:183], v[188:191], v[42:45]
	v_mfma_f32_16x16x32_bf16 v[34:37], v[172:175], v[196:199], v[34:37]
	v_mfma_f32_16x16x32_bf16 v[26:29], v[180:183], v[196:199], v[26:29]
	v_mfma_f32_16x16x32_bf16 v[18:21], v[172:175], v[204:207], v[18:21]
	v_mfma_f32_16x16x32_bf16 v[10:13], v[180:183], v[204:207], v[10:13]
	v_mfma_f32_16x16x32_bf16 v[6:9], v[172:175], v[212:215], v[6:9]
	v_mfma_f32_16x16x32_bf16 v[2:5], v[180:183], v[212:215], v[2:5]
	v_mfma_f32_16x16x32_bf16 v[50:53], v[176:179], v[192:195], v[50:53]
	v_mfma_f32_16x16x32_bf16 v[42:45], v[184:187], v[192:195], v[42:45]
	v_mfma_f32_16x16x32_bf16 v[34:37], v[176:179], v[200:203], v[34:37]
	v_mfma_f32_16x16x32_bf16 v[26:29], v[184:187], v[200:203], v[26:29]
	v_mfma_f32_16x16x32_bf16 v[18:21], v[176:179], v[208:211], v[18:21]
	v_mfma_f32_16x16x32_bf16 v[10:13], v[184:187], v[208:211], v[10:13]
	v_mfma_f32_16x16x32_bf16 v[6:9], v[176:179], v[216:219], v[6:9]
	v_mfma_f32_16x16x32_bf16 v[2:5], v[184:187], v[216:219], v[2:5]
	s_setprio 0
	s_barrier
	s_add_i32 s47, s47, 2
	s_mov_b32 s32, 1
	s_add_u32 s22, s22, 0x100
	s_addc_u32 s23, s23, 0
	s_add_u32 s45, s45, 0x100
	s_addc_u32 s46, s46, 0
	s_cmp_gt_u32 s47, 61
	s_cbranch_scc0 .LBB0_696
	s_and_b64 vcc, exec, s[8:9]
	s_cbranch_vccz .LBB0_699
	s_barrier

.LBB0_820:
	ds_read_b128 v[146:149], v154
	ds_read_b128 v[158:161], v154 offset:1024
	ds_read_b128 v[164:167], v154 offset:2048
	ds_read_b128 v[168:171], v154 offset:3072
	ds_read_b128 v[172:175], v155
	ds_read_b128 v[176:179], v155 offset:1024
	ds_read_b128 v[180:183], v155 offset:2048
	ds_read_b128 v[184:187], v155 offset:3072
	s_add_u32 s26, s24, 0xfff00080
	s_addc_u32 s27, s25, -1
	s_cmp_eq_u32 s47, 60
	s_cselect_b32 s29, s7, s27
	s_cselect_b32 s28, s17, s26
	s_cselect_b32 s27, s15, s46
	s_cselect_b32 s26, s44, s45
	s_add_i32 m0, s23, 0xc000
	ds_read_b128 v[188:191], v156
	ds_read_b128 v[192:195], v156 offset:1024
	ds_read_b128 v[196:199], v156 offset:2048
	ds_read_b128 v[200:203], v156 offset:3072
	ds_read_b128 v[204:207], v156 offset:4096
	ds_read_b128 v[208:211], v156 offset:5120
	ds_read_b128 v[212:215], v156 offset:6144
	ds_read_b128 v[216:219], v156 offset:7168
	s_cmp_lg_u32 s32, 0
	s_cbranch_scc0 .Lrebal_skip_820
	s_mov_b32 m0, s36
	s_nop 0
	global_load_lds_dwordx4 v[224:225], off
	s_mov_b32 m0, s37
	s_nop 0
	global_load_lds_dwordx4 v[226:227], off
.Lrebal_skip_820:
	s_add_i32 m0, s23, 0xc000
	s_nop 0
	global_load_lds_dwordx4 v138, s[24:25]
	s_add_i32 m0, s23, 0xe000
	s_nop 0
	global_load_lds_dwordx4 v140, s[24:25]
	s_waitcnt vmcnt(8)
	s_waitcnt lgkmcnt(0)
	s_setprio 1
	s_barrier
	v_mfma_f32_16x16x32_bf16 v[126:129], v[146:149], v[188:191], v[126:129]
	v_mfma_f32_16x16x32_bf16 v[122:125], v[164:167], v[188:191], v[122:125]
	v_mfma_f32_16x16x32_bf16 v[110:113], v[146:149], v[196:199], v[110:113]
	v_mfma_f32_16x16x32_bf16 v[106:109], v[164:167], v[196:199], v[106:109]
	v_mfma_f32_16x16x32_bf16 v[94:97], v[146:149], v[204:207], v[94:97]
	v_mfma_f32_16x16x32_bf16 v[90:93], v[164:167], v[204:207], v[90:93]
	v_mfma_f32_16x16x32_bf16 v[78:81], v[146:149], v[212:215], v[78:81]
	v_mfma_f32_16x16x32_bf16 v[74:77], v[164:167], v[212:215], v[74:77]
	v_mfma_f32_16x16x32_bf16 v[126:129], v[158:161], v[192:195], v[126:129]
	v_mfma_f32_16x16x32_bf16 v[122:125], v[168:171], v[192:195], v[122:125]
	v_mfma_f32_16x16x32_bf16 v[110:113], v[158:161], v[200:203], v[110:113]
	v_mfma_f32_16x16x32_bf16 v[106:109], v[168:171], v[200:203], v[106:109]
	v_mfma_f32_16x16x32_bf16 v[94:97], v[158:161], v[208:211], v[94:97]
	v_mfma_f32_16x16x32_bf16 v[90:93], v[168:171], v[208:211], v[90:93]
	v_mfma_f32_16x16x32_bf16 v[78:81], v[158:161], v[216:219], v[78:81]
	v_mfma_f32_16x16x32_bf16 v[74:77], v[168:171], v[216:219], v[74:77]
	v_mfma_f32_16x16x32_bf16 v[118:121], v[172:175], v[188:191], v[118:121]
	v_mfma_f32_16x16x32_bf16 v[114:117], v[180:183], v[188:191], v[114:117]
	v_mfma_f32_16x16x32_bf16 v[102:105], v[172:175], v[196:199], v[102:105]
	v_mfma_f32_16x16x32_bf16 v[98:101], v[180:183], v[196:199], v[98:101]
	v_mfma_f32_16x16x32_bf16 v[86:89], v[172:175], v[204:207], v[86:89]
	v_mfma_f32_16x16x32_bf16 v[82:85], v[180:183], v[204:207], v[82:85]
	v_mfma_f32_16x16x32_bf16 v[70:73], v[172:175], v[212:215], v[70:73]
	v_mfma_f32_16x16x32_bf16 v[66:69], v[180:183], v[212:215], v[66:69]
	v_mfma_f32_16x16x32_bf16 v[118:121], v[176:179], v[192:195], v[118:121]
	v_mfma_f32_16x16x32_bf16 v[114:117], v[184:187], v[192:195], v[114:117]
	v_mfma_f32_16x16x32_bf16 v[102:105], v[176:179], v[200:203], v[102:105]
	v_mfma_f32_16x16x32_bf16 v[98:101], v[184:187], v[200:203], v[98:101]
	v_mfma_f32_16x16x32_bf16 v[86:89], v[176:179], v[208:211], v[86:89]
	v_mfma_f32_16x16x32_bf16 v[82:85], v[184:187], v[208:211], v[82:85]
	v_mfma_f32_16x16x32_bf16 v[70:73], v[176:179], v[216:219], v[70:73]
	v_mfma_f32_16x16x32_bf16 v[66:69], v[184:187], v[216:219], v[66:69]
	s_setprio 0
	s_barrier
	s_add_i32 s48, s41, s30
	v_lshl_add_u64 v[220:221], s[26:27], 0, v[132:133]
	s_mov_b32 m0, s48
	ds_read_b128 v[188:191], v156 offset:16384
	ds_read_b128 v[192:195], v156 offset:17408
	ds_read_b128 v[196:199], v156 offset:18432
	ds_read_b128 v[200:203], v156 offset:19456
	ds_read_b128 v[204:207], v156 offset:20480
	ds_read_b128 v[208:211], v156 offset:21504
	ds_read_b128 v[212:215], v156 offset:22528
	ds_read_b128 v[216:219], v156 offset:23552
	global_load_lds_dwordx4 v132, s[26:27]
	s_add_i32 m0, s48, 0x2000
	s_add_u32 s48, s26, 0x100000
	v_lshl_add_u64 v[222:223], s[26:27], 0, v[136:137]
	s_addc_u32 s49, s27, 0
	s_add_i32 s50, s42, s30
	global_load_lds_dwordx4 v136, s[26:27]
	s_mov_b32 m0, s50
	v_lshl_add_u64 v[226:227], s[28:29], 0, v[134:135]
	global_load_lds_dwordx4 v132, s[48:49]
	s_add_i32 m0, s50, 0x2000
	s_nop 0
	global_load_lds_dwordx4 v136, s[48:49]
	v_lshl_add_u64 v[224:225], s[28:29], 0, v[130:131]
	s_waitcnt vmcnt(6)
	s_waitcnt lgkmcnt(0)
	s_setprio 1
	s_barrier
	v_mfma_f32_16x16x32_bf16 v[62:65], v[146:149], v[188:191], v[62:65]
	v_mfma_f32_16x16x32_bf16 v[58:61], v[164:167], v[188:191], v[58:61]
	v_mfma_f32_16x16x32_bf16 v[46:49], v[146:149], v[196:199], v[46:49]
	v_mfma_f32_16x16x32_bf16 v[42:45], v[164:167], v[196:199], v[42:45]
	v_mfma_f32_16x16x32_bf16 v[30:33], v[146:149], v[204:207], v[30:33]
	v_mfma_f32_16x16x32_bf16 v[26:29], v[164:167], v[204:207], v[26:29]
	v_mfma_f32_16x16x32_bf16 v[14:17], v[146:149], v[212:215], v[14:17]
	v_mfma_f32_16x16x32_bf16 v[10:13], v[164:167], v[212:215], v[10:13]
	v_mfma_f32_16x16x32_bf16 v[62:65], v[158:161], v[192:195], v[62:65]
	v_mfma_f32_16x16x32_bf16 v[58:61], v[168:171], v[192:195], v[58:61]
	v_mfma_f32_16x16x32_bf16 v[46:49], v[158:161], v[200:203], v[46:49]
	v_mfma_f32_16x16x32_bf16 v[42:45], v[168:171], v[200:203], v[42:45]
	v_mfma_f32_16x16x32_bf16 v[30:33], v[158:161], v[208:211], v[30:33]
	v_mfma_f32_16x16x32_bf16 v[26:29], v[168:171], v[208:211], v[26:29]
	v_mfma_f32_16x16x32_bf16 v[14:17], v[158:161], v[216:219], v[14:17]
	v_mfma_f32_16x16x32_bf16 v[10:13], v[168:171], v[216:219], v[10:13]
	v_mfma_f32_16x16x32_bf16 v[54:57], v[172:175], v[188:191], v[54:57]
	v_mfma_f32_16x16x32_bf16 v[50:53], v[180:183], v[188:191], v[50:53]
	v_mfma_f32_16x16x32_bf16 v[38:41], v[172:175], v[196:199], v[38:41]
	v_mfma_f32_16x16x32_bf16 v[34:37], v[180:183], v[196:199], v[34:37]
	v_mfma_f32_16x16x32_bf16 v[22:25], v[172:175], v[204:207], v[22:25]
	v_mfma_f32_16x16x32_bf16 v[18:21], v[180:183], v[204:207], v[18:21]
	v_mfma_f32_16x16x32_bf16 v[6:9], v[172:175], v[212:215], v[6:9]
	v_mfma_f32_16x16x32_bf16 v[2:5], v[180:183], v[212:215], v[2:5]
	v_mfma_f32_16x16x32_bf16 v[54:57], v[176:179], v[192:195], v[54:57]
	v_mfma_f32_16x16x32_bf16 v[50:53], v[184:187], v[192:195], v[50:53]
	v_mfma_f32_16x16x32_bf16 v[38:41], v[176:179], v[200:203], v[38:41]
	v_mfma_f32_16x16x32_bf16 v[34:37], v[184:187], v[200:203], v[34:37]
	v_mfma_f32_16x16x32_bf16 v[22:25], v[176:179], v[208:211], v[22:25]
	v_mfma_f32_16x16x32_bf16 v[18:21], v[184:187], v[208:211], v[18:21]
	v_mfma_f32_16x16x32_bf16 v[6:9], v[176:179], v[216:219], v[6:9]
	v_mfma_f32_16x16x32_bf16 v[2:5], v[184:187], v[216:219], v[2:5]
	s_setprio 0
	s_barrier
	s_add_i32 s48, 0, 0x18000
	v_add_u32_e32 v150, s48, v151
	s_add_i32 s49, 0, 0x1c000
	ds_read_b128 v[146:149], v150
	ds_read_b128 v[158:161], v150 offset:1024
	ds_read_b128 v[164:167], v150 offset:2048
	ds_read_b128 v[168:171], v150 offset:3072
	v_add_u32_e32 v150, s49, v151
	ds_read_b128 v[172:175], v150
	ds_read_b128 v[176:179], v150 offset:1024
	ds_read_b128 v[180:183], v150 offset:2048
	ds_read_b128 v[184:187], v150 offset:3072
	s_add_u32 s28, s28, 0x100000
	s_addc_u32 s29, s29, 0
	s_mov_b32 m0, s33
	ds_read_b128 v[188:191], v156 offset:32768
	ds_read_b128 v[192:195], v156 offset:33792
	ds_read_b128 v[196:199], v156 offset:34816
	ds_read_b128 v[200:203], v156 offset:35840
	ds_read_b128 v[204:207], v156 offset:36864
	ds_read_b128 v[208:211], v156 offset:37888
	ds_read_b128 v[212:215], v156 offset:38912
	ds_read_b128 v[216:219], v156 offset:39936
	s_mov_b32 m0, s23
	s_nop 0
	global_load_lds_dwordx4 v[224:225], off
	s_mov_b32 m0, s31
	s_nop 0
	global_load_lds_dwordx4 v[226:227], off
	s_mov_b32 m0, s33
	s_nop 0
	global_load_lds_dwordx4 v130, s[28:29]
	s_mov_b32 m0, s34
	s_nop 0
	global_load_lds_dwordx4 v134, s[28:29]
	s_waitcnt vmcnt(8)
	s_waitcnt lgkmcnt(0)
	s_setprio 1
	s_barrier
	v_mfma_f32_16x16x32_bf16 v[126:129], v[146:149], v[188:191], v[126:129]
	v_mfma_f32_16x16x32_bf16 v[122:125], v[164:167], v[188:191], v[122:125]
	v_mfma_f32_16x16x32_bf16 v[110:113], v[146:149], v[196:199], v[110:113]
	v_mfma_f32_16x16x32_bf16 v[106:109], v[164:167], v[196:199], v[106:109]
	v_mfma_f32_16x16x32_bf16 v[94:97], v[146:149], v[204:207], v[94:97]
	v_mfma_f32_16x16x32_bf16 v[90:93], v[164:167], v[204:207], v[90:93]
	v_mfma_f32_16x16x32_bf16 v[78:81], v[146:149], v[212:215], v[78:81]
	v_mfma_f32_16x16x32_bf16 v[74:77], v[164:167], v[212:215], v[74:77]
	v_mfma_f32_16x16x32_bf16 v[126:129], v[158:161], v[192:195], v[126:129]
	v_mfma_f32_16x16x32_bf16 v[122:125], v[168:171], v[192:195], v[122:125]
	v_mfma_f32_16x16x32_bf16 v[110:113], v[158:161], v[200:203], v[110:113]
	v_mfma_f32_16x16x32_bf16 v[106:109], v[168:171], v[200:203], v[106:109]
	v_mfma_f32_16x16x32_bf16 v[94:97], v[158:161], v[208:211], v[94:97]
	v_mfma_f32_16x16x32_bf16 v[90:93], v[168:171], v[208:211], v[90:93]
	v_mfma_f32_16x16x32_bf16 v[78:81], v[158:161], v[216:219], v[78:81]
	v_mfma_f32_16x16x32_bf16 v[74:77], v[168:171], v[216:219], v[74:77]
	v_mfma_f32_16x16x32_bf16 v[118:121], v[172:175], v[188:191], v[118:121]
	v_mfma_f32_16x16x32_bf16 v[114:117], v[180:183], v[188:191], v[114:117]
	v_mfma_f32_16x16x32_bf16 v[102:105], v[172:175], v[196:199], v[102:105]
	v_mfma_f32_16x16x32_bf16 v[98:101], v[180:183], v[196:199], v[98:101]
	v_mfma_f32_16x16x32_bf16 v[86:89], v[172:175], v[204:207], v[86:89]
	v_mfma_f32_16x16x32_bf16 v[82:85], v[180:183], v[204:207], v[82:85]
	v_mfma_f32_16x16x32_bf16 v[70:73], v[172:175], v[212:215], v[70:73]
	v_mfma_f32_16x16x32_bf16 v[66:69], v[180:183], v[212:215], v[66:69]
	v_mfma_f32_16x16x32_bf16 v[118:121], v[176:179], v[192:195], v[118:121]
	v_mfma_f32_16x16x32_bf16 v[114:117], v[184:187], v[192:195], v[114:117]
	v_mfma_f32_16x16x32_bf16 v[102:105], v[176:179], v[200:203], v[102:105]
	v_mfma_f32_16x16x32_bf16 v[98:101], v[184:187], v[200:203], v[98:101]
	v_mfma_f32_16x16x32_bf16 v[86:89], v[176:179], v[208:211], v[86:89]
	v_mfma_f32_16x16x32_bf16 v[82:85], v[184:187], v[208:211], v[82:85]
	v_mfma_f32_16x16x32_bf16 v[70:73], v[176:179], v[216:219], v[70:73]
	v_mfma_f32_16x16x32_bf16 v[66:69], v[184:187], v[216:219], v[66:69]
	s_setprio 0
	s_barrier
	s_add_i32 s28, s48, s30
	v_lshl_add_u64 v[220:221], v[220:221], 0, s[8:9]
	s_mov_b32 m0, s28
	ds_read_b128 v[188:191], v156 offset:49152
	ds_read_b128 v[192:195], v156 offset:50176
	ds_read_b128 v[196:199], v156 offset:51200
	ds_read_b128 v[200:203], v156 offset:52224
	ds_read_b128 v[204:207], v156 offset:53248
	ds_read_b128 v[208:211], v156 offset:54272
	ds_read_b128 v[212:215], v156 offset:55296
	ds_read_b128 v[216:219], v156 offset:56320
	global_load_lds_dwordx4 v[220:221], off
	s_add_i32 m0, s28, 0x2000
	s_add_u32 s26, s26, 0x100080
	v_lshl_add_u64 v[220:221], v[222:223], 0, s[8:9]
	s_addc_u32 s27, s27, 0
	s_add_i32 s28, s49, s30
	global_load_lds_dwordx4 v[220:221], off
	s_mov_b32 m0, s28
	s_nop 0
	global_load_lds_dwordx4 v132, s[26:27]
	s_add_i32 m0, s28, 0x2000
	s_nop 0
	global_load_lds_dwordx4 v136, s[26:27]
	v_lshl_add_u64 v[224:225], v[224:225], 0, s[8:9]
	v_lshl_add_u64 v[226:227], v[226:227], 0, s[8:9]
	s_waitcnt vmcnt(6)
	s_waitcnt lgkmcnt(0)
	s_setprio 1
	s_barrier
	v_mfma_f32_16x16x32_bf16 v[62:65], v[146:149], v[188:191], v[62:65]
	v_mfma_f32_16x16x32_bf16 v[58:61], v[164:167], v[188:191], v[58:61]
	v_mfma_f32_16x16x32_bf16 v[46:49], v[146:149], v[196:199], v[46:49]
	v_mfma_f32_16x16x32_bf16 v[42:45], v[164:167], v[196:199], v[42:45]
	v_mfma_f32_16x16x32_bf16 v[30:33], v[146:149], v[204:207], v[30:33]
	v_mfma_f32_16x16x32_bf16 v[26:29], v[164:167], v[204:207], v[26:29]
	v_mfma_f32_16x16x32_bf16 v[14:17], v[146:149], v[212:215], v[14:17]
	v_mfma_f32_16x16x32_bf16 v[10:13], v[164:167], v[212:215], v[10:13]
	v_mfma_f32_16x16x32_bf16 v[62:65], v[158:161], v[192:195], v[62:65]
	v_mfma_f32_16x16x32_bf16 v[58:61], v[168:171], v[192:195], v[58:61]
	v_mfma_f32_16x16x32_bf16 v[46:49], v[158:161], v[200:203], v[46:49]
	v_mfma_f32_16x16x32_bf16 v[42:45], v[168:171], v[200:203], v[42:45]
	v_mfma_f32_16x16x32_bf16 v[30:33], v[158:161], v[208:211], v[30:33]
	v_mfma_f32_16x16x32_bf16 v[26:29], v[168:171], v[208:211], v[26:29]
	v_mfma_f32_16x16x32_bf16 v[14:17], v[158:161], v[216:219], v[14:17]
	v_mfma_f32_16x16x32_bf16 v[10:13], v[168:171], v[216:219], v[10:13]
	v_mfma_f32_16x16x32_bf16 v[54:57], v[172:175], v[188:191], v[54:57]
	v_mfma_f32_16x16x32_bf16 v[50:53], v[180:183], v[188:191], v[50:53]
	v_mfma_f32_16x16x32_bf16 v[38:41], v[172:175], v[196:199], v[38:41]
	v_mfma_f32_16x16x32_bf16 v[34:37], v[180:183], v[196:199], v[34:37]
	v_mfma_f32_16x16x32_bf16 v[22:25], v[172:175], v[204:207], v[22:25]
	v_mfma_f32_16x16x32_bf16 v[18:21], v[180:183], v[204:207], v[18:21]
	v_mfma_f32_16x16x32_bf16 v[6:9], v[172:175], v[212:215], v[6:9]
	v_mfma_f32_16x16x32_bf16 v[2:5], v[180:183], v[212:215], v[2:5]
	v_mfma_f32_16x16x32_bf16 v[54:57], v[176:179], v[192:195], v[54:57]
	v_mfma_f32_16x16x32_bf16 v[50:53], v[184:187], v[192:195], v[50:53]
	v_mfma_f32_16x16x32_bf16 v[38:41], v[176:179], v[200:203], v[38:41]
	v_mfma_f32_16x16x32_bf16 v[34:37], v[184:187], v[200:203], v[34:37]
	v_mfma_f32_16x16x32_bf16 v[22:25], v[176:179], v[208:211], v[22:25]
	v_mfma_f32_16x16x32_bf16 v[18:21], v[184:187], v[208:211], v[18:21]
	v_mfma_f32_16x16x32_bf16 v[6:9], v[176:179], v[216:219], v[6:9]
	v_mfma_f32_16x16x32_bf16 v[2:5], v[184:187], v[216:219], v[2:5]
	s_setprio 0
	s_barrier
	s_add_i32 s47, s47, 2
	s_mov_b32 s32, 1
	s_add_u32 s24, s24, 0x100
	s_addc_u32 s25, s25, 0
	s_add_u32 s45, s45, 0x100
	s_addc_u32 s46, s46, 0
	s_cmp_gt_u32 s47, 61
	s_cbranch_scc0 .LBB0_820
	s_and_b64 vcc, exec, s[10:11]
	s_cbranch_vccz .LBB0_823
	s_barrier

.LBB0_978:
	ds_read_b128 v[154:157], v150
	ds_read_b128 v[158:161], v150 offset:1024
	ds_read_b128 v[164:167], v150 offset:2048
	ds_read_b128 v[168:171], v150 offset:3072
	ds_read_b128 v[172:175], v151
	ds_read_b128 v[176:179], v151 offset:1024
	ds_read_b128 v[180:183], v151 offset:2048
	ds_read_b128 v[184:187], v151 offset:3072
	s_add_u32 s22, s20, 0xffd50080
	s_addc_u32 s23, s21, -1
	s_cmpk_eq_i32 s49, 0xa8
	s_cselect_b32 s25, s1, s23
	s_cselect_b32 s24, s0, s22
	s_cselect_b32 s23, s19, s48
	s_cselect_b32 s22, s18, s47
	s_add_i32 m0, s28, 0xc000
	ds_read_b128 v[188:191], v152
	ds_read_b128 v[192:195], v152 offset:1024
	ds_read_b128 v[196:199], v152 offset:2048
	ds_read_b128 v[200:203], v152 offset:3072
	ds_read_b128 v[204:207], v152 offset:4096
	ds_read_b128 v[208:211], v152 offset:5120
	ds_read_b128 v[212:215], v152 offset:6144
	ds_read_b128 v[216:219], v152 offset:7168
	s_cmp_lg_u32 s32, 0
	s_cbranch_scc0 .Lrebal_skip_978
	s_mov_b32 m0, s34
	s_nop 0
	global_load_lds_dwordx4 v[222:223], off
	s_mov_b32 m0, s35
	s_nop 0
	global_load_lds_dwordx4 v[224:225], off
.Lrebal_skip_978:
	s_add_i32 m0, s28, 0xc000
	s_nop 0
	global_load_lds_dwordx4 v138, s[20:21]
	s_add_i32 m0, s28, 0xe000
	s_nop 0
	global_load_lds_dwordx4 v140, s[20:21]
	s_waitcnt vmcnt(8)
	s_waitcnt lgkmcnt(0)
	s_setprio 1
	s_barrier
	v_mfma_f32_16x16x32_bf16 v[126:129], v[154:157], v[188:191], v[126:129]
	v_mfma_f32_16x16x32_bf16 v[122:125], v[164:167], v[188:191], v[122:125]
	v_mfma_f32_16x16x32_bf16 v[118:121], v[154:157], v[196:199], v[118:121]
	v_mfma_f32_16x16x32_bf16 v[110:113], v[164:167], v[196:199], v[110:113]
	v_mfma_f32_16x16x32_bf16 v[102:105], v[154:157], v[204:207], v[102:105]
	v_mfma_f32_16x16x32_bf16 v[94:97], v[164:167], v[204:207], v[94:97]
	v_mfma_f32_16x16x32_bf16 v[82:85], v[154:157], v[212:215], v[82:85]
	v_mfma_f32_16x16x32_bf16 v[74:77], v[164:167], v[212:215], v[74:77]
	v_mfma_f32_16x16x32_bf16 v[126:129], v[158:161], v[192:195], v[126:129]
	v_mfma_f32_16x16x32_bf16 v[122:125], v[168:171], v[192:195], v[122:125]
	v_mfma_f32_16x16x32_bf16 v[118:121], v[158:161], v[200:203], v[118:121]
	v_mfma_f32_16x16x32_bf16 v[110:113], v[168:171], v[200:203], v[110:113]
	v_mfma_f32_16x16x32_bf16 v[102:105], v[158:161], v[208:211], v[102:105]
	v_mfma_f32_16x16x32_bf16 v[94:97], v[168:171], v[208:211], v[94:97]
	v_mfma_f32_16x16x32_bf16 v[82:85], v[158:161], v[216:219], v[82:85]
	v_mfma_f32_16x16x32_bf16 v[74:77], v[168:171], v[216:219], v[74:77]
	v_mfma_f32_16x16x32_bf16 v[114:117], v[172:175], v[188:191], v[114:117]
	v_mfma_f32_16x16x32_bf16 v[106:109], v[180:183], v[188:191], v[106:109]
	v_mfma_f32_16x16x32_bf16 v[98:101], v[172:175], v[196:199], v[98:101]
	v_mfma_f32_16x16x32_bf16 v[90:93], v[180:183], v[196:199], v[90:93]
	v_mfma_f32_16x16x32_bf16 v[86:89], v[172:175], v[204:207], v[86:89]
	v_mfma_f32_16x16x32_bf16 v[78:81], v[180:183], v[204:207], v[78:81]
	v_mfma_f32_16x16x32_bf16 v[70:73], v[172:175], v[212:215], v[70:73]
	v_mfma_f32_16x16x32_bf16 v[66:69], v[180:183], v[212:215], v[66:69]
	v_mfma_f32_16x16x32_bf16 v[114:117], v[176:179], v[192:195], v[114:117]
	v_mfma_f32_16x16x32_bf16 v[106:109], v[184:187], v[192:195], v[106:109]
	v_mfma_f32_16x16x32_bf16 v[98:101], v[176:179], v[200:203], v[98:101]
	v_mfma_f32_16x16x32_bf16 v[90:93], v[184:187], v[200:203], v[90:93]
	v_mfma_f32_16x16x32_bf16 v[86:89], v[176:179], v[208:211], v[86:89]
	v_mfma_f32_16x16x32_bf16 v[78:81], v[184:187], v[208:211], v[78:81]
	v_mfma_f32_16x16x32_bf16 v[70:73], v[176:179], v[216:219], v[70:73]
	v_mfma_f32_16x16x32_bf16 v[66:69], v[184:187], v[216:219], v[66:69]
	s_setprio 0
	s_barrier
	s_add_i32 s50, s37, s27
	v_lshl_add_u64 v[146:147], s[22:23], 0, v[132:133]
	s_mov_b32 m0, s50
	ds_read_b128 v[188:191], v152 offset:16384
	ds_read_b128 v[192:195], v152 offset:17408
	ds_read_b128 v[196:199], v152 offset:18432
	ds_read_b128 v[200:203], v152 offset:19456
	ds_read_b128 v[204:207], v152 offset:20480
	ds_read_b128 v[208:211], v152 offset:21504
	ds_read_b128 v[212:215], v152 offset:22528
	ds_read_b128 v[216:219], v152 offset:23552
	global_load_lds_dwordx4 v132, s[22:23]
	s_add_i32 m0, s50, 0x2000
	s_add_u32 s50, s22, 0x2b0000
	v_lshl_add_u64 v[220:221], s[22:23], 0, v[136:137]
	s_addc_u32 s51, s23, 0
	s_add_i32 s52, s38, s27
	global_load_lds_dwordx4 v136, s[22:23]
	s_mov_b32 m0, s52
	v_lshl_add_u64 v[224:225], s[24:25], 0, v[134:135]
	global_load_lds_dwordx4 v132, s[50:51]
	s_add_i32 m0, s52, 0x2000
	s_nop 0
	global_load_lds_dwordx4 v136, s[50:51]
	v_lshl_add_u64 v[222:223], s[24:25], 0, v[130:131]
	s_waitcnt vmcnt(6)
	s_waitcnt lgkmcnt(0)
	s_setprio 1
	s_barrier
	v_mfma_f32_16x16x32_bf16 v[62:65], v[154:157], v[188:191], v[62:65]
	v_mfma_f32_16x16x32_bf16 v[58:61], v[164:167], v[188:191], v[58:61]
	v_mfma_f32_16x16x32_bf16 v[54:57], v[154:157], v[196:199], v[54:57]
	v_mfma_f32_16x16x32_bf16 v[46:49], v[164:167], v[196:199], v[46:49]
	v_mfma_f32_16x16x32_bf16 v[38:41], v[154:157], v[204:207], v[38:41]
	v_mfma_f32_16x16x32_bf16 v[30:33], v[164:167], v[204:207], v[30:33]
	v_mfma_f32_16x16x32_bf16 v[22:25], v[154:157], v[212:215], v[22:25]
	v_mfma_f32_16x16x32_bf16 v[14:17], v[164:167], v[212:215], v[14:17]
	v_mfma_f32_16x16x32_bf16 v[62:65], v[158:161], v[192:195], v[62:65]
	v_mfma_f32_16x16x32_bf16 v[58:61], v[168:171], v[192:195], v[58:61]
	v_mfma_f32_16x16x32_bf16 v[54:57], v[158:161], v[200:203], v[54:57]
	v_mfma_f32_16x16x32_bf16 v[46:49], v[168:171], v[200:203], v[46:49]
	v_mfma_f32_16x16x32_bf16 v[38:41], v[158:161], v[208:211], v[38:41]
	v_mfma_f32_16x16x32_bf16 v[30:33], v[168:171], v[208:211], v[30:33]
	v_mfma_f32_16x16x32_bf16 v[22:25], v[158:161], v[216:219], v[22:25]
	v_mfma_f32_16x16x32_bf16 v[14:17], v[168:171], v[216:219], v[14:17]
	v_mfma_f32_16x16x32_bf16 v[50:53], v[172:175], v[188:191], v[50:53]
	v_mfma_f32_16x16x32_bf16 v[42:45], v[180:183], v[188:191], v[42:45]
	v_mfma_f32_16x16x32_bf16 v[34:37], v[172:175], v[196:199], v[34:37]
	v_mfma_f32_16x16x32_bf16 v[26:29], v[180:183], v[196:199], v[26:29]
	v_mfma_f32_16x16x32_bf16 v[18:21], v[172:175], v[204:207], v[18:21]
	v_mfma_f32_16x16x32_bf16 v[10:13], v[180:183], v[204:207], v[10:13]
	v_mfma_f32_16x16x32_bf16 v[6:9], v[172:175], v[212:215], v[6:9]
	v_mfma_f32_16x16x32_bf16 v[2:5], v[180:183], v[212:215], v[2:5]
	v_mfma_f32_16x16x32_bf16 v[50:53], v[176:179], v[192:195], v[50:53]
	v_mfma_f32_16x16x32_bf16 v[42:45], v[184:187], v[192:195], v[42:45]
	v_mfma_f32_16x16x32_bf16 v[34:37], v[176:179], v[200:203], v[34:37]
	v_mfma_f32_16x16x32_bf16 v[26:29], v[184:187], v[200:203], v[26:29]
	v_mfma_f32_16x16x32_bf16 v[18:21], v[176:179], v[208:211], v[18:21]
	v_mfma_f32_16x16x32_bf16 v[10:13], v[184:187], v[208:211], v[10:13]
	v_mfma_f32_16x16x32_bf16 v[6:9], v[176:179], v[216:219], v[6:9]
	v_mfma_f32_16x16x32_bf16 v[2:5], v[184:187], v[216:219], v[2:5]
	s_setprio 0
	s_barrier
	s_add_i32 s50, 0, 0x18000
	v_add_u32_e32 v153, s50, v148
	s_add_i32 s51, 0, 0x1c000
	ds_read_b128 v[154:157], v153
	ds_read_b128 v[158:161], v153 offset:1024
	ds_read_b128 v[164:167], v153 offset:2048
	ds_read_b128 v[168:171], v153 offset:3072
	v_add_u32_e32 v153, s51, v148
	ds_read_b128 v[172:175], v153
	ds_read_b128 v[176:179], v153 offset:1024
	ds_read_b128 v[180:183], v153 offset:2048
	ds_read_b128 v[184:187], v153 offset:3072
	s_add_u32 s24, s24, 0x2b0000
	s_addc_u32 s25, s25, 0
	s_mov_b32 m0, s30
	ds_read_b128 v[188:191], v152 offset:32768
	ds_read_b128 v[192:195], v152 offset:33792
	ds_read_b128 v[196:199], v152 offset:34816
	ds_read_b128 v[200:203], v152 offset:35840
	ds_read_b128 v[204:207], v152 offset:36864
	ds_read_b128 v[208:211], v152 offset:37888
	ds_read_b128 v[212:215], v152 offset:38912
	ds_read_b128 v[216:219], v152 offset:39936
	s_mov_b32 m0, s28
	s_nop 0
	global_load_lds_dwordx4 v[222:223], off
	s_mov_b32 m0, s29
	s_nop 0
	global_load_lds_dwordx4 v[224:225], off
	s_mov_b32 m0, s30
	s_nop 0
	global_load_lds_dwordx4 v130, s[24:25]
	s_mov_b32 m0, s31
	s_nop 0
	global_load_lds_dwordx4 v134, s[24:25]
	s_waitcnt vmcnt(8)
	s_waitcnt lgkmcnt(0)
	s_setprio 1
	s_barrier
	v_mfma_f32_16x16x32_bf16 v[126:129], v[154:157], v[188:191], v[126:129]
	v_mfma_f32_16x16x32_bf16 v[122:125], v[164:167], v[188:191], v[122:125]
	v_mfma_f32_16x16x32_bf16 v[118:121], v[154:157], v[196:199], v[118:121]
	v_mfma_f32_16x16x32_bf16 v[110:113], v[164:167], v[196:199], v[110:113]
	v_mfma_f32_16x16x32_bf16 v[102:105], v[154:157], v[204:207], v[102:105]
	v_mfma_f32_16x16x32_bf16 v[94:97], v[164:167], v[204:207], v[94:97]
	v_mfma_f32_16x16x32_bf16 v[82:85], v[154:157], v[212:215], v[82:85]
	v_mfma_f32_16x16x32_bf16 v[74:77], v[164:167], v[212:215], v[74:77]
	v_mfma_f32_16x16x32_bf16 v[126:129], v[158:161], v[192:195], v[126:129]
	v_mfma_f32_16x16x32_bf16 v[122:125], v[168:171], v[192:195], v[122:125]
	v_mfma_f32_16x16x32_bf16 v[118:121], v[158:161], v[200:203], v[118:121]
	v_mfma_f32_16x16x32_bf16 v[110:113], v[168:171], v[200:203], v[110:113]
	v_mfma_f32_16x16x32_bf16 v[102:105], v[158:161], v[208:211], v[102:105]
	v_mfma_f32_16x16x32_bf16 v[94:97], v[168:171], v[208:211], v[94:97]
	v_mfma_f32_16x16x32_bf16 v[82:85], v[158:161], v[216:219], v[82:85]
	v_mfma_f32_16x16x32_bf16 v[74:77], v[168:171], v[216:219], v[74:77]
	v_mfma_f32_16x16x32_bf16 v[114:117], v[172:175], v[188:191], v[114:117]
	v_mfma_f32_16x16x32_bf16 v[106:109], v[180:183], v[188:191], v[106:109]
	v_mfma_f32_16x16x32_bf16 v[98:101], v[172:175], v[196:199], v[98:101]
	v_mfma_f32_16x16x32_bf16 v[90:93], v[180:183], v[196:199], v[90:93]
	v_mfma_f32_16x16x32_bf16 v[86:89], v[172:175], v[204:207], v[86:89]
	v_mfma_f32_16x16x32_bf16 v[78:81], v[180:183], v[204:207], v[78:81]
	v_mfma_f32_16x16x32_bf16 v[70:73], v[172:175], v[212:215], v[70:73]
	v_mfma_f32_16x16x32_bf16 v[66:69], v[180:183], v[212:215], v[66:69]
	v_mfma_f32_16x16x32_bf16 v[114:117], v[176:179], v[192:195], v[114:117]
	v_mfma_f32_16x16x32_bf16 v[106:109], v[184:187], v[192:195], v[106:109]
	v_mfma_f32_16x16x32_bf16 v[98:101], v[176:179], v[200:203], v[98:101]
	v_mfma_f32_16x16x32_bf16 v[90:93], v[184:187], v[200:203], v[90:93]
	v_mfma_f32_16x16x32_bf16 v[86:89], v[176:179], v[208:211], v[86:89]
	v_mfma_f32_16x16x32_bf16 v[78:81], v[184:187], v[208:211], v[78:81]
	v_mfma_f32_16x16x32_bf16 v[70:73], v[176:179], v[216:219], v[70:73]
	v_mfma_f32_16x16x32_bf16 v[66:69], v[184:187], v[216:219], v[66:69]
	s_setprio 0
	s_barrier
	s_add_i32 s24, s50, s27
	v_lshl_add_u64 v[146:147], v[146:147], 0, s[8:9]
	s_mov_b32 m0, s24
	ds_read_b128 v[188:191], v152 offset:49152
	ds_read_b128 v[192:195], v152 offset:50176
	ds_read_b128 v[196:199], v152 offset:51200
	ds_read_b128 v[200:203], v152 offset:52224
	ds_read_b128 v[204:207], v152 offset:53248
	ds_read_b128 v[208:211], v152 offset:54272
	ds_read_b128 v[212:215], v152 offset:55296
	ds_read_b128 v[216:219], v152 offset:56320
	global_load_lds_dwordx4 v[146:147], off
	s_add_i32 m0, s24, 0x2000
	s_add_u32 s22, s22, 0x2b0080
	v_lshl_add_u64 v[146:147], v[220:221], 0, s[8:9]
	s_addc_u32 s23, s23, 0
	s_add_i32 s24, s51, s27
	global_load_lds_dwordx4 v[146:147], off
	s_mov_b32 m0, s24
	s_nop 0
	global_load_lds_dwordx4 v132, s[22:23]
	s_add_i32 m0, s24, 0x2000
	s_nop 0
	global_load_lds_dwordx4 v136, s[22:23]
	v_lshl_add_u64 v[222:223], v[222:223], 0, s[8:9]
	v_lshl_add_u64 v[224:225], v[224:225], 0, s[8:9]
	s_waitcnt vmcnt(6)
	s_waitcnt lgkmcnt(0)
	s_setprio 1
	s_barrier
	v_mfma_f32_16x16x32_bf16 v[62:65], v[154:157], v[188:191], v[62:65]
	v_mfma_f32_16x16x32_bf16 v[58:61], v[164:167], v[188:191], v[58:61]
	v_mfma_f32_16x16x32_bf16 v[54:57], v[154:157], v[196:199], v[54:57]
	v_mfma_f32_16x16x32_bf16 v[46:49], v[164:167], v[196:199], v[46:49]
	v_mfma_f32_16x16x32_bf16 v[38:41], v[154:157], v[204:207], v[38:41]
	v_mfma_f32_16x16x32_bf16 v[30:33], v[164:167], v[204:207], v[30:33]
	v_mfma_f32_16x16x32_bf16 v[22:25], v[154:157], v[212:215], v[22:25]
	v_mfma_f32_16x16x32_bf16 v[14:17], v[164:167], v[212:215], v[14:17]
	v_mfma_f32_16x16x32_bf16 v[62:65], v[158:161], v[192:195], v[62:65]
	v_mfma_f32_16x16x32_bf16 v[58:61], v[168:171], v[192:195], v[58:61]
	v_mfma_f32_16x16x32_bf16 v[54:57], v[158:161], v[200:203], v[54:57]
	v_mfma_f32_16x16x32_bf16 v[46:49], v[168:171], v[200:203], v[46:49]
	v_mfma_f32_16x16x32_bf16 v[38:41], v[158:161], v[208:211], v[38:41]
	v_mfma_f32_16x16x32_bf16 v[30:33], v[168:171], v[208:211], v[30:33]
	v_mfma_f32_16x16x32_bf16 v[22:25], v[158:161], v[216:219], v[22:25]
	v_mfma_f32_16x16x32_bf16 v[14:17], v[168:171], v[216:219], v[14:17]
	v_mfma_f32_16x16x32_bf16 v[50:53], v[172:175], v[188:191], v[50:53]
	v_mfma_f32_16x16x32_bf16 v[42:45], v[180:183], v[188:191], v[42:45]
	v_mfma_f32_16x16x32_bf16 v[34:37], v[172:175], v[196:199], v[34:37]
	v_mfma_f32_16x16x32_bf16 v[26:29], v[180:183], v[196:199], v[26:29]
	v_mfma_f32_16x16x32_bf16 v[18:21], v[172:175], v[204:207], v[18:21]
	v_mfma_f32_16x16x32_bf16 v[10:13], v[180:183], v[204:207], v[10:13]
	v_mfma_f32_16x16x32_bf16 v[6:9], v[172:175], v[212:215], v[6:9]
	v_mfma_f32_16x16x32_bf16 v[2:5], v[180:183], v[212:215], v[2:5]
	v_mfma_f32_16x16x32_bf16 v[50:53], v[176:179], v[192:195], v[50:53]
	v_mfma_f32_16x16x32_bf16 v[42:45], v[184:187], v[192:195], v[42:45]
	v_mfma_f32_16x16x32_bf16 v[34:37], v[176:179], v[200:203], v[34:37]
	v_mfma_f32_16x16x32_bf16 v[26:29], v[184:187], v[200:203], v[26:29]
	v_mfma_f32_16x16x32_bf16 v[18:21], v[176:179], v[208:211], v[18:21]
	v_mfma_f32_16x16x32_bf16 v[10:13], v[184:187], v[208:211], v[10:13]
	v_mfma_f32_16x16x32_bf16 v[6:9], v[176:179], v[216:219], v[6:9]
	v_mfma_f32_16x16x32_bf16 v[2:5], v[184:187], v[216:219], v[2:5]
	s_setprio 0
	s_barrier
	s_add_i32 s49, s49, 2
	s_mov_b32 s32, 1
	s_add_u32 s20, s20, 0x100
	s_addc_u32 s21, s21, 0
	s_add_u32 s47, s47, 0x100
	s_addc_u32 s48, s48, 0
	s_cmpk_gt_u32 s49, 0xa9
	s_cbranch_scc0 .LBB0_978
	s_and_b64 vcc, exec, s[10:11]
	s_cbranch_vccz .LBB0_981
	s_barrier

.LBB0_1131:
	ds_read_b128 v[146:149], v156
	ds_read_b128 v[150:153], v156 offset:1024
	ds_read_b128 v[164:167], v156 offset:2048
	ds_read_b128 v[168:171], v156 offset:3072
	ds_read_b128 v[172:175], v157
	ds_read_b128 v[176:179], v157 offset:1024
	ds_read_b128 v[180:183], v157 offset:2048
	ds_read_b128 v[184:187], v157 offset:3072
	s_add_u32 s34, s30, 0xfff00080
	s_addc_u32 s35, s31, -1
	s_cmp_eq_u32 s53, 60
	s_cselect_b32 s37, s23, s35
	s_cselect_b32 s36, s49, s34
	s_cselect_b32 s35, s21, s52
	s_cselect_b32 s34, s50, s51
	s_add_i32 m0, s29, 0xc000
	ds_read_b128 v[188:191], v158
	ds_read_b128 v[192:195], v158 offset:1024
	ds_read_b128 v[196:199], v158 offset:2048
	ds_read_b128 v[200:203], v158 offset:3072
	ds_read_b128 v[204:207], v158 offset:4096
	ds_read_b128 v[208:211], v158 offset:5120
	ds_read_b128 v[212:215], v158 offset:6144
	ds_read_b128 v[216:219], v158 offset:7168
	s_cmp_lg_u32 s32, 0
	s_cbranch_scc0 .Lrebal_skip_1131
	s_mov_b32 m0, s43
	s_nop 0
	global_load_lds_dwordx4 v[222:223], off
	s_mov_b32 m0, s44
	s_nop 0
	global_load_lds_dwordx4 v[224:225], off
.Lrebal_skip_1131:
	s_add_i32 m0, s29, 0xc000
	s_nop 0
	global_load_lds_dwordx4 v138, s[30:31]
	s_add_i32 m0, s29, 0xe000
	s_nop 0
	global_load_lds_dwordx4 v140, s[30:31]
	s_waitcnt vmcnt(8)
	s_waitcnt lgkmcnt(0)
	s_setprio 1
	s_barrier
	v_mfma_f32_16x16x32_bf16 v[126:129], v[146:149], v[188:191], v[126:129]
	v_mfma_f32_16x16x32_bf16 v[122:125], v[164:167], v[188:191], v[122:125]
	v_mfma_f32_16x16x32_bf16 v[110:113], v[146:149], v[196:199], v[110:113]
	v_mfma_f32_16x16x32_bf16 v[106:109], v[164:167], v[196:199], v[106:109]
	v_mfma_f32_16x16x32_bf16 v[94:97], v[146:149], v[204:207], v[94:97]
	v_mfma_f32_16x16x32_bf16 v[90:93], v[164:167], v[204:207], v[90:93]
	v_mfma_f32_16x16x32_bf16 v[78:81], v[146:149], v[212:215], v[78:81]
	v_mfma_f32_16x16x32_bf16 v[74:77], v[164:167], v[212:215], v[74:77]
	v_mfma_f32_16x16x32_bf16 v[126:129], v[150:153], v[192:195], v[126:129]
	v_mfma_f32_16x16x32_bf16 v[122:125], v[168:171], v[192:195], v[122:125]
	v_mfma_f32_16x16x32_bf16 v[110:113], v[150:153], v[200:203], v[110:113]
	v_mfma_f32_16x16x32_bf16 v[106:109], v[168:171], v[200:203], v[106:109]
	v_mfma_f32_16x16x32_bf16 v[94:97], v[150:153], v[208:211], v[94:97]
	v_mfma_f32_16x16x32_bf16 v[90:93], v[168:171], v[208:211], v[90:93]
	v_mfma_f32_16x16x32_bf16 v[78:81], v[150:153], v[216:219], v[78:81]
	v_mfma_f32_16x16x32_bf16 v[74:77], v[168:171], v[216:219], v[74:77]
	v_mfma_f32_16x16x32_bf16 v[118:121], v[172:175], v[188:191], v[118:121]
	v_mfma_f32_16x16x32_bf16 v[114:117], v[180:183], v[188:191], v[114:117]
	v_mfma_f32_16x16x32_bf16 v[102:105], v[172:175], v[196:199], v[102:105]
	v_mfma_f32_16x16x32_bf16 v[98:101], v[180:183], v[196:199], v[98:101]
	v_mfma_f32_16x16x32_bf16 v[86:89], v[172:175], v[204:207], v[86:89]
	v_mfma_f32_16x16x32_bf16 v[82:85], v[180:183], v[204:207], v[82:85]
	v_mfma_f32_16x16x32_bf16 v[70:73], v[172:175], v[212:215], v[70:73]
	v_mfma_f32_16x16x32_bf16 v[66:69], v[180:183], v[212:215], v[66:69]
	v_mfma_f32_16x16x32_bf16 v[118:121], v[176:179], v[192:195], v[118:121]
	v_mfma_f32_16x16x32_bf16 v[114:117], v[184:187], v[192:195], v[114:117]
	v_mfma_f32_16x16x32_bf16 v[102:105], v[176:179], v[200:203], v[102:105]
	v_mfma_f32_16x16x32_bf16 v[98:101], v[184:187], v[200:203], v[98:101]
	v_mfma_f32_16x16x32_bf16 v[86:89], v[176:179], v[208:211], v[86:89]
	v_mfma_f32_16x16x32_bf16 v[82:85], v[184:187], v[208:211], v[82:85]
	v_mfma_f32_16x16x32_bf16 v[70:73], v[176:179], v[216:219], v[70:73]
	v_mfma_f32_16x16x32_bf16 v[66:69], v[184:187], v[216:219], v[66:69]
	s_setprio 0
	s_barrier
	s_add_i32 s54, s46, s38
	v_lshl_add_u64 v[160:161], s[34:35], 0, v[132:133]
	s_mov_b32 m0, s54
	ds_read_b128 v[188:191], v158 offset:16384
	ds_read_b128 v[192:195], v158 offset:17408
	ds_read_b128 v[196:199], v158 offset:18432
	ds_read_b128 v[200:203], v158 offset:19456
	ds_read_b128 v[204:207], v158 offset:20480
	ds_read_b128 v[208:211], v158 offset:21504
	ds_read_b128 v[212:215], v158 offset:22528
	ds_read_b128 v[216:219], v158 offset:23552
	global_load_lds_dwordx4 v132, s[34:35]
	s_add_i32 m0, s54, 0x2000
	s_add_u32 s54, s34, 0x100000
	v_lshl_add_u64 v[220:221], s[34:35], 0, v[136:137]
	s_addc_u32 s55, s35, 0
	s_add_i32 s56, s47, s38
	global_load_lds_dwordx4 v136, s[34:35]
	s_mov_b32 m0, s56
	v_lshl_add_u64 v[224:225], s[36:37], 0, v[134:135]
	global_load_lds_dwordx4 v132, s[54:55]
	s_add_i32 m0, s56, 0x2000
	s_nop 0
	global_load_lds_dwordx4 v136, s[54:55]
	v_lshl_add_u64 v[222:223], s[36:37], 0, v[130:131]
	s_waitcnt vmcnt(6)
	s_waitcnt lgkmcnt(0)
	s_setprio 1
	s_barrier
	v_mfma_f32_16x16x32_bf16 v[62:65], v[146:149], v[188:191], v[62:65]
	v_mfma_f32_16x16x32_bf16 v[58:61], v[164:167], v[188:191], v[58:61]
	v_mfma_f32_16x16x32_bf16 v[46:49], v[146:149], v[196:199], v[46:49]
	v_mfma_f32_16x16x32_bf16 v[42:45], v[164:167], v[196:199], v[42:45]
	v_mfma_f32_16x16x32_bf16 v[30:33], v[146:149], v[204:207], v[30:33]
	v_mfma_f32_16x16x32_bf16 v[26:29], v[164:167], v[204:207], v[26:29]
	v_mfma_f32_16x16x32_bf16 v[14:17], v[146:149], v[212:215], v[14:17]
	v_mfma_f32_16x16x32_bf16 v[10:13], v[164:167], v[212:215], v[10:13]
	v_mfma_f32_16x16x32_bf16 v[62:65], v[150:153], v[192:195], v[62:65]
	v_mfma_f32_16x16x32_bf16 v[58:61], v[168:171], v[192:195], v[58:61]
	v_mfma_f32_16x16x32_bf16 v[46:49], v[150:153], v[200:203], v[46:49]
	v_mfma_f32_16x16x32_bf16 v[42:45], v[168:171], v[200:203], v[42:45]
	v_mfma_f32_16x16x32_bf16 v[30:33], v[150:153], v[208:211], v[30:33]
	v_mfma_f32_16x16x32_bf16 v[26:29], v[168:171], v[208:211], v[26:29]
	v_mfma_f32_16x16x32_bf16 v[14:17], v[150:153], v[216:219], v[14:17]
	v_mfma_f32_16x16x32_bf16 v[10:13], v[168:171], v[216:219], v[10:13]
	v_mfma_f32_16x16x32_bf16 v[54:57], v[172:175], v[188:191], v[54:57]
	v_mfma_f32_16x16x32_bf16 v[50:53], v[180:183], v[188:191], v[50:53]
	v_mfma_f32_16x16x32_bf16 v[38:41], v[172:175], v[196:199], v[38:41]
	v_mfma_f32_16x16x32_bf16 v[34:37], v[180:183], v[196:199], v[34:37]
	v_mfma_f32_16x16x32_bf16 v[22:25], v[172:175], v[204:207], v[22:25]
	v_mfma_f32_16x16x32_bf16 v[18:21], v[180:183], v[204:207], v[18:21]
	v_mfma_f32_16x16x32_bf16 v[6:9], v[172:175], v[212:215], v[6:9]
	v_mfma_f32_16x16x32_bf16 v[2:5], v[180:183], v[212:215], v[2:5]
	v_mfma_f32_16x16x32_bf16 v[54:57], v[176:179], v[192:195], v[54:57]
	v_mfma_f32_16x16x32_bf16 v[50:53], v[184:187], v[192:195], v[50:53]
	v_mfma_f32_16x16x32_bf16 v[38:41], v[176:179], v[200:203], v[38:41]
	v_mfma_f32_16x16x32_bf16 v[34:37], v[184:187], v[200:203], v[34:37]
	v_mfma_f32_16x16x32_bf16 v[22:25], v[176:179], v[208:211], v[22:25]
	v_mfma_f32_16x16x32_bf16 v[18:21], v[184:187], v[208:211], v[18:21]
	v_mfma_f32_16x16x32_bf16 v[6:9], v[176:179], v[216:219], v[6:9]
	v_mfma_f32_16x16x32_bf16 v[2:5], v[184:187], v[216:219], v[2:5]
	s_setprio 0
	s_barrier
	s_add_i32 s54, 0, 0x18000
	v_add_u32_e32 v159, s54, v154
	s_add_i32 s55, 0, 0x1c000
	ds_read_b128 v[146:149], v159
	ds_read_b128 v[150:153], v159 offset:1024
	ds_read_b128 v[164:167], v159 offset:2048
	ds_read_b128 v[168:171], v159 offset:3072
	v_add_u32_e32 v159, s55, v154
	ds_read_b128 v[172:175], v159
	ds_read_b128 v[176:179], v159 offset:1024
	ds_read_b128 v[180:183], v159 offset:2048
	ds_read_b128 v[184:187], v159 offset:3072
	s_add_u32 s36, s36, 0x100000
	s_addc_u32 s37, s37, 0
	s_mov_b32 m0, s40
	ds_read_b128 v[188:191], v158 offset:32768
	ds_read_b128 v[192:195], v158 offset:33792
	ds_read_b128 v[196:199], v158 offset:34816
	ds_read_b128 v[200:203], v158 offset:35840
	ds_read_b128 v[204:207], v158 offset:36864
	ds_read_b128 v[208:211], v158 offset:37888
	ds_read_b128 v[212:215], v158 offset:38912
	ds_read_b128 v[216:219], v158 offset:39936
	s_mov_b32 m0, s29
	s_nop 0
	global_load_lds_dwordx4 v[222:223], off
	s_mov_b32 m0, s39
	s_nop 0
	global_load_lds_dwordx4 v[224:225], off
	s_mov_b32 m0, s40
	s_nop 0
	global_load_lds_dwordx4 v130, s[36:37]
	s_mov_b32 m0, s41
	s_nop 0
	global_load_lds_dwordx4 v134, s[36:37]
	s_waitcnt vmcnt(8)
	s_waitcnt lgkmcnt(0)
	s_setprio 1
	s_barrier
	v_mfma_f32_16x16x32_bf16 v[126:129], v[146:149], v[188:191], v[126:129]
	v_mfma_f32_16x16x32_bf16 v[122:125], v[164:167], v[188:191], v[122:125]
	v_mfma_f32_16x16x32_bf16 v[110:113], v[146:149], v[196:199], v[110:113]
	v_mfma_f32_16x16x32_bf16 v[106:109], v[164:167], v[196:199], v[106:109]
	v_mfma_f32_16x16x32_bf16 v[94:97], v[146:149], v[204:207], v[94:97]
	v_mfma_f32_16x16x32_bf16 v[90:93], v[164:167], v[204:207], v[90:93]
	v_mfma_f32_16x16x32_bf16 v[78:81], v[146:149], v[212:215], v[78:81]
	v_mfma_f32_16x16x32_bf16 v[74:77], v[164:167], v[212:215], v[74:77]
	v_mfma_f32_16x16x32_bf16 v[126:129], v[150:153], v[192:195], v[126:129]
	v_mfma_f32_16x16x32_bf16 v[122:125], v[168:171], v[192:195], v[122:125]
	v_mfma_f32_16x16x32_bf16 v[110:113], v[150:153], v[200:203], v[110:113]
	v_mfma_f32_16x16x32_bf16 v[106:109], v[168:171], v[200:203], v[106:109]
	v_mfma_f32_16x16x32_bf16 v[94:97], v[150:153], v[208:211], v[94:97]
	v_mfma_f32_16x16x32_bf16 v[90:93], v[168:171], v[208:211], v[90:93]
	v_mfma_f32_16x16x32_bf16 v[78:81], v[150:153], v[216:219], v[78:81]
	v_mfma_f32_16x16x32_bf16 v[74:77], v[168:171], v[216:219], v[74:77]
	v_mfma_f32_16x16x32_bf16 v[118:121], v[172:175], v[188:191], v[118:121]
	v_mfma_f32_16x16x32_bf16 v[114:117], v[180:183], v[188:191], v[114:117]
	v_mfma_f32_16x16x32_bf16 v[102:105], v[172:175], v[196:199], v[102:105]
	v_mfma_f32_16x16x32_bf16 v[98:101], v[180:183], v[196:199], v[98:101]
	v_mfma_f32_16x16x32_bf16 v[86:89], v[172:175], v[204:207], v[86:89]
	v_mfma_f32_16x16x32_bf16 v[82:85], v[180:183], v[204:207], v[82:85]
	v_mfma_f32_16x16x32_bf16 v[70:73], v[172:175], v[212:215], v[70:73]
	v_mfma_f32_16x16x32_bf16 v[66:69], v[180:183], v[212:215], v[66:69]
	v_mfma_f32_16x16x32_bf16 v[118:121], v[176:179], v[192:195], v[118:121]
	v_mfma_f32_16x16x32_bf16 v[114:117], v[184:187], v[192:195], v[114:117]
	v_mfma_f32_16x16x32_bf16 v[102:105], v[176:179], v[200:203], v[102:105]
	v_mfma_f32_16x16x32_bf16 v[98:101], v[184:187], v[200:203], v[98:101]
	v_mfma_f32_16x16x32_bf16 v[86:89], v[176:179], v[208:211], v[86:89]
	v_mfma_f32_16x16x32_bf16 v[82:85], v[184:187], v[208:211], v[82:85]
	v_mfma_f32_16x16x32_bf16 v[70:73], v[176:179], v[216:219], v[70:73]
	v_mfma_f32_16x16x32_bf16 v[66:69], v[184:187], v[216:219], v[66:69]
	s_setprio 0
	s_barrier
	s_add_i32 s36, s54, s38
	v_lshl_add_u64 v[160:161], v[160:161], 0, s[10:11]
	s_mov_b32 m0, s36
	ds_read_b128 v[188:191], v158 offset:49152
	ds_read_b128 v[192:195], v158 offset:50176
	ds_read_b128 v[196:199], v158 offset:51200
	ds_read_b128 v[200:203], v158 offset:52224
	ds_read_b128 v[204:207], v158 offset:53248
	ds_read_b128 v[208:211], v158 offset:54272
	ds_read_b128 v[212:215], v158 offset:55296
	ds_read_b128 v[216:219], v158 offset:56320
	global_load_lds_dwordx4 v[160:161], off
	s_add_i32 m0, s36, 0x2000
	s_add_u32 s34, s34, 0x100080
	v_lshl_add_u64 v[160:161], v[220:221], 0, s[10:11]
	s_addc_u32 s35, s35, 0
	s_add_i32 s36, s55, s38
	global_load_lds_dwordx4 v[160:161], off
	s_mov_b32 m0, s36
	s_nop 0
	global_load_lds_dwordx4 v132, s[34:35]
	s_add_i32 m0, s36, 0x2000
	s_nop 0
	global_load_lds_dwordx4 v136, s[34:35]
	v_lshl_add_u64 v[222:223], v[222:223], 0, s[10:11]
	v_lshl_add_u64 v[224:225], v[224:225], 0, s[10:11]
	s_waitcnt vmcnt(6)
	s_waitcnt lgkmcnt(0)
	s_setprio 1
	s_barrier
	v_mfma_f32_16x16x32_bf16 v[62:65], v[146:149], v[188:191], v[62:65]
	v_mfma_f32_16x16x32_bf16 v[58:61], v[164:167], v[188:191], v[58:61]
	v_mfma_f32_16x16x32_bf16 v[46:49], v[146:149], v[196:199], v[46:49]
	v_mfma_f32_16x16x32_bf16 v[42:45], v[164:167], v[196:199], v[42:45]
	v_mfma_f32_16x16x32_bf16 v[30:33], v[146:149], v[204:207], v[30:33]
	v_mfma_f32_16x16x32_bf16 v[26:29], v[164:167], v[204:207], v[26:29]
	v_mfma_f32_16x16x32_bf16 v[14:17], v[146:149], v[212:215], v[14:17]
	v_mfma_f32_16x16x32_bf16 v[10:13], v[164:167], v[212:215], v[10:13]
	v_mfma_f32_16x16x32_bf16 v[62:65], v[150:153], v[192:195], v[62:65]
	v_mfma_f32_16x16x32_bf16 v[58:61], v[168:171], v[192:195], v[58:61]
	v_mfma_f32_16x16x32_bf16 v[46:49], v[150:153], v[200:203], v[46:49]
	v_mfma_f32_16x16x32_bf16 v[42:45], v[168:171], v[200:203], v[42:45]
	v_mfma_f32_16x16x32_bf16 v[30:33], v[150:153], v[208:211], v[30:33]
	v_mfma_f32_16x16x32_bf16 v[26:29], v[168:171], v[208:211], v[26:29]
	v_mfma_f32_16x16x32_bf16 v[14:17], v[150:153], v[216:219], v[14:17]
	v_mfma_f32_16x16x32_bf16 v[10:13], v[168:171], v[216:219], v[10:13]
	v_mfma_f32_16x16x32_bf16 v[54:57], v[172:175], v[188:191], v[54:57]
	v_mfma_f32_16x16x32_bf16 v[50:53], v[180:183], v[188:191], v[50:53]
	v_mfma_f32_16x16x32_bf16 v[38:41], v[172:175], v[196:199], v[38:41]
	v_mfma_f32_16x16x32_bf16 v[34:37], v[180:183], v[196:199], v[34:37]
	v_mfma_f32_16x16x32_bf16 v[22:25], v[172:175], v[204:207], v[22:25]
	v_mfma_f32_16x16x32_bf16 v[18:21], v[180:183], v[204:207], v[18:21]
	v_mfma_f32_16x16x32_bf16 v[6:9], v[172:175], v[212:215], v[6:9]
	v_mfma_f32_16x16x32_bf16 v[2:5], v[180:183], v[212:215], v[2:5]
	v_mfma_f32_16x16x32_bf16 v[54:57], v[176:179], v[192:195], v[54:57]
	v_mfma_f32_16x16x32_bf16 v[50:53], v[184:187], v[192:195], v[50:53]
	v_mfma_f32_16x16x32_bf16 v[38:41], v[176:179], v[200:203], v[38:41]
	v_mfma_f32_16x16x32_bf16 v[34:37], v[184:187], v[200:203], v[34:37]
	v_mfma_f32_16x16x32_bf16 v[22:25], v[176:179], v[208:211], v[22:25]
	v_mfma_f32_16x16x32_bf16 v[18:21], v[184:187], v[208:211], v[18:21]
	v_mfma_f32_16x16x32_bf16 v[6:9], v[176:179], v[216:219], v[6:9]
	v_mfma_f32_16x16x32_bf16 v[2:5], v[184:187], v[216:219], v[2:5]
	s_setprio 0
	s_barrier
	s_add_i32 s53, s53, 2
	s_mov_b32 s32, 1
	s_add_u32 s30, s30, 0x100
	s_addc_u32 s31, s31, 0
	s_add_u32 s51, s51, 0x100
	s_addc_u32 s52, s52, 0
	s_cmp_gt_u32 s53, 61
	s_cbranch_scc0 .LBB0_1131
	s_and_b64 vcc, exec, s[12:13]
	s_cbranch_vccz .LBB0_1134
	s_barrier

.LBB0_1260:
	ds_read_b128 v[148:151], v166
	ds_read_b128 v[152:155], v166 offset:1024
	ds_read_b128 v[156:159], v166 offset:2048
	ds_read_b128 v[170:173], v166 offset:3072
	ds_read_b128 v[174:177], v167
	ds_read_b128 v[178:181], v167 offset:1024
	ds_read_b128 v[182:185], v167 offset:2048
	ds_read_b128 v[186:189], v167 offset:3072
	s_add_u32 s28, s26, 0xfff00080
	s_addc_u32 s29, s27, -1
	s_cmp_eq_u32 s55, 60
	s_cselect_b32 s31, s19, s29
	s_cselect_b32 s30, s25, s28
	s_cselect_b32 s29, s17, s54
	s_cselect_b32 s28, s52, s53
	s_add_i32 m0, s36, 0xc000
	ds_read_b128 v[190:193], v168
	ds_read_b128 v[194:197], v168 offset:1024
	ds_read_b128 v[198:201], v168 offset:2048
	ds_read_b128 v[202:205], v168 offset:3072
	ds_read_b128 v[206:209], v168 offset:4096
	ds_read_b128 v[210:213], v168 offset:5120
	ds_read_b128 v[214:217], v168 offset:6144
	ds_read_b128 v[218:221], v168 offset:7168
	s_cmp_lg_u32 s32, 0
	s_cbranch_scc0 .Lrebal_skip_1260
	s_mov_b32 m0, s41
	s_nop 0
	global_load_lds_dwordx4 v[224:225], off
	s_mov_b32 m0, s42
	s_nop 0
	global_load_lds_dwordx4 v[226:227], off
.Lrebal_skip_1260:
	s_add_i32 m0, s36, 0xc000
	s_nop 0
	global_load_lds_dwordx4 v140, s[26:27]
	s_add_i32 m0, s36, 0xe000
	s_nop 0
	global_load_lds_dwordx4 v142, s[26:27]
	s_waitcnt vmcnt(8)
	s_waitcnt lgkmcnt(0)
	s_setprio 1
	s_barrier
	v_mfma_f32_16x16x32_bf16 v[126:129], v[148:151], v[190:193], v[126:129]
	v_mfma_f32_16x16x32_bf16 v[122:125], v[156:159], v[190:193], v[122:125]
	v_mfma_f32_16x16x32_bf16 v[110:113], v[148:151], v[198:201], v[110:113]
	v_mfma_f32_16x16x32_bf16 v[106:109], v[156:159], v[198:201], v[106:109]
	v_mfma_f32_16x16x32_bf16 v[94:97], v[148:151], v[206:209], v[94:97]
	v_mfma_f32_16x16x32_bf16 v[90:93], v[156:159], v[206:209], v[90:93]
	v_mfma_f32_16x16x32_bf16 v[86:89], v[148:151], v[214:217], v[86:89]
	v_mfma_f32_16x16x32_bf16 v[78:81], v[156:159], v[214:217], v[78:81]
	v_mfma_f32_16x16x32_bf16 v[126:129], v[152:155], v[194:197], v[126:129]
	v_mfma_f32_16x16x32_bf16 v[122:125], v[170:173], v[194:197], v[122:125]
	v_mfma_f32_16x16x32_bf16 v[110:113], v[152:155], v[202:205], v[110:113]
	v_mfma_f32_16x16x32_bf16 v[106:109], v[170:173], v[202:205], v[106:109]
	v_mfma_f32_16x16x32_bf16 v[94:97], v[152:155], v[210:213], v[94:97]
	v_mfma_f32_16x16x32_bf16 v[90:93], v[170:173], v[210:213], v[90:93]
	v_mfma_f32_16x16x32_bf16 v[86:89], v[152:155], v[218:221], v[86:89]
	v_mfma_f32_16x16x32_bf16 v[78:81], v[170:173], v[218:221], v[78:81]
	v_mfma_f32_16x16x32_bf16 v[118:121], v[174:177], v[190:193], v[118:121]
	v_mfma_f32_16x16x32_bf16 v[114:117], v[182:185], v[190:193], v[114:117]
	v_mfma_f32_16x16x32_bf16 v[102:105], v[174:177], v[198:201], v[102:105]
	v_mfma_f32_16x16x32_bf16 v[98:101], v[182:185], v[198:201], v[98:101]
	v_mfma_f32_16x16x32_bf16 v[82:85], v[174:177], v[206:209], v[82:85]
	v_mfma_f32_16x16x32_bf16 v[74:77], v[182:185], v[206:209], v[74:77]
	v_mfma_f32_16x16x32_bf16 v[70:73], v[174:177], v[214:217], v[70:73]
	v_mfma_f32_16x16x32_bf16 v[66:69], v[182:185], v[214:217], v[66:69]
	v_mfma_f32_16x16x32_bf16 v[118:121], v[178:181], v[194:197], v[118:121]
	v_mfma_f32_16x16x32_bf16 v[114:117], v[186:189], v[194:197], v[114:117]
	v_mfma_f32_16x16x32_bf16 v[102:105], v[178:181], v[202:205], v[102:105]
	v_mfma_f32_16x16x32_bf16 v[98:101], v[186:189], v[202:205], v[98:101]
	v_mfma_f32_16x16x32_bf16 v[82:85], v[178:181], v[210:213], v[82:85]
	v_mfma_f32_16x16x32_bf16 v[74:77], v[186:189], v[210:213], v[74:77]
	v_mfma_f32_16x16x32_bf16 v[70:73], v[178:181], v[218:221], v[70:73]
	v_mfma_f32_16x16x32_bf16 v[66:69], v[186:189], v[218:221], v[66:69]
	s_setprio 0
	s_barrier
	s_add_i32 s56, s44, s33
	v_lshl_add_u64 v[160:161], s[28:29], 0, v[134:135]
	s_mov_b32 m0, s56
	ds_read_b128 v[190:193], v168 offset:16384
	ds_read_b128 v[194:197], v168 offset:17408
	ds_read_b128 v[198:201], v168 offset:18432
	ds_read_b128 v[202:205], v168 offset:19456
	ds_read_b128 v[206:209], v168 offset:20480
	ds_read_b128 v[210:213], v168 offset:21504
	ds_read_b128 v[214:217], v168 offset:22528
	ds_read_b128 v[218:221], v168 offset:23552
	global_load_lds_dwordx4 v134, s[28:29]
	s_add_i32 m0, s56, 0x2000
	s_add_u32 s56, s28, 0x100000
	v_lshl_add_u64 v[222:223], s[28:29], 0, v[130:131]
	s_addc_u32 s57, s29, 0
	s_add_i32 s58, s45, s33
	global_load_lds_dwordx4 v130, s[28:29]
	s_mov_b32 m0, s58
	v_lshl_add_u64 v[226:227], s[30:31], 0, v[132:133]
	global_load_lds_dwordx4 v134, s[56:57]
	s_add_i32 m0, s58, 0x2000
	s_nop 0
	global_load_lds_dwordx4 v130, s[56:57]
	v_lshl_add_u64 v[224:225], s[30:31], 0, v[136:137]
	s_waitcnt vmcnt(6)
	s_waitcnt lgkmcnt(0)
	s_setprio 1
	s_barrier
	v_mfma_f32_16x16x32_bf16 v[62:65], v[148:151], v[190:193], v[62:65]
	v_mfma_f32_16x16x32_bf16 v[58:61], v[156:159], v[190:193], v[58:61]
	v_mfma_f32_16x16x32_bf16 v[46:49], v[148:151], v[198:201], v[46:49]
	v_mfma_f32_16x16x32_bf16 v[42:45], v[156:159], v[198:201], v[42:45]
	v_mfma_f32_16x16x32_bf16 v[30:33], v[148:151], v[206:209], v[30:33]
	v_mfma_f32_16x16x32_bf16 v[26:29], v[156:159], v[206:209], v[26:29]
	v_mfma_f32_16x16x32_bf16 v[14:17], v[148:151], v[214:217], v[14:17]
	v_mfma_f32_16x16x32_bf16 v[10:13], v[156:159], v[214:217], v[10:13]
	v_mfma_f32_16x16x32_bf16 v[62:65], v[152:155], v[194:197], v[62:65]
	v_mfma_f32_16x16x32_bf16 v[58:61], v[170:173], v[194:197], v[58:61]
	v_mfma_f32_16x16x32_bf16 v[46:49], v[152:155], v[202:205], v[46:49]
	v_mfma_f32_16x16x32_bf16 v[42:45], v[170:173], v[202:205], v[42:45]
	v_mfma_f32_16x16x32_bf16 v[30:33], v[152:155], v[210:213], v[30:33]
	v_mfma_f32_16x16x32_bf16 v[26:29], v[170:173], v[210:213], v[26:29]
	v_mfma_f32_16x16x32_bf16 v[14:17], v[152:155], v[218:221], v[14:17]
	v_mfma_f32_16x16x32_bf16 v[10:13], v[170:173], v[218:221], v[10:13]
	v_mfma_f32_16x16x32_bf16 v[54:57], v[174:177], v[190:193], v[54:57]
	v_mfma_f32_16x16x32_bf16 v[50:53], v[182:185], v[190:193], v[50:53]
	v_mfma_f32_16x16x32_bf16 v[38:41], v[174:177], v[198:201], v[38:41]
	v_mfma_f32_16x16x32_bf16 v[34:37], v[182:185], v[198:201], v[34:37]
	v_mfma_f32_16x16x32_bf16 v[22:25], v[174:177], v[206:209], v[22:25]
	v_mfma_f32_16x16x32_bf16 v[18:21], v[182:185], v[206:209], v[18:21]
	v_mfma_f32_16x16x32_bf16 v[6:9], v[174:177], v[214:217], v[6:9]
	v_mfma_f32_16x16x32_bf16 v[2:5], v[182:185], v[214:217], v[2:5]
	v_mfma_f32_16x16x32_bf16 v[54:57], v[178:181], v[194:197], v[54:57]
	v_mfma_f32_16x16x32_bf16 v[50:53], v[186:189], v[194:197], v[50:53]
	v_mfma_f32_16x16x32_bf16 v[38:41], v[178:181], v[202:205], v[38:41]
	v_mfma_f32_16x16x32_bf16 v[34:37], v[186:189], v[202:205], v[34:37]
	v_mfma_f32_16x16x32_bf16 v[22:25], v[178:181], v[210:213], v[22:25]
	v_mfma_f32_16x16x32_bf16 v[18:21], v[186:189], v[210:213], v[18:21]
	v_mfma_f32_16x16x32_bf16 v[6:9], v[178:181], v[218:221], v[6:9]
	v_mfma_f32_16x16x32_bf16 v[2:5], v[186:189], v[218:221], v[2:5]
	s_setprio 0
	s_barrier
	s_add_i32 s56, 0, 0x18000
	v_add_u32_e32 v169, s56, v164
	s_add_i32 s57, 0, 0x1c000
	ds_read_b128 v[148:151], v169
	ds_read_b128 v[152:155], v169 offset:1024
	ds_read_b128 v[156:159], v169 offset:2048
	ds_read_b128 v[170:173], v169 offset:3072
	v_add_u32_e32 v169, s57, v164
	ds_read_b128 v[174:177], v169
	ds_read_b128 v[178:181], v169 offset:1024
	ds_read_b128 v[182:185], v169 offset:2048
	ds_read_b128 v[186:189], v169 offset:3072
	s_add_u32 s30, s30, 0x100000
	s_addc_u32 s31, s31, 0
	s_mov_b32 m0, s38
	ds_read_b128 v[190:193], v168 offset:32768
	ds_read_b128 v[194:197], v168 offset:33792
	ds_read_b128 v[198:201], v168 offset:34816
	ds_read_b128 v[202:205], v168 offset:35840
	ds_read_b128 v[206:209], v168 offset:36864
	ds_read_b128 v[210:213], v168 offset:37888
	ds_read_b128 v[214:217], v168 offset:38912
	ds_read_b128 v[218:221], v168 offset:39936
	s_mov_b32 m0, s36
	s_nop 0
	global_load_lds_dwordx4 v[224:225], off
	s_mov_b32 m0, s37
	s_nop 0
	global_load_lds_dwordx4 v[226:227], off
	s_mov_b32 m0, s38
	s_nop 0
	global_load_lds_dwordx4 v136, s[30:31]
	s_mov_b32 m0, s39
	s_nop 0
	global_load_lds_dwordx4 v132, s[30:31]
	s_waitcnt vmcnt(8)
	s_waitcnt lgkmcnt(0)
	s_setprio 1
	s_barrier
	v_mfma_f32_16x16x32_bf16 v[126:129], v[148:151], v[190:193], v[126:129]
	v_mfma_f32_16x16x32_bf16 v[122:125], v[156:159], v[190:193], v[122:125]
	v_mfma_f32_16x16x32_bf16 v[110:113], v[148:151], v[198:201], v[110:113]
	v_mfma_f32_16x16x32_bf16 v[106:109], v[156:159], v[198:201], v[106:109]
	v_mfma_f32_16x16x32_bf16 v[94:97], v[148:151], v[206:209], v[94:97]
	v_mfma_f32_16x16x32_bf16 v[90:93], v[156:159], v[206:209], v[90:93]
	v_mfma_f32_16x16x32_bf16 v[86:89], v[148:151], v[214:217], v[86:89]
	v_mfma_f32_16x16x32_bf16 v[78:81], v[156:159], v[214:217], v[78:81]
	v_mfma_f32_16x16x32_bf16 v[126:129], v[152:155], v[194:197], v[126:129]
	v_mfma_f32_16x16x32_bf16 v[122:125], v[170:173], v[194:197], v[122:125]
	v_mfma_f32_16x16x32_bf16 v[110:113], v[152:155], v[202:205], v[110:113]
	v_mfma_f32_16x16x32_bf16 v[106:109], v[170:173], v[202:205], v[106:109]
	v_mfma_f32_16x16x32_bf16 v[94:97], v[152:155], v[210:213], v[94:97]
	v_mfma_f32_16x16x32_bf16 v[90:93], v[170:173], v[210:213], v[90:93]
	v_mfma_f32_16x16x32_bf16 v[86:89], v[152:155], v[218:221], v[86:89]
	v_mfma_f32_16x16x32_bf16 v[78:81], v[170:173], v[218:221], v[78:81]
	v_mfma_f32_16x16x32_bf16 v[118:121], v[174:177], v[190:193], v[118:121]
	v_mfma_f32_16x16x32_bf16 v[114:117], v[182:185], v[190:193], v[114:117]
	v_mfma_f32_16x16x32_bf16 v[102:105], v[174:177], v[198:201], v[102:105]
	v_mfma_f32_16x16x32_bf16 v[98:101], v[182:185], v[198:201], v[98:101]
	v_mfma_f32_16x16x32_bf16 v[82:85], v[174:177], v[206:209], v[82:85]
	v_mfma_f32_16x16x32_bf16 v[74:77], v[182:185], v[206:209], v[74:77]
	v_mfma_f32_16x16x32_bf16 v[70:73], v[174:177], v[214:217], v[70:73]
	v_mfma_f32_16x16x32_bf16 v[66:69], v[182:185], v[214:217], v[66:69]
	v_mfma_f32_16x16x32_bf16 v[118:121], v[178:181], v[194:197], v[118:121]
	v_mfma_f32_16x16x32_bf16 v[114:117], v[186:189], v[194:197], v[114:117]
	v_mfma_f32_16x16x32_bf16 v[102:105], v[178:181], v[202:205], v[102:105]
	v_mfma_f32_16x16x32_bf16 v[98:101], v[186:189], v[202:205], v[98:101]
	v_mfma_f32_16x16x32_bf16 v[82:85], v[178:181], v[210:213], v[82:85]
	v_mfma_f32_16x16x32_bf16 v[74:77], v[186:189], v[210:213], v[74:77]
	v_mfma_f32_16x16x32_bf16 v[70:73], v[178:181], v[218:221], v[70:73]
	v_mfma_f32_16x16x32_bf16 v[66:69], v[186:189], v[218:221], v[66:69]
	s_setprio 0
	s_barrier
	s_add_i32 s30, s56, s33
	v_lshl_add_u64 v[160:161], v[160:161], 0, s[6:7]
	s_mov_b32 m0, s30
	ds_read_b128 v[190:193], v168 offset:49152
	ds_read_b128 v[194:197], v168 offset:50176
	ds_read_b128 v[198:201], v168 offset:51200
	ds_read_b128 v[202:205], v168 offset:52224
	ds_read_b128 v[206:209], v168 offset:53248
	ds_read_b128 v[210:213], v168 offset:54272
	ds_read_b128 v[214:217], v168 offset:55296
	ds_read_b128 v[218:221], v168 offset:56320
	global_load_lds_dwordx4 v[160:161], off
	s_add_i32 m0, s30, 0x2000
	s_add_u32 s28, s28, 0x100080
	v_lshl_add_u64 v[160:161], v[222:223], 0, s[6:7]
	s_addc_u32 s29, s29, 0
	s_add_i32 s30, s57, s33
	global_load_lds_dwordx4 v[160:161], off
	s_mov_b32 m0, s30
	s_nop 0
	global_load_lds_dwordx4 v134, s[28:29]
	s_add_i32 m0, s30, 0x2000
	s_nop 0
	global_load_lds_dwordx4 v130, s[28:29]
	v_lshl_add_u64 v[224:225], v[224:225], 0, s[6:7]
	v_lshl_add_u64 v[226:227], v[226:227], 0, s[6:7]
	s_waitcnt vmcnt(6)
	s_waitcnt lgkmcnt(0)
	s_setprio 1
	s_barrier
	v_mfma_f32_16x16x32_bf16 v[62:65], v[148:151], v[190:193], v[62:65]
	v_mfma_f32_16x16x32_bf16 v[58:61], v[156:159], v[190:193], v[58:61]
	v_mfma_f32_16x16x32_bf16 v[46:49], v[148:151], v[198:201], v[46:49]
	v_mfma_f32_16x16x32_bf16 v[42:45], v[156:159], v[198:201], v[42:45]
	v_mfma_f32_16x16x32_bf16 v[30:33], v[148:151], v[206:209], v[30:33]
	v_mfma_f32_16x16x32_bf16 v[26:29], v[156:159], v[206:209], v[26:29]
	v_mfma_f32_16x16x32_bf16 v[14:17], v[148:151], v[214:217], v[14:17]
	v_mfma_f32_16x16x32_bf16 v[10:13], v[156:159], v[214:217], v[10:13]
	v_mfma_f32_16x16x32_bf16 v[62:65], v[152:155], v[194:197], v[62:65]
	v_mfma_f32_16x16x32_bf16 v[58:61], v[170:173], v[194:197], v[58:61]
	v_mfma_f32_16x16x32_bf16 v[46:49], v[152:155], v[202:205], v[46:49]
	v_mfma_f32_16x16x32_bf16 v[42:45], v[170:173], v[202:205], v[42:45]
	v_mfma_f32_16x16x32_bf16 v[30:33], v[152:155], v[210:213], v[30:33]
	v_mfma_f32_16x16x32_bf16 v[26:29], v[170:173], v[210:213], v[26:29]
	v_mfma_f32_16x16x32_bf16 v[14:17], v[152:155], v[218:221], v[14:17]
	v_mfma_f32_16x16x32_bf16 v[10:13], v[170:173], v[218:221], v[10:13]
	v_mfma_f32_16x16x32_bf16 v[54:57], v[174:177], v[190:193], v[54:57]
	v_mfma_f32_16x16x32_bf16 v[50:53], v[182:185], v[190:193], v[50:53]
	v_mfma_f32_16x16x32_bf16 v[38:41], v[174:177], v[198:201], v[38:41]
	v_mfma_f32_16x16x32_bf16 v[34:37], v[182:185], v[198:201], v[34:37]
	v_mfma_f32_16x16x32_bf16 v[22:25], v[174:177], v[206:209], v[22:25]
	v_mfma_f32_16x16x32_bf16 v[18:21], v[182:185], v[206:209], v[18:21]
	v_mfma_f32_16x16x32_bf16 v[6:9], v[174:177], v[214:217], v[6:9]
	v_mfma_f32_16x16x32_bf16 v[2:5], v[182:185], v[214:217], v[2:5]
	v_mfma_f32_16x16x32_bf16 v[54:57], v[178:181], v[194:197], v[54:57]
	v_mfma_f32_16x16x32_bf16 v[50:53], v[186:189], v[194:197], v[50:53]
	v_mfma_f32_16x16x32_bf16 v[38:41], v[178:181], v[202:205], v[38:41]
	v_mfma_f32_16x16x32_bf16 v[34:37], v[186:189], v[202:205], v[34:37]
	v_mfma_f32_16x16x32_bf16 v[22:25], v[178:181], v[210:213], v[22:25]
	v_mfma_f32_16x16x32_bf16 v[18:21], v[186:189], v[210:213], v[18:21]
	v_mfma_f32_16x16x32_bf16 v[6:9], v[178:181], v[218:221], v[6:9]
	v_mfma_f32_16x16x32_bf16 v[2:5], v[186:189], v[218:221], v[2:5]
	s_setprio 0
	s_barrier
	s_add_i32 s55, s55, 2
	s_mov_b32 s32, 1
	s_add_u32 s26, s26, 0x100
	s_addc_u32 s27, s27, 0
	s_add_u32 s53, s53, 0x100
	s_addc_u32 s54, s54, 0
	s_cmp_gt_u32 s55, 61
	s_cbranch_scc0 .LBB0_1260
	s_and_b64 vcc, exec, s[8:9]
	s_cbranch_vccz .LBB0_1263
	s_barrier

.LBB0_1571:
	ds_read_b128 v[154:157], v150
	ds_read_b128 v[158:161], v150 offset:1024
	ds_read_b128 v[164:167], v150 offset:2048
	ds_read_b128 v[168:171], v150 offset:3072
	ds_read_b128 v[172:175], v151
	ds_read_b128 v[176:179], v151 offset:1024
	ds_read_b128 v[180:183], v151 offset:2048
	ds_read_b128 v[184:187], v151 offset:3072
	s_add_u32 s34, s30, 0xfff00080
	s_addc_u32 s35, s31, -1
	s_cmp_eq_u32 s57, 60
	s_cselect_b32 s37, s23, s35
	s_cselect_b32 s36, s53, s34
	s_cselect_b32 s35, s21, s56
	s_cselect_b32 s34, s54, s55
	s_add_i32 m0, s29, 0xc000
	ds_read_b128 v[188:191], v152
	ds_read_b128 v[192:195], v152 offset:1024
	ds_read_b128 v[196:199], v152 offset:2048
	ds_read_b128 v[200:203], v152 offset:3072
	ds_read_b128 v[204:207], v152 offset:4096
	ds_read_b128 v[208:211], v152 offset:5120
	ds_read_b128 v[212:215], v152 offset:6144
	ds_read_b128 v[216:219], v152 offset:7168
	s_cmp_lg_u32 s32, 0
	s_cbranch_scc0 .Lrebal_skip_1571
	s_mov_b32 m0, s43
	s_nop 0
	global_load_lds_dwordx4 v[222:223], off
	s_mov_b32 m0, s44
	s_nop 0
	global_load_lds_dwordx4 v[224:225], off
.Lrebal_skip_1571:
	s_add_i32 m0, s29, 0xc000
	s_nop 0
	global_load_lds_dwordx4 v138, s[30:31]
	s_add_i32 m0, s29, 0xe000
	s_nop 0
	global_load_lds_dwordx4 v140, s[30:31]
	s_waitcnt vmcnt(8)
	s_waitcnt lgkmcnt(0)
	s_setprio 1
	s_barrier
	v_mfma_f32_16x16x32_bf16 v[126:129], v[154:157], v[188:191], v[126:129]
	v_mfma_f32_16x16x32_bf16 v[122:125], v[164:167], v[188:191], v[122:125]
	v_mfma_f32_16x16x32_bf16 v[118:121], v[154:157], v[196:199], v[118:121]
	v_mfma_f32_16x16x32_bf16 v[110:113], v[164:167], v[196:199], v[110:113]
	v_mfma_f32_16x16x32_bf16 v[102:105], v[154:157], v[204:207], v[102:105]
	v_mfma_f32_16x16x32_bf16 v[94:97], v[164:167], v[204:207], v[94:97]
	v_mfma_f32_16x16x32_bf16 v[82:85], v[154:157], v[212:215], v[82:85]
	v_mfma_f32_16x16x32_bf16 v[74:77], v[164:167], v[212:215], v[74:77]
	v_mfma_f32_16x16x32_bf16 v[126:129], v[158:161], v[192:195], v[126:129]
	v_mfma_f32_16x16x32_bf16 v[122:125], v[168:171], v[192:195], v[122:125]
	v_mfma_f32_16x16x32_bf16 v[118:121], v[158:161], v[200:203], v[118:121]
	v_mfma_f32_16x16x32_bf16 v[110:113], v[168:171], v[200:203], v[110:113]
	v_mfma_f32_16x16x32_bf16 v[102:105], v[158:161], v[208:211], v[102:105]
	v_mfma_f32_16x16x32_bf16 v[94:97], v[168:171], v[208:211], v[94:97]
	v_mfma_f32_16x16x32_bf16 v[82:85], v[158:161], v[216:219], v[82:85]
	v_mfma_f32_16x16x32_bf16 v[74:77], v[168:171], v[216:219], v[74:77]
	v_mfma_f32_16x16x32_bf16 v[114:117], v[172:175], v[188:191], v[114:117]
	v_mfma_f32_16x16x32_bf16 v[106:109], v[180:183], v[188:191], v[106:109]
	v_mfma_f32_16x16x32_bf16 v[98:101], v[172:175], v[196:199], v[98:101]
	v_mfma_f32_16x16x32_bf16 v[90:93], v[180:183], v[196:199], v[90:93]
	v_mfma_f32_16x16x32_bf16 v[86:89], v[172:175], v[204:207], v[86:89]
	v_mfma_f32_16x16x32_bf16 v[78:81], v[180:183], v[204:207], v[78:81]
	v_mfma_f32_16x16x32_bf16 v[70:73], v[172:175], v[212:215], v[70:73]
	v_mfma_f32_16x16x32_bf16 v[66:69], v[180:183], v[212:215], v[66:69]
	v_mfma_f32_16x16x32_bf16 v[114:117], v[176:179], v[192:195], v[114:117]
	v_mfma_f32_16x16x32_bf16 v[106:109], v[184:187], v[192:195], v[106:109]
	v_mfma_f32_16x16x32_bf16 v[98:101], v[176:179], v[200:203], v[98:101]
	v_mfma_f32_16x16x32_bf16 v[90:93], v[184:187], v[200:203], v[90:93]
	v_mfma_f32_16x16x32_bf16 v[86:89], v[176:179], v[208:211], v[86:89]
	v_mfma_f32_16x16x32_bf16 v[78:81], v[184:187], v[208:211], v[78:81]
	v_mfma_f32_16x16x32_bf16 v[70:73], v[176:179], v[216:219], v[70:73]
	v_mfma_f32_16x16x32_bf16 v[66:69], v[184:187], v[216:219], v[66:69]
	s_setprio 0
	s_barrier
	s_add_i32 s58, s46, s38
	v_lshl_add_u64 v[146:147], s[34:35], 0, v[132:133]
	s_mov_b32 m0, s58
	ds_read_b128 v[188:191], v152 offset:16384
	ds_read_b128 v[192:195], v152 offset:17408
	ds_read_b128 v[196:199], v152 offset:18432
	ds_read_b128 v[200:203], v152 offset:19456
	ds_read_b128 v[204:207], v152 offset:20480
	ds_read_b128 v[208:211], v152 offset:21504
	ds_read_b128 v[212:215], v152 offset:22528
	ds_read_b128 v[216:219], v152 offset:23552
	global_load_lds_dwordx4 v132, s[34:35]
	s_add_i32 m0, s58, 0x2000
	s_add_u32 s58, s34, 0x100000
	v_lshl_add_u64 v[220:221], s[34:35], 0, v[136:137]
	s_addc_u32 s59, s35, 0
	s_add_i32 s60, s47, s38
	global_load_lds_dwordx4 v136, s[34:35]
	s_mov_b32 m0, s60
	v_lshl_add_u64 v[224:225], s[36:37], 0, v[134:135]
	global_load_lds_dwordx4 v132, s[58:59]
	s_add_i32 m0, s60, 0x2000
	s_nop 0
	global_load_lds_dwordx4 v136, s[58:59]
	v_lshl_add_u64 v[222:223], s[36:37], 0, v[130:131]
	s_waitcnt vmcnt(6)
	s_waitcnt lgkmcnt(0)
	s_setprio 1
	s_barrier
	v_mfma_f32_16x16x32_bf16 v[62:65], v[154:157], v[188:191], v[62:65]
	v_mfma_f32_16x16x32_bf16 v[58:61], v[164:167], v[188:191], v[58:61]
	v_mfma_f32_16x16x32_bf16 v[54:57], v[154:157], v[196:199], v[54:57]
	v_mfma_f32_16x16x32_bf16 v[46:49], v[164:167], v[196:199], v[46:49]
	v_mfma_f32_16x16x32_bf16 v[38:41], v[154:157], v[204:207], v[38:41]
	v_mfma_f32_16x16x32_bf16 v[30:33], v[164:167], v[204:207], v[30:33]
	v_mfma_f32_16x16x32_bf16 v[22:25], v[154:157], v[212:215], v[22:25]
	v_mfma_f32_16x16x32_bf16 v[14:17], v[164:167], v[212:215], v[14:17]
	v_mfma_f32_16x16x32_bf16 v[62:65], v[158:161], v[192:195], v[62:65]
	v_mfma_f32_16x16x32_bf16 v[58:61], v[168:171], v[192:195], v[58:61]
	v_mfma_f32_16x16x32_bf16 v[54:57], v[158:161], v[200:203], v[54:57]
	v_mfma_f32_16x16x32_bf16 v[46:49], v[168:171], v[200:203], v[46:49]
	v_mfma_f32_16x16x32_bf16 v[38:41], v[158:161], v[208:211], v[38:41]
	v_mfma_f32_16x16x32_bf16 v[30:33], v[168:171], v[208:211], v[30:33]
	v_mfma_f32_16x16x32_bf16 v[22:25], v[158:161], v[216:219], v[22:25]
	v_mfma_f32_16x16x32_bf16 v[14:17], v[168:171], v[216:219], v[14:17]
	v_mfma_f32_16x16x32_bf16 v[50:53], v[172:175], v[188:191], v[50:53]
	v_mfma_f32_16x16x32_bf16 v[42:45], v[180:183], v[188:191], v[42:45]
	v_mfma_f32_16x16x32_bf16 v[34:37], v[172:175], v[196:199], v[34:37]
	v_mfma_f32_16x16x32_bf16 v[26:29], v[180:183], v[196:199], v[26:29]
	v_mfma_f32_16x16x32_bf16 v[18:21], v[172:175], v[204:207], v[18:21]
	v_mfma_f32_16x16x32_bf16 v[10:13], v[180:183], v[204:207], v[10:13]
	v_mfma_f32_16x16x32_bf16 v[6:9], v[172:175], v[212:215], v[6:9]
	v_mfma_f32_16x16x32_bf16 v[2:5], v[180:183], v[212:215], v[2:5]
	v_mfma_f32_16x16x32_bf16 v[50:53], v[176:179], v[192:195], v[50:53]
	v_mfma_f32_16x16x32_bf16 v[42:45], v[184:187], v[192:195], v[42:45]
	v_mfma_f32_16x16x32_bf16 v[34:37], v[176:179], v[200:203], v[34:37]
	v_mfma_f32_16x16x32_bf16 v[26:29], v[184:187], v[200:203], v[26:29]
	v_mfma_f32_16x16x32_bf16 v[18:21], v[176:179], v[208:211], v[18:21]
	v_mfma_f32_16x16x32_bf16 v[10:13], v[184:187], v[208:211], v[10:13]
	v_mfma_f32_16x16x32_bf16 v[6:9], v[176:179], v[216:219], v[6:9]
	v_mfma_f32_16x16x32_bf16 v[2:5], v[184:187], v[216:219], v[2:5]
	s_setprio 0
	s_barrier
	s_add_i32 s58, 0, 0x18000
	v_add_u32_e32 v153, s58, v148
	s_add_i32 s59, 0, 0x1c000
	ds_read_b128 v[154:157], v153
	ds_read_b128 v[158:161], v153 offset:1024
	ds_read_b128 v[164:167], v153 offset:2048
	ds_read_b128 v[168:171], v153 offset:3072
	v_add_u32_e32 v153, s59, v148
	ds_read_b128 v[172:175], v153
	ds_read_b128 v[176:179], v153 offset:1024
	ds_read_b128 v[180:183], v153 offset:2048
	ds_read_b128 v[184:187], v153 offset:3072
	s_add_u32 s36, s36, 0x100000
	s_addc_u32 s37, s37, 0
	s_mov_b32 m0, s40
	ds_read_b128 v[188:191], v152 offset:32768
	ds_read_b128 v[192:195], v152 offset:33792
	ds_read_b128 v[196:199], v152 offset:34816
	ds_read_b128 v[200:203], v152 offset:35840
	ds_read_b128 v[204:207], v152 offset:36864
	ds_read_b128 v[208:211], v152 offset:37888
	ds_read_b128 v[212:215], v152 offset:38912
	ds_read_b128 v[216:219], v152 offset:39936
	s_mov_b32 m0, s29
	s_nop 0
	global_load_lds_dwordx4 v[222:223], off
	s_mov_b32 m0, s39
	s_nop 0
	global_load_lds_dwordx4 v[224:225], off
	s_mov_b32 m0, s40
	s_nop 0
	global_load_lds_dwordx4 v130, s[36:37]
	s_mov_b32 m0, s41
	s_nop 0
	global_load_lds_dwordx4 v134, s[36:37]
	s_waitcnt vmcnt(8)
	s_waitcnt lgkmcnt(0)
	s_setprio 1
	s_barrier
	v_mfma_f32_16x16x32_bf16 v[126:129], v[154:157], v[188:191], v[126:129]
	v_mfma_f32_16x16x32_bf16 v[122:125], v[164:167], v[188:191], v[122:125]
	v_mfma_f32_16x16x32_bf16 v[118:121], v[154:157], v[196:199], v[118:121]
	v_mfma_f32_16x16x32_bf16 v[110:113], v[164:167], v[196:199], v[110:113]
	v_mfma_f32_16x16x32_bf16 v[102:105], v[154:157], v[204:207], v[102:105]
	v_mfma_f32_16x16x32_bf16 v[94:97], v[164:167], v[204:207], v[94:97]
	v_mfma_f32_16x16x32_bf16 v[82:85], v[154:157], v[212:215], v[82:85]
	v_mfma_f32_16x16x32_bf16 v[74:77], v[164:167], v[212:215], v[74:77]
	v_mfma_f32_16x16x32_bf16 v[126:129], v[158:161], v[192:195], v[126:129]
	v_mfma_f32_16x16x32_bf16 v[122:125], v[168:171], v[192:195], v[122:125]
	v_mfma_f32_16x16x32_bf16 v[118:121], v[158:161], v[200:203], v[118:121]
	v_mfma_f32_16x16x32_bf16 v[110:113], v[168:171], v[200:203], v[110:113]
	v_mfma_f32_16x16x32_bf16 v[102:105], v[158:161], v[208:211], v[102:105]
	v_mfma_f32_16x16x32_bf16 v[94:97], v[168:171], v[208:211], v[94:97]
	v_mfma_f32_16x16x32_bf16 v[82:85], v[158:161], v[216:219], v[82:85]
	v_mfma_f32_16x16x32_bf16 v[74:77], v[168:171], v[216:219], v[74:77]
	v_mfma_f32_16x16x32_bf16 v[114:117], v[172:175], v[188:191], v[114:117]
	v_mfma_f32_16x16x32_bf16 v[106:109], v[180:183], v[188:191], v[106:109]
	v_mfma_f32_16x16x32_bf16 v[98:101], v[172:175], v[196:199], v[98:101]
	v_mfma_f32_16x16x32_bf16 v[90:93], v[180:183], v[196:199], v[90:93]
	v_mfma_f32_16x16x32_bf16 v[86:89], v[172:175], v[204:207], v[86:89]
	v_mfma_f32_16x16x32_bf16 v[78:81], v[180:183], v[204:207], v[78:81]
	v_mfma_f32_16x16x32_bf16 v[70:73], v[172:175], v[212:215], v[70:73]
	v_mfma_f32_16x16x32_bf16 v[66:69], v[180:183], v[212:215], v[66:69]
	v_mfma_f32_16x16x32_bf16 v[114:117], v[176:179], v[192:195], v[114:117]
	v_mfma_f32_16x16x32_bf16 v[106:109], v[184:187], v[192:195], v[106:109]
	v_mfma_f32_16x16x32_bf16 v[98:101], v[176:179], v[200:203], v[98:101]
	v_mfma_f32_16x16x32_bf16 v[90:93], v[184:187], v[200:203], v[90:93]
	v_mfma_f32_16x16x32_bf16 v[86:89], v[176:179], v[208:211], v[86:89]
	v_mfma_f32_16x16x32_bf16 v[78:81], v[184:187], v[208:211], v[78:81]
	v_mfma_f32_16x16x32_bf16 v[70:73], v[176:179], v[216:219], v[70:73]
	v_mfma_f32_16x16x32_bf16 v[66:69], v[184:187], v[216:219], v[66:69]
	s_setprio 0
	s_barrier
	s_add_i32 s36, s58, s38
	v_lshl_add_u64 v[146:147], v[146:147], 0, s[10:11]
	s_mov_b32 m0, s36
	ds_read_b128 v[188:191], v152 offset:49152
	ds_read_b128 v[192:195], v152 offset:50176
	ds_read_b128 v[196:199], v152 offset:51200
	ds_read_b128 v[200:203], v152 offset:52224
	ds_read_b128 v[204:207], v152 offset:53248
	ds_read_b128 v[208:211], v152 offset:54272
	ds_read_b128 v[212:215], v152 offset:55296
	ds_read_b128 v[216:219], v152 offset:56320
	global_load_lds_dwordx4 v[146:147], off
	s_add_i32 m0, s36, 0x2000
	s_add_u32 s34, s34, 0x100080
	v_lshl_add_u64 v[146:147], v[220:221], 0, s[10:11]
	s_addc_u32 s35, s35, 0
	s_add_i32 s36, s59, s38
	global_load_lds_dwordx4 v[146:147], off
	s_mov_b32 m0, s36
	s_nop 0
	global_load_lds_dwordx4 v132, s[34:35]
	s_add_i32 m0, s36, 0x2000
	s_nop 0
	global_load_lds_dwordx4 v136, s[34:35]
	v_lshl_add_u64 v[222:223], v[222:223], 0, s[10:11]
	v_lshl_add_u64 v[224:225], v[224:225], 0, s[10:11]
	s_waitcnt vmcnt(6)
	s_waitcnt lgkmcnt(0)
	s_setprio 1
	s_barrier
	v_mfma_f32_16x16x32_bf16 v[62:65], v[154:157], v[188:191], v[62:65]
	v_mfma_f32_16x16x32_bf16 v[58:61], v[164:167], v[188:191], v[58:61]
	v_mfma_f32_16x16x32_bf16 v[54:57], v[154:157], v[196:199], v[54:57]
	v_mfma_f32_16x16x32_bf16 v[46:49], v[164:167], v[196:199], v[46:49]
	v_mfma_f32_16x16x32_bf16 v[38:41], v[154:157], v[204:207], v[38:41]
	v_mfma_f32_16x16x32_bf16 v[30:33], v[164:167], v[204:207], v[30:33]
	v_mfma_f32_16x16x32_bf16 v[22:25], v[154:157], v[212:215], v[22:25]
	v_mfma_f32_16x16x32_bf16 v[14:17], v[164:167], v[212:215], v[14:17]
	v_mfma_f32_16x16x32_bf16 v[62:65], v[158:161], v[192:195], v[62:65]
	v_mfma_f32_16x16x32_bf16 v[58:61], v[168:171], v[192:195], v[58:61]
	v_mfma_f32_16x16x32_bf16 v[54:57], v[158:161], v[200:203], v[54:57]
	v_mfma_f32_16x16x32_bf16 v[46:49], v[168:171], v[200:203], v[46:49]
	v_mfma_f32_16x16x32_bf16 v[38:41], v[158:161], v[208:211], v[38:41]
	v_mfma_f32_16x16x32_bf16 v[30:33], v[168:171], v[208:211], v[30:33]
	v_mfma_f32_16x16x32_bf16 v[22:25], v[158:161], v[216:219], v[22:25]
	v_mfma_f32_16x16x32_bf16 v[14:17], v[168:171], v[216:219], v[14:17]
	v_mfma_f32_16x16x32_bf16 v[50:53], v[172:175], v[188:191], v[50:53]
	v_mfma_f32_16x16x32_bf16 v[42:45], v[180:183], v[188:191], v[42:45]
	v_mfma_f32_16x16x32_bf16 v[34:37], v[172:175], v[196:199], v[34:37]
	v_mfma_f32_16x16x32_bf16 v[26:29], v[180:183], v[196:199], v[26:29]
	v_mfma_f32_16x16x32_bf16 v[18:21], v[172:175], v[204:207], v[18:21]
	v_mfma_f32_16x16x32_bf16 v[10:13], v[180:183], v[204:207], v[10:13]
	v_mfma_f32_16x16x32_bf16 v[6:9], v[172:175], v[212:215], v[6:9]
	v_mfma_f32_16x16x32_bf16 v[2:5], v[180:183], v[212:215], v[2:5]
	v_mfma_f32_16x16x32_bf16 v[50:53], v[176:179], v[192:195], v[50:53]
	v_mfma_f32_16x16x32_bf16 v[42:45], v[184:187], v[192:195], v[42:45]
	v_mfma_f32_16x16x32_bf16 v[34:37], v[176:179], v[200:203], v[34:37]
	v_mfma_f32_16x16x32_bf16 v[26:29], v[184:187], v[200:203], v[26:29]
	v_mfma_f32_16x16x32_bf16 v[18:21], v[176:179], v[208:211], v[18:21]
	v_mfma_f32_16x16x32_bf16 v[10:13], v[184:187], v[208:211], v[10:13]
	v_mfma_f32_16x16x32_bf16 v[6:9], v[176:179], v[216:219], v[6:9]
	v_mfma_f32_16x16x32_bf16 v[2:5], v[184:187], v[216:219], v[2:5]
	s_setprio 0
	s_barrier
	s_add_i32 s57, s57, 2
	s_mov_b32 s32, 1
	s_add_u32 s30, s30, 0x100
	s_addc_u32 s31, s31, 0
	s_add_u32 s55, s55, 0x100
	s_addc_u32 s56, s56, 0
	s_cmp_gt_u32 s57, 61
	s_cbranch_scc0 .LBB0_1571
	s_and_b64 vcc, exec, s[12:13]
	s_cbranch_vccz .LBB0_1574
	s_barrier

.LBB0_1695:
	ds_read_b128 v[146:149], v154
	ds_read_b128 v[158:161], v154 offset:1024
	ds_read_b128 v[164:167], v154 offset:2048
	ds_read_b128 v[168:171], v154 offset:3072
	ds_read_b128 v[172:175], v155
	ds_read_b128 v[176:179], v155 offset:1024
	ds_read_b128 v[180:183], v155 offset:2048
	ds_read_b128 v[184:187], v155 offset:3072
	s_add_u32 s26, s24, 0xfff00080
	s_addc_u32 s27, s25, -1
	s_cmp_eq_u32 s49, 60
	s_cselect_b32 s29, s7, s27
	s_cselect_b32 s28, s17, s26
	s_cselect_b32 s27, s15, s48
	s_cselect_b32 s26, s46, s47
	s_add_i32 m0, s23, 0xc000
	ds_read_b128 v[188:191], v156
	ds_read_b128 v[192:195], v156 offset:1024
	ds_read_b128 v[196:199], v156 offset:2048
	ds_read_b128 v[200:203], v156 offset:3072
	ds_read_b128 v[204:207], v156 offset:4096
	ds_read_b128 v[208:211], v156 offset:5120
	ds_read_b128 v[212:215], v156 offset:6144
	ds_read_b128 v[216:219], v156 offset:7168
	s_cmp_lg_u32 s32, 0
	s_cbranch_scc0 .Lrebal_skip_1695
	s_mov_b32 m0, s38
	s_nop 0
	global_load_lds_dwordx4 v[224:225], off
	s_mov_b32 m0, s39
	s_nop 0
	global_load_lds_dwordx4 v[226:227], off
.Lrebal_skip_1695:
	s_add_i32 m0, s23, 0xc000
	s_nop 0
	global_load_lds_dwordx4 v138, s[24:25]
	s_add_i32 m0, s23, 0xe000
	s_nop 0
	global_load_lds_dwordx4 v140, s[24:25]
	s_waitcnt vmcnt(8)
	s_waitcnt lgkmcnt(0)
	s_setprio 1
	s_barrier
	v_mfma_f32_16x16x32_bf16 v[126:129], v[146:149], v[188:191], v[126:129]
	v_mfma_f32_16x16x32_bf16 v[122:125], v[164:167], v[188:191], v[122:125]
	v_mfma_f32_16x16x32_bf16 v[110:113], v[146:149], v[196:199], v[110:113]
	v_mfma_f32_16x16x32_bf16 v[106:109], v[164:167], v[196:199], v[106:109]
	v_mfma_f32_16x16x32_bf16 v[94:97], v[146:149], v[204:207], v[94:97]
	v_mfma_f32_16x16x32_bf16 v[90:93], v[164:167], v[204:207], v[90:93]
	v_mfma_f32_16x16x32_bf16 v[78:81], v[146:149], v[212:215], v[78:81]
	v_mfma_f32_16x16x32_bf16 v[74:77], v[164:167], v[212:215], v[74:77]
	v_mfma_f32_16x16x32_bf16 v[126:129], v[158:161], v[192:195], v[126:129]
	v_mfma_f32_16x16x32_bf16 v[122:125], v[168:171], v[192:195], v[122:125]
	v_mfma_f32_16x16x32_bf16 v[110:113], v[158:161], v[200:203], v[110:113]
	v_mfma_f32_16x16x32_bf16 v[106:109], v[168:171], v[200:203], v[106:109]
	v_mfma_f32_16x16x32_bf16 v[94:97], v[158:161], v[208:211], v[94:97]
	v_mfma_f32_16x16x32_bf16 v[90:93], v[168:171], v[208:211], v[90:93]
	v_mfma_f32_16x16x32_bf16 v[78:81], v[158:161], v[216:219], v[78:81]
	v_mfma_f32_16x16x32_bf16 v[74:77], v[168:171], v[216:219], v[74:77]
	v_mfma_f32_16x16x32_bf16 v[118:121], v[172:175], v[188:191], v[118:121]
	v_mfma_f32_16x16x32_bf16 v[114:117], v[180:183], v[188:191], v[114:117]
	v_mfma_f32_16x16x32_bf16 v[102:105], v[172:175], v[196:199], v[102:105]
	v_mfma_f32_16x16x32_bf16 v[98:101], v[180:183], v[196:199], v[98:101]
	v_mfma_f32_16x16x32_bf16 v[86:89], v[172:175], v[204:207], v[86:89]
	v_mfma_f32_16x16x32_bf16 v[82:85], v[180:183], v[204:207], v[82:85]
	v_mfma_f32_16x16x32_bf16 v[70:73], v[172:175], v[212:215], v[70:73]
	v_mfma_f32_16x16x32_bf16 v[66:69], v[180:183], v[212:215], v[66:69]
	v_mfma_f32_16x16x32_bf16 v[118:121], v[176:179], v[192:195], v[118:121]
	v_mfma_f32_16x16x32_bf16 v[114:117], v[184:187], v[192:195], v[114:117]
	v_mfma_f32_16x16x32_bf16 v[102:105], v[176:179], v[200:203], v[102:105]
	v_mfma_f32_16x16x32_bf16 v[98:101], v[184:187], v[200:203], v[98:101]
	v_mfma_f32_16x16x32_bf16 v[86:89], v[176:179], v[208:211], v[86:89]
	v_mfma_f32_16x16x32_bf16 v[82:85], v[184:187], v[208:211], v[82:85]
	v_mfma_f32_16x16x32_bf16 v[70:73], v[176:179], v[216:219], v[70:73]
	v_mfma_f32_16x16x32_bf16 v[66:69], v[184:187], v[216:219], v[66:69]
	s_setprio 0
	s_barrier
	s_add_i32 s50, s43, s33
	v_lshl_add_u64 v[220:221], s[26:27], 0, v[132:133]
	s_mov_b32 m0, s50
	ds_read_b128 v[188:191], v156 offset:16384
	ds_read_b128 v[192:195], v156 offset:17408
	ds_read_b128 v[196:199], v156 offset:18432
	ds_read_b128 v[200:203], v156 offset:19456
	ds_read_b128 v[204:207], v156 offset:20480
	ds_read_b128 v[208:211], v156 offset:21504
	ds_read_b128 v[212:215], v156 offset:22528
	ds_read_b128 v[216:219], v156 offset:23552
	global_load_lds_dwordx4 v132, s[26:27]
	s_add_i32 m0, s50, 0x2000
	s_add_u32 s50, s26, 0x100000
	v_lshl_add_u64 v[222:223], s[26:27], 0, v[136:137]
	s_addc_u32 s51, s27, 0
	s_add_i32 s52, s44, s33
	global_load_lds_dwordx4 v136, s[26:27]
	s_mov_b32 m0, s52
	v_lshl_add_u64 v[226:227], s[28:29], 0, v[134:135]
	global_load_lds_dwordx4 v132, s[50:51]
	s_add_i32 m0, s52, 0x2000
	s_nop 0
	global_load_lds_dwordx4 v136, s[50:51]
	v_lshl_add_u64 v[224:225], s[28:29], 0, v[130:131]
	s_waitcnt vmcnt(6)
	s_waitcnt lgkmcnt(0)
	s_setprio 1
	s_barrier
	v_mfma_f32_16x16x32_bf16 v[62:65], v[146:149], v[188:191], v[62:65]
	v_mfma_f32_16x16x32_bf16 v[58:61], v[164:167], v[188:191], v[58:61]
	v_mfma_f32_16x16x32_bf16 v[46:49], v[146:149], v[196:199], v[46:49]
	v_mfma_f32_16x16x32_bf16 v[42:45], v[164:167], v[196:199], v[42:45]
	v_mfma_f32_16x16x32_bf16 v[30:33], v[146:149], v[204:207], v[30:33]
	v_mfma_f32_16x16x32_bf16 v[26:29], v[164:167], v[204:207], v[26:29]
	v_mfma_f32_16x16x32_bf16 v[14:17], v[146:149], v[212:215], v[14:17]
	v_mfma_f32_16x16x32_bf16 v[10:13], v[164:167], v[212:215], v[10:13]
	v_mfma_f32_16x16x32_bf16 v[62:65], v[158:161], v[192:195], v[62:65]
	v_mfma_f32_16x16x32_bf16 v[58:61], v[168:171], v[192:195], v[58:61]
	v_mfma_f32_16x16x32_bf16 v[46:49], v[158:161], v[200:203], v[46:49]
	v_mfma_f32_16x16x32_bf16 v[42:45], v[168:171], v[200:203], v[42:45]
	v_mfma_f32_16x16x32_bf16 v[30:33], v[158:161], v[208:211], v[30:33]
	v_mfma_f32_16x16x32_bf16 v[26:29], v[168:171], v[208:211], v[26:29]
	v_mfma_f32_16x16x32_bf16 v[14:17], v[158:161], v[216:219], v[14:17]
	v_mfma_f32_16x16x32_bf16 v[10:13], v[168:171], v[216:219], v[10:13]
	v_mfma_f32_16x16x32_bf16 v[54:57], v[172:175], v[188:191], v[54:57]
	v_mfma_f32_16x16x32_bf16 v[50:53], v[180:183], v[188:191], v[50:53]
	v_mfma_f32_16x16x32_bf16 v[38:41], v[172:175], v[196:199], v[38:41]
	v_mfma_f32_16x16x32_bf16 v[34:37], v[180:183], v[196:199], v[34:37]
	v_mfma_f32_16x16x32_bf16 v[22:25], v[172:175], v[204:207], v[22:25]
	v_mfma_f32_16x16x32_bf16 v[18:21], v[180:183], v[204:207], v[18:21]
	v_mfma_f32_16x16x32_bf16 v[6:9], v[172:175], v[212:215], v[6:9]
	v_mfma_f32_16x16x32_bf16 v[2:5], v[180:183], v[212:215], v[2:5]
	v_mfma_f32_16x16x32_bf16 v[54:57], v[176:179], v[192:195], v[54:57]
	v_mfma_f32_16x16x32_bf16 v[50:53], v[184:187], v[192:195], v[50:53]
	v_mfma_f32_16x16x32_bf16 v[38:41], v[176:179], v[200:203], v[38:41]
	v_mfma_f32_16x16x32_bf16 v[34:37], v[184:187], v[200:203], v[34:37]
	v_mfma_f32_16x16x32_bf16 v[22:25], v[176:179], v[208:211], v[22:25]
	v_mfma_f32_16x16x32_bf16 v[18:21], v[184:187], v[208:211], v[18:21]
	v_mfma_f32_16x16x32_bf16 v[6:9], v[176:179], v[216:219], v[6:9]
	v_mfma_f32_16x16x32_bf16 v[2:5], v[184:187], v[216:219], v[2:5]
	s_setprio 0
	s_barrier
	s_add_i32 s50, 0, 0x18000
	v_add_u32_e32 v150, s50, v151
	s_add_i32 s51, 0, 0x1c000
	ds_read_b128 v[146:149], v150
	ds_read_b128 v[158:161], v150 offset:1024
	ds_read_b128 v[164:167], v150 offset:2048
	ds_read_b128 v[168:171], v150 offset:3072
	v_add_u32_e32 v150, s51, v151
	ds_read_b128 v[172:175], v150
	ds_read_b128 v[176:179], v150 offset:1024
	ds_read_b128 v[180:183], v150 offset:2048
	ds_read_b128 v[184:187], v150 offset:3072
	s_add_u32 s28, s28, 0x100000
	s_addc_u32 s29, s29, 0
	s_mov_b32 m0, s35
	ds_read_b128 v[188:191], v156 offset:32768
	ds_read_b128 v[192:195], v156 offset:33792
	ds_read_b128 v[196:199], v156 offset:34816
	ds_read_b128 v[200:203], v156 offset:35840
	ds_read_b128 v[204:207], v156 offset:36864
	ds_read_b128 v[208:211], v156 offset:37888
	ds_read_b128 v[212:215], v156 offset:38912
	ds_read_b128 v[216:219], v156 offset:39936
	s_mov_b32 m0, s23
	s_nop 0
	global_load_lds_dwordx4 v[224:225], off
	s_mov_b32 m0, s34
	s_nop 0
	global_load_lds_dwordx4 v[226:227], off
	s_mov_b32 m0, s35
	s_nop 0
	global_load_lds_dwordx4 v130, s[28:29]
	s_mov_b32 m0, s36
	s_nop 0
	global_load_lds_dwordx4 v134, s[28:29]
	s_waitcnt vmcnt(8)
	s_waitcnt lgkmcnt(0)
	s_setprio 1
	s_barrier
	v_mfma_f32_16x16x32_bf16 v[126:129], v[146:149], v[188:191], v[126:129]
	v_mfma_f32_16x16x32_bf16 v[122:125], v[164:167], v[188:191], v[122:125]
	v_mfma_f32_16x16x32_bf16 v[110:113], v[146:149], v[196:199], v[110:113]
	v_mfma_f32_16x16x32_bf16 v[106:109], v[164:167], v[196:199], v[106:109]
	v_mfma_f32_16x16x32_bf16 v[94:97], v[146:149], v[204:207], v[94:97]
	v_mfma_f32_16x16x32_bf16 v[90:93], v[164:167], v[204:207], v[90:93]
	v_mfma_f32_16x16x32_bf16 v[78:81], v[146:149], v[212:215], v[78:81]
	v_mfma_f32_16x16x32_bf16 v[74:77], v[164:167], v[212:215], v[74:77]
	v_mfma_f32_16x16x32_bf16 v[126:129], v[158:161], v[192:195], v[126:129]
	v_mfma_f32_16x16x32_bf16 v[122:125], v[168:171], v[192:195], v[122:125]
	v_mfma_f32_16x16x32_bf16 v[110:113], v[158:161], v[200:203], v[110:113]
	v_mfma_f32_16x16x32_bf16 v[106:109], v[168:171], v[200:203], v[106:109]
	v_mfma_f32_16x16x32_bf16 v[94:97], v[158:161], v[208:211], v[94:97]
	v_mfma_f32_16x16x32_bf16 v[90:93], v[168:171], v[208:211], v[90:93]
	v_mfma_f32_16x16x32_bf16 v[78:81], v[158:161], v[216:219], v[78:81]
	v_mfma_f32_16x16x32_bf16 v[74:77], v[168:171], v[216:219], v[74:77]
	v_mfma_f32_16x16x32_bf16 v[118:121], v[172:175], v[188:191], v[118:121]
	v_mfma_f32_16x16x32_bf16 v[114:117], v[180:183], v[188:191], v[114:117]
	v_mfma_f32_16x16x32_bf16 v[102:105], v[172:175], v[196:199], v[102:105]
	v_mfma_f32_16x16x32_bf16 v[98:101], v[180:183], v[196:199], v[98:101]
	v_mfma_f32_16x16x32_bf16 v[86:89], v[172:175], v[204:207], v[86:89]
	v_mfma_f32_16x16x32_bf16 v[82:85], v[180:183], v[204:207], v[82:85]
	v_mfma_f32_16x16x32_bf16 v[70:73], v[172:175], v[212:215], v[70:73]
	v_mfma_f32_16x16x32_bf16 v[66:69], v[180:183], v[212:215], v[66:69]
	v_mfma_f32_16x16x32_bf16 v[118:121], v[176:179], v[192:195], v[118:121]
	v_mfma_f32_16x16x32_bf16 v[114:117], v[184:187], v[192:195], v[114:117]
	v_mfma_f32_16x16x32_bf16 v[102:105], v[176:179], v[200:203], v[102:105]
	v_mfma_f32_16x16x32_bf16 v[98:101], v[184:187], v[200:203], v[98:101]
	v_mfma_f32_16x16x32_bf16 v[86:89], v[176:179], v[208:211], v[86:89]
	v_mfma_f32_16x16x32_bf16 v[82:85], v[184:187], v[208:211], v[82:85]
	v_mfma_f32_16x16x32_bf16 v[70:73], v[176:179], v[216:219], v[70:73]
	v_mfma_f32_16x16x32_bf16 v[66:69], v[184:187], v[216:219], v[66:69]
	s_setprio 0
	s_barrier
	s_add_i32 s28, s50, s33
	v_lshl_add_u64 v[220:221], v[220:221], 0, s[8:9]
	s_mov_b32 m0, s28
	ds_read_b128 v[188:191], v156 offset:49152
	ds_read_b128 v[192:195], v156 offset:50176
	ds_read_b128 v[196:199], v156 offset:51200
	ds_read_b128 v[200:203], v156 offset:52224
	ds_read_b128 v[204:207], v156 offset:53248
	ds_read_b128 v[208:211], v156 offset:54272
	ds_read_b128 v[212:215], v156 offset:55296
	ds_read_b128 v[216:219], v156 offset:56320
	global_load_lds_dwordx4 v[220:221], off
	s_add_i32 m0, s28, 0x2000
	s_add_u32 s26, s26, 0x100080
	v_lshl_add_u64 v[220:221], v[222:223], 0, s[8:9]
	s_addc_u32 s27, s27, 0
	s_add_i32 s28, s51, s33
	global_load_lds_dwordx4 v[220:221], off
	s_mov_b32 m0, s28
	s_nop 0
	global_load_lds_dwordx4 v132, s[26:27]
	s_add_i32 m0, s28, 0x2000
	s_nop 0
	global_load_lds_dwordx4 v136, s[26:27]
	v_lshl_add_u64 v[224:225], v[224:225], 0, s[8:9]
	v_lshl_add_u64 v[226:227], v[226:227], 0, s[8:9]
	s_waitcnt vmcnt(6)
	s_waitcnt lgkmcnt(0)
	s_setprio 1
	s_barrier
	v_mfma_f32_16x16x32_bf16 v[62:65], v[146:149], v[188:191], v[62:65]
	v_mfma_f32_16x16x32_bf16 v[58:61], v[164:167], v[188:191], v[58:61]
	v_mfma_f32_16x16x32_bf16 v[46:49], v[146:149], v[196:199], v[46:49]
	v_mfma_f32_16x16x32_bf16 v[42:45], v[164:167], v[196:199], v[42:45]
	v_mfma_f32_16x16x32_bf16 v[30:33], v[146:149], v[204:207], v[30:33]
	v_mfma_f32_16x16x32_bf16 v[26:29], v[164:167], v[204:207], v[26:29]
	v_mfma_f32_16x16x32_bf16 v[14:17], v[146:149], v[212:215], v[14:17]
	v_mfma_f32_16x16x32_bf16 v[10:13], v[164:167], v[212:215], v[10:13]
	v_mfma_f32_16x16x32_bf16 v[62:65], v[158:161], v[192:195], v[62:65]
	v_mfma_f32_16x16x32_bf16 v[58:61], v[168:171], v[192:195], v[58:61]
	v_mfma_f32_16x16x32_bf16 v[46:49], v[158:161], v[200:203], v[46:49]
	v_mfma_f32_16x16x32_bf16 v[42:45], v[168:171], v[200:203], v[42:45]
	v_mfma_f32_16x16x32_bf16 v[30:33], v[158:161], v[208:211], v[30:33]
	v_mfma_f32_16x16x32_bf16 v[26:29], v[168:171], v[208:211], v[26:29]
	v_mfma_f32_16x16x32_bf16 v[14:17], v[158:161], v[216:219], v[14:17]
	v_mfma_f32_16x16x32_bf16 v[10:13], v[168:171], v[216:219], v[10:13]
	v_mfma_f32_16x16x32_bf16 v[54:57], v[172:175], v[188:191], v[54:57]
	v_mfma_f32_16x16x32_bf16 v[50:53], v[180:183], v[188:191], v[50:53]
	v_mfma_f32_16x16x32_bf16 v[38:41], v[172:175], v[196:199], v[38:41]
	v_mfma_f32_16x16x32_bf16 v[34:37], v[180:183], v[196:199], v[34:37]
	v_mfma_f32_16x16x32_bf16 v[22:25], v[172:175], v[204:207], v[22:25]
	v_mfma_f32_16x16x32_bf16 v[18:21], v[180:183], v[204:207], v[18:21]
	v_mfma_f32_16x16x32_bf16 v[6:9], v[172:175], v[212:215], v[6:9]
	v_mfma_f32_16x16x32_bf16 v[2:5], v[180:183], v[212:215], v[2:5]
	v_mfma_f32_16x16x32_bf16 v[54:57], v[176:179], v[192:195], v[54:57]
	v_mfma_f32_16x16x32_bf16 v[50:53], v[184:187], v[192:195], v[50:53]
	v_mfma_f32_16x16x32_bf16 v[38:41], v[176:179], v[200:203], v[38:41]
	v_mfma_f32_16x16x32_bf16 v[34:37], v[184:187], v[200:203], v[34:37]
	v_mfma_f32_16x16x32_bf16 v[22:25], v[176:179], v[208:211], v[22:25]
	v_mfma_f32_16x16x32_bf16 v[18:21], v[184:187], v[208:211], v[18:21]
	v_mfma_f32_16x16x32_bf16 v[6:9], v[176:179], v[216:219], v[6:9]
	v_mfma_f32_16x16x32_bf16 v[2:5], v[184:187], v[216:219], v[2:5]
	s_setprio 0
	s_barrier
	s_add_i32 s49, s49, 2
	s_mov_b32 s32, 1
	s_add_u32 s24, s24, 0x100
	s_addc_u32 s25, s25, 0
	s_add_u32 s47, s47, 0x100
	s_addc_u32 s48, s48, 0
	s_cmp_gt_u32 s49, 61
	s_cbranch_scc0 .LBB0_1695
	s_and_b64 vcc, exec, s[10:11]
	s_cbranch_vccz .LBB0_1698
	s_barrier

.LBB0_1853:
	ds_read_b128 v[154:157], v150
	ds_read_b128 v[158:161], v150 offset:1024
	ds_read_b128 v[164:167], v150 offset:2048
	ds_read_b128 v[168:171], v150 offset:3072
	ds_read_b128 v[172:175], v151
	ds_read_b128 v[176:179], v151 offset:1024
	ds_read_b128 v[180:183], v151 offset:2048
	ds_read_b128 v[184:187], v151 offset:3072
	s_add_u32 s24, s22, 0xffd50080
	s_addc_u32 s25, s23, -1
	s_cmpk_eq_i32 s53, 0xa8
	s_cselect_b32 s27, s1, s25
	s_cselect_b32 s26, s0, s24
	s_cselect_b32 s25, s21, s52
	s_cselect_b32 s24, s20, s51
	s_add_i32 m0, s33, 0xc000
	ds_read_b128 v[188:191], v152
	ds_read_b128 v[192:195], v152 offset:1024
	ds_read_b128 v[196:199], v152 offset:2048
	ds_read_b128 v[200:203], v152 offset:3072
	ds_read_b128 v[204:207], v152 offset:4096
	ds_read_b128 v[208:211], v152 offset:5120
	ds_read_b128 v[212:215], v152 offset:6144
	ds_read_b128 v[216:219], v152 offset:7168
	s_cmp_lg_u32 s32, 0
	s_cbranch_scc0 .Lrebal_skip_1853
	s_mov_b32 m0, s38
	s_nop 0
	global_load_lds_dwordx4 v[222:223], off
	s_mov_b32 m0, s39
	s_nop 0
	global_load_lds_dwordx4 v[224:225], off
.Lrebal_skip_1853:
	s_add_i32 m0, s33, 0xc000
	s_nop 0
	global_load_lds_dwordx4 v138, s[22:23]
	s_add_i32 m0, s33, 0xe000
	s_nop 0
	global_load_lds_dwordx4 v140, s[22:23]
	s_waitcnt vmcnt(8)
	s_waitcnt lgkmcnt(0)
	s_setprio 1
	s_barrier
	v_mfma_f32_16x16x32_bf16 v[126:129], v[154:157], v[188:191], v[126:129]
	v_mfma_f32_16x16x32_bf16 v[122:125], v[164:167], v[188:191], v[122:125]
	v_mfma_f32_16x16x32_bf16 v[118:121], v[154:157], v[196:199], v[118:121]
	v_mfma_f32_16x16x32_bf16 v[110:113], v[164:167], v[196:199], v[110:113]
	v_mfma_f32_16x16x32_bf16 v[102:105], v[154:157], v[204:207], v[102:105]
	v_mfma_f32_16x16x32_bf16 v[94:97], v[164:167], v[204:207], v[94:97]
	v_mfma_f32_16x16x32_bf16 v[82:85], v[154:157], v[212:215], v[82:85]
	v_mfma_f32_16x16x32_bf16 v[74:77], v[164:167], v[212:215], v[74:77]
	v_mfma_f32_16x16x32_bf16 v[126:129], v[158:161], v[192:195], v[126:129]
	v_mfma_f32_16x16x32_bf16 v[122:125], v[168:171], v[192:195], v[122:125]
	v_mfma_f32_16x16x32_bf16 v[118:121], v[158:161], v[200:203], v[118:121]
	v_mfma_f32_16x16x32_bf16 v[110:113], v[168:171], v[200:203], v[110:113]
	v_mfma_f32_16x16x32_bf16 v[102:105], v[158:161], v[208:211], v[102:105]
	v_mfma_f32_16x16x32_bf16 v[94:97], v[168:171], v[208:211], v[94:97]
	v_mfma_f32_16x16x32_bf16 v[82:85], v[158:161], v[216:219], v[82:85]
	v_mfma_f32_16x16x32_bf16 v[74:77], v[168:171], v[216:219], v[74:77]
	v_mfma_f32_16x16x32_bf16 v[114:117], v[172:175], v[188:191], v[114:117]
	v_mfma_f32_16x16x32_bf16 v[106:109], v[180:183], v[188:191], v[106:109]
	v_mfma_f32_16x16x32_bf16 v[98:101], v[172:175], v[196:199], v[98:101]
	v_mfma_f32_16x16x32_bf16 v[90:93], v[180:183], v[196:199], v[90:93]
	v_mfma_f32_16x16x32_bf16 v[86:89], v[172:175], v[204:207], v[86:89]
	v_mfma_f32_16x16x32_bf16 v[78:81], v[180:183], v[204:207], v[78:81]
	v_mfma_f32_16x16x32_bf16 v[70:73], v[172:175], v[212:215], v[70:73]
	v_mfma_f32_16x16x32_bf16 v[66:69], v[180:183], v[212:215], v[66:69]
	v_mfma_f32_16x16x32_bf16 v[114:117], v[176:179], v[192:195], v[114:117]
	v_mfma_f32_16x16x32_bf16 v[106:109], v[184:187], v[192:195], v[106:109]
	v_mfma_f32_16x16x32_bf16 v[98:101], v[176:179], v[200:203], v[98:101]
	v_mfma_f32_16x16x32_bf16 v[90:93], v[184:187], v[200:203], v[90:93]
	v_mfma_f32_16x16x32_bf16 v[86:89], v[176:179], v[208:211], v[86:89]
	v_mfma_f32_16x16x32_bf16 v[78:81], v[184:187], v[208:211], v[78:81]
	v_mfma_f32_16x16x32_bf16 v[70:73], v[176:179], v[216:219], v[70:73]
	v_mfma_f32_16x16x32_bf16 v[66:69], v[184:187], v[216:219], v[66:69]
	s_setprio 0
	s_barrier
	s_add_i32 s54, s41, s31
	v_lshl_add_u64 v[146:147], s[24:25], 0, v[132:133]
	s_mov_b32 m0, s54
	ds_read_b128 v[188:191], v152 offset:16384
	ds_read_b128 v[192:195], v152 offset:17408
	ds_read_b128 v[196:199], v152 offset:18432
	ds_read_b128 v[200:203], v152 offset:19456
	ds_read_b128 v[204:207], v152 offset:20480
	ds_read_b128 v[208:211], v152 offset:21504
	ds_read_b128 v[212:215], v152 offset:22528
	ds_read_b128 v[216:219], v152 offset:23552
	global_load_lds_dwordx4 v132, s[24:25]
	s_add_i32 m0, s54, 0x2000
	s_add_u32 s54, s24, 0x2b0000
	v_lshl_add_u64 v[220:221], s[24:25], 0, v[136:137]
	s_addc_u32 s55, s25, 0
	s_add_i32 s56, s42, s31
	global_load_lds_dwordx4 v136, s[24:25]
	s_mov_b32 m0, s56
	v_lshl_add_u64 v[224:225], s[26:27], 0, v[134:135]
	global_load_lds_dwordx4 v132, s[54:55]
	s_add_i32 m0, s56, 0x2000
	s_nop 0
	global_load_lds_dwordx4 v136, s[54:55]
	v_lshl_add_u64 v[222:223], s[26:27], 0, v[130:131]
	s_waitcnt vmcnt(6)
	s_waitcnt lgkmcnt(0)
	s_setprio 1
	s_barrier
	v_mfma_f32_16x16x32_bf16 v[62:65], v[154:157], v[188:191], v[62:65]
	v_mfma_f32_16x16x32_bf16 v[58:61], v[164:167], v[188:191], v[58:61]
	v_mfma_f32_16x16x32_bf16 v[54:57], v[154:157], v[196:199], v[54:57]
	v_mfma_f32_16x16x32_bf16 v[46:49], v[164:167], v[196:199], v[46:49]
	v_mfma_f32_16x16x32_bf16 v[38:41], v[154:157], v[204:207], v[38:41]
	v_mfma_f32_16x16x32_bf16 v[30:33], v[164:167], v[204:207], v[30:33]
	v_mfma_f32_16x16x32_bf16 v[22:25], v[154:157], v[212:215], v[22:25]
	v_mfma_f32_16x16x32_bf16 v[14:17], v[164:167], v[212:215], v[14:17]
	v_mfma_f32_16x16x32_bf16 v[62:65], v[158:161], v[192:195], v[62:65]
	v_mfma_f32_16x16x32_bf16 v[58:61], v[168:171], v[192:195], v[58:61]
	v_mfma_f32_16x16x32_bf16 v[54:57], v[158:161], v[200:203], v[54:57]
	v_mfma_f32_16x16x32_bf16 v[46:49], v[168:171], v[200:203], v[46:49]
	v_mfma_f32_16x16x32_bf16 v[38:41], v[158:161], v[208:211], v[38:41]
	v_mfma_f32_16x16x32_bf16 v[30:33], v[168:171], v[208:211], v[30:33]
	v_mfma_f32_16x16x32_bf16 v[22:25], v[158:161], v[216:219], v[22:25]
	v_mfma_f32_16x16x32_bf16 v[14:17], v[168:171], v[216:219], v[14:17]
	v_mfma_f32_16x16x32_bf16 v[50:53], v[172:175], v[188:191], v[50:53]
	v_mfma_f32_16x16x32_bf16 v[42:45], v[180:183], v[188:191], v[42:45]
	v_mfma_f32_16x16x32_bf16 v[34:37], v[172:175], v[196:199], v[34:37]
	v_mfma_f32_16x16x32_bf16 v[26:29], v[180:183], v[196:199], v[26:29]
	v_mfma_f32_16x16x32_bf16 v[18:21], v[172:175], v[204:207], v[18:21]
	v_mfma_f32_16x16x32_bf16 v[10:13], v[180:183], v[204:207], v[10:13]
	v_mfma_f32_16x16x32_bf16 v[6:9], v[172:175], v[212:215], v[6:9]
	v_mfma_f32_16x16x32_bf16 v[2:5], v[180:183], v[212:215], v[2:5]
	v_mfma_f32_16x16x32_bf16 v[50:53], v[176:179], v[192:195], v[50:53]
	v_mfma_f32_16x16x32_bf16 v[42:45], v[184:187], v[192:195], v[42:45]
	v_mfma_f32_16x16x32_bf16 v[34:37], v[176:179], v[200:203], v[34:37]
	v_mfma_f32_16x16x32_bf16 v[26:29], v[184:187], v[200:203], v[26:29]
	v_mfma_f32_16x16x32_bf16 v[18:21], v[176:179], v[208:211], v[18:21]
	v_mfma_f32_16x16x32_bf16 v[10:13], v[184:187], v[208:211], v[10:13]
	v_mfma_f32_16x16x32_bf16 v[6:9], v[176:179], v[216:219], v[6:9]
	v_mfma_f32_16x16x32_bf16 v[2:5], v[184:187], v[216:219], v[2:5]
	s_setprio 0
	s_barrier
	s_add_i32 s54, 0, 0x18000
	v_add_u32_e32 v153, s54, v148
	s_add_i32 s55, 0, 0x1c000
	ds_read_b128 v[154:157], v153
	ds_read_b128 v[158:161], v153 offset:1024
	ds_read_b128 v[164:167], v153 offset:2048
	ds_read_b128 v[168:171], v153 offset:3072
	v_add_u32_e32 v153, s55, v148
	ds_read_b128 v[172:175], v153
	ds_read_b128 v[176:179], v153 offset:1024
	ds_read_b128 v[180:183], v153 offset:2048
	ds_read_b128 v[184:187], v153 offset:3072
	s_add_u32 s26, s26, 0x2b0000
	s_addc_u32 s27, s27, 0
	s_mov_b32 m0, s35
	ds_read_b128 v[188:191], v152 offset:32768
	ds_read_b128 v[192:195], v152 offset:33792
	ds_read_b128 v[196:199], v152 offset:34816
	ds_read_b128 v[200:203], v152 offset:35840
	ds_read_b128 v[204:207], v152 offset:36864
	ds_read_b128 v[208:211], v152 offset:37888
	ds_read_b128 v[212:215], v152 offset:38912
	ds_read_b128 v[216:219], v152 offset:39936
	s_mov_b32 m0, s33
	s_nop 0
	global_load_lds_dwordx4 v[222:223], off
	s_mov_b32 m0, s34
	s_nop 0
	global_load_lds_dwordx4 v[224:225], off
	s_mov_b32 m0, s35
	s_nop 0
	global_load_lds_dwordx4 v130, s[26:27]
	s_mov_b32 m0, s36
	s_nop 0
	global_load_lds_dwordx4 v134, s[26:27]
	s_waitcnt vmcnt(8)
	s_waitcnt lgkmcnt(0)
	s_setprio 1
	s_barrier
	v_mfma_f32_16x16x32_bf16 v[126:129], v[154:157], v[188:191], v[126:129]
	v_mfma_f32_16x16x32_bf16 v[122:125], v[164:167], v[188:191], v[122:125]
	v_mfma_f32_16x16x32_bf16 v[118:121], v[154:157], v[196:199], v[118:121]
	v_mfma_f32_16x16x32_bf16 v[110:113], v[164:167], v[196:199], v[110:113]
	v_mfma_f32_16x16x32_bf16 v[102:105], v[154:157], v[204:207], v[102:105]
	v_mfma_f32_16x16x32_bf16 v[94:97], v[164:167], v[204:207], v[94:97]
	v_mfma_f32_16x16x32_bf16 v[82:85], v[154:157], v[212:215], v[82:85]
	v_mfma_f32_16x16x32_bf16 v[74:77], v[164:167], v[212:215], v[74:77]
	v_mfma_f32_16x16x32_bf16 v[126:129], v[158:161], v[192:195], v[126:129]
	v_mfma_f32_16x16x32_bf16 v[122:125], v[168:171], v[192:195], v[122:125]
	v_mfma_f32_16x16x32_bf16 v[118:121], v[158:161], v[200:203], v[118:121]
	v_mfma_f32_16x16x32_bf16 v[110:113], v[168:171], v[200:203], v[110:113]
	v_mfma_f32_16x16x32_bf16 v[102:105], v[158:161], v[208:211], v[102:105]
	v_mfma_f32_16x16x32_bf16 v[94:97], v[168:171], v[208:211], v[94:97]
	v_mfma_f32_16x16x32_bf16 v[82:85], v[158:161], v[216:219], v[82:85]
	v_mfma_f32_16x16x32_bf16 v[74:77], v[168:171], v[216:219], v[74:77]
	v_mfma_f32_16x16x32_bf16 v[114:117], v[172:175], v[188:191], v[114:117]
	v_mfma_f32_16x16x32_bf16 v[106:109], v[180:183], v[188:191], v[106:109]
	v_mfma_f32_16x16x32_bf16 v[98:101], v[172:175], v[196:199], v[98:101]
	v_mfma_f32_16x16x32_bf16 v[90:93], v[180:183], v[196:199], v[90:93]
	v_mfma_f32_16x16x32_bf16 v[86:89], v[172:175], v[204:207], v[86:89]
	v_mfma_f32_16x16x32_bf16 v[78:81], v[180:183], v[204:207], v[78:81]
	v_mfma_f32_16x16x32_bf16 v[70:73], v[172:175], v[212:215], v[70:73]
	v_mfma_f32_16x16x32_bf16 v[66:69], v[180:183], v[212:215], v[66:69]
	v_mfma_f32_16x16x32_bf16 v[114:117], v[176:179], v[192:195], v[114:117]
	v_mfma_f32_16x16x32_bf16 v[106:109], v[184:187], v[192:195], v[106:109]
	v_mfma_f32_16x16x32_bf16 v[98:101], v[176:179], v[200:203], v[98:101]
	v_mfma_f32_16x16x32_bf16 v[90:93], v[184:187], v[200:203], v[90:93]
	v_mfma_f32_16x16x32_bf16 v[86:89], v[176:179], v[208:211], v[86:89]
	v_mfma_f32_16x16x32_bf16 v[78:81], v[184:187], v[208:211], v[78:81]
	v_mfma_f32_16x16x32_bf16 v[70:73], v[176:179], v[216:219], v[70:73]
	v_mfma_f32_16x16x32_bf16 v[66:69], v[184:187], v[216:219], v[66:69]
	s_setprio 0
	s_barrier
	s_add_i32 s26, s54, s31
	v_lshl_add_u64 v[146:147], v[146:147], 0, s[8:9]
	s_mov_b32 m0, s26
	ds_read_b128 v[188:191], v152 offset:49152
	ds_read_b128 v[192:195], v152 offset:50176
	ds_read_b128 v[196:199], v152 offset:51200
	ds_read_b128 v[200:203], v152 offset:52224
	ds_read_b128 v[204:207], v152 offset:53248
	ds_read_b128 v[208:211], v152 offset:54272
	ds_read_b128 v[212:215], v152 offset:55296
	ds_read_b128 v[216:219], v152 offset:56320
	global_load_lds_dwordx4 v[146:147], off
	s_add_i32 m0, s26, 0x2000
	s_add_u32 s24, s24, 0x2b0080
	v_lshl_add_u64 v[146:147], v[220:221], 0, s[8:9]
	s_addc_u32 s25, s25, 0
	s_add_i32 s26, s55, s31
	global_load_lds_dwordx4 v[146:147], off
	s_mov_b32 m0, s26
	s_nop 0
	global_load_lds_dwordx4 v132, s[24:25]
	s_add_i32 m0, s26, 0x2000
	s_nop 0
	global_load_lds_dwordx4 v136, s[24:25]
	v_lshl_add_u64 v[222:223], v[222:223], 0, s[8:9]
	v_lshl_add_u64 v[224:225], v[224:225], 0, s[8:9]
	s_waitcnt vmcnt(6)
	s_waitcnt lgkmcnt(0)
	s_setprio 1
	s_barrier
	v_mfma_f32_16x16x32_bf16 v[62:65], v[154:157], v[188:191], v[62:65]
	v_mfma_f32_16x16x32_bf16 v[58:61], v[164:167], v[188:191], v[58:61]
	v_mfma_f32_16x16x32_bf16 v[54:57], v[154:157], v[196:199], v[54:57]
	v_mfma_f32_16x16x32_bf16 v[46:49], v[164:167], v[196:199], v[46:49]
	v_mfma_f32_16x16x32_bf16 v[38:41], v[154:157], v[204:207], v[38:41]
	v_mfma_f32_16x16x32_bf16 v[30:33], v[164:167], v[204:207], v[30:33]
	v_mfma_f32_16x16x32_bf16 v[22:25], v[154:157], v[212:215], v[22:25]
	v_mfma_f32_16x16x32_bf16 v[14:17], v[164:167], v[212:215], v[14:17]
	v_mfma_f32_16x16x32_bf16 v[62:65], v[158:161], v[192:195], v[62:65]
	v_mfma_f32_16x16x32_bf16 v[58:61], v[168:171], v[192:195], v[58:61]
	v_mfma_f32_16x16x32_bf16 v[54:57], v[158:161], v[200:203], v[54:57]
	v_mfma_f32_16x16x32_bf16 v[46:49], v[168:171], v[200:203], v[46:49]
	v_mfma_f32_16x16x32_bf16 v[38:41], v[158:161], v[208:211], v[38:41]
	v_mfma_f32_16x16x32_bf16 v[30:33], v[168:171], v[208:211], v[30:33]
	v_mfma_f32_16x16x32_bf16 v[22:25], v[158:161], v[216:219], v[22:25]
	v_mfma_f32_16x16x32_bf16 v[14:17], v[168:171], v[216:219], v[14:17]
	v_mfma_f32_16x16x32_bf16 v[50:53], v[172:175], v[188:191], v[50:53]
	v_mfma_f32_16x16x32_bf16 v[42:45], v[180:183], v[188:191], v[42:45]
	v_mfma_f32_16x16x32_bf16 v[34:37], v[172:175], v[196:199], v[34:37]
	v_mfma_f32_16x16x32_bf16 v[26:29], v[180:183], v[196:199], v[26:29]
	v_mfma_f32_16x16x32_bf16 v[18:21], v[172:175], v[204:207], v[18:21]
	v_mfma_f32_16x16x32_bf16 v[10:13], v[180:183], v[204:207], v[10:13]
	v_mfma_f32_16x16x32_bf16 v[6:9], v[172:175], v[212:215], v[6:9]
	v_mfma_f32_16x16x32_bf16 v[2:5], v[180:183], v[212:215], v[2:5]
	v_mfma_f32_16x16x32_bf16 v[50:53], v[176:179], v[192:195], v[50:53]
	v_mfma_f32_16x16x32_bf16 v[42:45], v[184:187], v[192:195], v[42:45]
	v_mfma_f32_16x16x32_bf16 v[34:37], v[176:179], v[200:203], v[34:37]
	v_mfma_f32_16x16x32_bf16 v[26:29], v[184:187], v[200:203], v[26:29]
	v_mfma_f32_16x16x32_bf16 v[18:21], v[176:179], v[208:211], v[18:21]
	v_mfma_f32_16x16x32_bf16 v[10:13], v[184:187], v[208:211], v[10:13]
	v_mfma_f32_16x16x32_bf16 v[6:9], v[176:179], v[216:219], v[6:9]
	v_mfma_f32_16x16x32_bf16 v[2:5], v[184:187], v[216:219], v[2:5]
	s_setprio 0
	s_barrier
	s_add_i32 s53, s53, 2
	s_mov_b32 s32, 1
	s_add_u32 s22, s22, 0x100
	s_addc_u32 s23, s23, 0
	s_add_u32 s51, s51, 0x100
	s_addc_u32 s52, s52, 0
	s_cmpk_gt_u32 s53, 0xa9
	s_cbranch_scc0 .LBB0_1853
	s_and_b64 vcc, exec, s[10:11]
	s_cbranch_vccz .LBB0_1856
	s_barrier

.LBB0_1983:
	ds_read_b128 v[146:149], v156
	ds_read_b128 v[150:153], v156 offset:1024
	ds_read_b128 v[164:167], v156 offset:2048
	ds_read_b128 v[168:171], v156 offset:3072
	ds_read_b128 v[172:175], v157
	ds_read_b128 v[176:179], v157 offset:1024
	ds_read_b128 v[180:183], v157 offset:2048
	ds_read_b128 v[184:187], v157 offset:3072
	s_add_u32 s34, s30, 0xfff00080
	s_addc_u32 s35, s31, -1
	s_cmp_eq_u32 s55, 60
	s_cselect_b32 s37, s23, s35
	s_cselect_b32 s36, s51, s34
	s_cselect_b32 s35, s21, s54
	s_cselect_b32 s34, s52, s53
	s_add_i32 m0, s29, 0xc000
	ds_read_b128 v[188:191], v158
	ds_read_b128 v[192:195], v158 offset:1024
	ds_read_b128 v[196:199], v158 offset:2048
	ds_read_b128 v[200:203], v158 offset:3072
	ds_read_b128 v[204:207], v158 offset:4096
	ds_read_b128 v[208:211], v158 offset:5120
	ds_read_b128 v[212:215], v158 offset:6144
	ds_read_b128 v[216:219], v158 offset:7168
	s_cmp_lg_u32 s32, 0
	s_cbranch_scc0 .Lrebal_skip_1983
	s_mov_b32 m0, s45
	s_nop 0
	global_load_lds_dwordx4 v[222:223], off
	s_mov_b32 m0, s46
	s_nop 0
	global_load_lds_dwordx4 v[224:225], off
.Lrebal_skip_1983:
	s_add_i32 m0, s29, 0xc000
	s_nop 0
	global_load_lds_dwordx4 v138, s[30:31]
	s_add_i32 m0, s29, 0xe000
	s_nop 0
	global_load_lds_dwordx4 v140, s[30:31]
	s_waitcnt vmcnt(8)
	s_waitcnt lgkmcnt(0)
	s_setprio 1
	s_barrier
	v_mfma_f32_16x16x32_bf16 v[126:129], v[146:149], v[188:191], v[126:129]
	v_mfma_f32_16x16x32_bf16 v[122:125], v[164:167], v[188:191], v[122:125]
	v_mfma_f32_16x16x32_bf16 v[110:113], v[146:149], v[196:199], v[110:113]
	v_mfma_f32_16x16x32_bf16 v[106:109], v[164:167], v[196:199], v[106:109]
	v_mfma_f32_16x16x32_bf16 v[94:97], v[146:149], v[204:207], v[94:97]
	v_mfma_f32_16x16x32_bf16 v[90:93], v[164:167], v[204:207], v[90:93]
	v_mfma_f32_16x16x32_bf16 v[78:81], v[146:149], v[212:215], v[78:81]
	v_mfma_f32_16x16x32_bf16 v[74:77], v[164:167], v[212:215], v[74:77]
	v_mfma_f32_16x16x32_bf16 v[126:129], v[150:153], v[192:195], v[126:129]
	v_mfma_f32_16x16x32_bf16 v[122:125], v[168:171], v[192:195], v[122:125]
	v_mfma_f32_16x16x32_bf16 v[110:113], v[150:153], v[200:203], v[110:113]
	v_mfma_f32_16x16x32_bf16 v[106:109], v[168:171], v[200:203], v[106:109]
	v_mfma_f32_16x16x32_bf16 v[94:97], v[150:153], v[208:211], v[94:97]
	v_mfma_f32_16x16x32_bf16 v[90:93], v[168:171], v[208:211], v[90:93]
	v_mfma_f32_16x16x32_bf16 v[78:81], v[150:153], v[216:219], v[78:81]
	v_mfma_f32_16x16x32_bf16 v[74:77], v[168:171], v[216:219], v[74:77]
	v_mfma_f32_16x16x32_bf16 v[118:121], v[172:175], v[188:191], v[118:121]
	v_mfma_f32_16x16x32_bf16 v[114:117], v[180:183], v[188:191], v[114:117]
	v_mfma_f32_16x16x32_bf16 v[102:105], v[172:175], v[196:199], v[102:105]
	v_mfma_f32_16x16x32_bf16 v[98:101], v[180:183], v[196:199], v[98:101]
	v_mfma_f32_16x16x32_bf16 v[86:89], v[172:175], v[204:207], v[86:89]
	v_mfma_f32_16x16x32_bf16 v[82:85], v[180:183], v[204:207], v[82:85]
	v_mfma_f32_16x16x32_bf16 v[70:73], v[172:175], v[212:215], v[70:73]
	v_mfma_f32_16x16x32_bf16 v[66:69], v[180:183], v[212:215], v[66:69]
	v_mfma_f32_16x16x32_bf16 v[118:121], v[176:179], v[192:195], v[118:121]
	v_mfma_f32_16x16x32_bf16 v[114:117], v[184:187], v[192:195], v[114:117]
	v_mfma_f32_16x16x32_bf16 v[102:105], v[176:179], v[200:203], v[102:105]
	v_mfma_f32_16x16x32_bf16 v[98:101], v[184:187], v[200:203], v[98:101]
	v_mfma_f32_16x16x32_bf16 v[86:89], v[176:179], v[208:211], v[86:89]
	v_mfma_f32_16x16x32_bf16 v[82:85], v[184:187], v[208:211], v[82:85]
	v_mfma_f32_16x16x32_bf16 v[70:73], v[176:179], v[216:219], v[70:73]
	v_mfma_f32_16x16x32_bf16 v[66:69], v[184:187], v[216:219], v[66:69]
	s_setprio 0
	s_barrier
	s_add_i32 s56, s48, s40
	v_lshl_add_u64 v[160:161], s[34:35], 0, v[132:133]
	s_mov_b32 m0, s56
	ds_read_b128 v[188:191], v158 offset:16384
	ds_read_b128 v[192:195], v158 offset:17408
	ds_read_b128 v[196:199], v158 offset:18432
	ds_read_b128 v[200:203], v158 offset:19456
	ds_read_b128 v[204:207], v158 offset:20480
	ds_read_b128 v[208:211], v158 offset:21504
	ds_read_b128 v[212:215], v158 offset:22528
	ds_read_b128 v[216:219], v158 offset:23552
	global_load_lds_dwordx4 v132, s[34:35]
	s_add_i32 m0, s56, 0x2000
	s_add_u32 s56, s34, 0x100000
	v_lshl_add_u64 v[220:221], s[34:35], 0, v[136:137]
	s_addc_u32 s57, s35, 0
	s_add_i32 s58, s49, s40
	global_load_lds_dwordx4 v136, s[34:35]
	s_mov_b32 m0, s58
	v_lshl_add_u64 v[224:225], s[36:37], 0, v[134:135]
	global_load_lds_dwordx4 v132, s[56:57]
	s_add_i32 m0, s58, 0x2000
	s_nop 0
	global_load_lds_dwordx4 v136, s[56:57]
	v_lshl_add_u64 v[222:223], s[36:37], 0, v[130:131]
	s_waitcnt vmcnt(6)
	s_waitcnt lgkmcnt(0)
	s_setprio 1
	s_barrier
	v_mfma_f32_16x16x32_bf16 v[62:65], v[146:149], v[188:191], v[62:65]
	v_mfma_f32_16x16x32_bf16 v[58:61], v[164:167], v[188:191], v[58:61]
	v_mfma_f32_16x16x32_bf16 v[46:49], v[146:149], v[196:199], v[46:49]
	v_mfma_f32_16x16x32_bf16 v[42:45], v[164:167], v[196:199], v[42:45]
	v_mfma_f32_16x16x32_bf16 v[30:33], v[146:149], v[204:207], v[30:33]
	v_mfma_f32_16x16x32_bf16 v[26:29], v[164:167], v[204:207], v[26:29]
	v_mfma_f32_16x16x32_bf16 v[14:17], v[146:149], v[212:215], v[14:17]
	v_mfma_f32_16x16x32_bf16 v[10:13], v[164:167], v[212:215], v[10:13]
	v_mfma_f32_16x16x32_bf16 v[62:65], v[150:153], v[192:195], v[62:65]
	v_mfma_f32_16x16x32_bf16 v[58:61], v[168:171], v[192:195], v[58:61]
	v_mfma_f32_16x16x32_bf16 v[46:49], v[150:153], v[200:203], v[46:49]
	v_mfma_f32_16x16x32_bf16 v[42:45], v[168:171], v[200:203], v[42:45]
	v_mfma_f32_16x16x32_bf16 v[30:33], v[150:153], v[208:211], v[30:33]
	v_mfma_f32_16x16x32_bf16 v[26:29], v[168:171], v[208:211], v[26:29]
	v_mfma_f32_16x16x32_bf16 v[14:17], v[150:153], v[216:219], v[14:17]
	v_mfma_f32_16x16x32_bf16 v[10:13], v[168:171], v[216:219], v[10:13]
	v_mfma_f32_16x16x32_bf16 v[54:57], v[172:175], v[188:191], v[54:57]
	v_mfma_f32_16x16x32_bf16 v[50:53], v[180:183], v[188:191], v[50:53]
	v_mfma_f32_16x16x32_bf16 v[38:41], v[172:175], v[196:199], v[38:41]
	v_mfma_f32_16x16x32_bf16 v[34:37], v[180:183], v[196:199], v[34:37]
	v_mfma_f32_16x16x32_bf16 v[22:25], v[172:175], v[204:207], v[22:25]
	v_mfma_f32_16x16x32_bf16 v[18:21], v[180:183], v[204:207], v[18:21]
	v_mfma_f32_16x16x32_bf16 v[6:9], v[172:175], v[212:215], v[6:9]
	v_mfma_f32_16x16x32_bf16 v[2:5], v[180:183], v[212:215], v[2:5]
	v_mfma_f32_16x16x32_bf16 v[54:57], v[176:179], v[192:195], v[54:57]
	v_mfma_f32_16x16x32_bf16 v[50:53], v[184:187], v[192:195], v[50:53]
	v_mfma_f32_16x16x32_bf16 v[38:41], v[176:179], v[200:203], v[38:41]
	v_mfma_f32_16x16x32_bf16 v[34:37], v[184:187], v[200:203], v[34:37]
	v_mfma_f32_16x16x32_bf16 v[22:25], v[176:179], v[208:211], v[22:25]
	v_mfma_f32_16x16x32_bf16 v[18:21], v[184:187], v[208:211], v[18:21]
	v_mfma_f32_16x16x32_bf16 v[6:9], v[176:179], v[216:219], v[6:9]
	v_mfma_f32_16x16x32_bf16 v[2:5], v[184:187], v[216:219], v[2:5]
	s_setprio 0
	s_barrier
	s_add_i32 s56, 0, 0x18000
	v_add_u32_e32 v159, s56, v154
	s_add_i32 s57, 0, 0x1c000
	ds_read_b128 v[146:149], v159
	ds_read_b128 v[150:153], v159 offset:1024
	ds_read_b128 v[164:167], v159 offset:2048
	ds_read_b128 v[168:171], v159 offset:3072
	v_add_u32_e32 v159, s57, v154
	ds_read_b128 v[172:175], v159
	ds_read_b128 v[176:179], v159 offset:1024
	ds_read_b128 v[180:183], v159 offset:2048
	ds_read_b128 v[184:187], v159 offset:3072
	s_add_u32 s36, s36, 0x100000
	s_addc_u32 s37, s37, 0
	s_mov_b32 m0, s42
	ds_read_b128 v[188:191], v158 offset:32768
	ds_read_b128 v[192:195], v158 offset:33792
	ds_read_b128 v[196:199], v158 offset:34816
	ds_read_b128 v[200:203], v158 offset:35840
	ds_read_b128 v[204:207], v158 offset:36864
	ds_read_b128 v[208:211], v158 offset:37888
	ds_read_b128 v[212:215], v158 offset:38912
	ds_read_b128 v[216:219], v158 offset:39936
	s_mov_b32 m0, s29
	s_nop 0
	global_load_lds_dwordx4 v[222:223], off
	s_mov_b32 m0, s41
	s_nop 0
	global_load_lds_dwordx4 v[224:225], off
	s_mov_b32 m0, s42
	s_nop 0
	global_load_lds_dwordx4 v130, s[36:37]
	s_mov_b32 m0, s43
	s_nop 0
	global_load_lds_dwordx4 v134, s[36:37]
	s_waitcnt vmcnt(8)
	s_waitcnt lgkmcnt(0)
	s_setprio 1
	s_barrier
	v_mfma_f32_16x16x32_bf16 v[126:129], v[146:149], v[188:191], v[126:129]
	v_mfma_f32_16x16x32_bf16 v[122:125], v[164:167], v[188:191], v[122:125]
	v_mfma_f32_16x16x32_bf16 v[110:113], v[146:149], v[196:199], v[110:113]
	v_mfma_f32_16x16x32_bf16 v[106:109], v[164:167], v[196:199], v[106:109]
	v_mfma_f32_16x16x32_bf16 v[94:97], v[146:149], v[204:207], v[94:97]
	v_mfma_f32_16x16x32_bf16 v[90:93], v[164:167], v[204:207], v[90:93]
	v_mfma_f32_16x16x32_bf16 v[78:81], v[146:149], v[212:215], v[78:81]
	v_mfma_f32_16x16x32_bf16 v[74:77], v[164:167], v[212:215], v[74:77]
	v_mfma_f32_16x16x32_bf16 v[126:129], v[150:153], v[192:195], v[126:129]
	v_mfma_f32_16x16x32_bf16 v[122:125], v[168:171], v[192:195], v[122:125]
	v_mfma_f32_16x16x32_bf16 v[110:113], v[150:153], v[200:203], v[110:113]
	v_mfma_f32_16x16x32_bf16 v[106:109], v[168:171], v[200:203], v[106:109]
	v_mfma_f32_16x16x32_bf16 v[94:97], v[150:153], v[208:211], v[94:97]
	v_mfma_f32_16x16x32_bf16 v[90:93], v[168:171], v[208:211], v[90:93]
	v_mfma_f32_16x16x32_bf16 v[78:81], v[150:153], v[216:219], v[78:81]
	v_mfma_f32_16x16x32_bf16 v[74:77], v[168:171], v[216:219], v[74:77]
	v_mfma_f32_16x16x32_bf16 v[118:121], v[172:175], v[188:191], v[118:121]
	v_mfma_f32_16x16x32_bf16 v[114:117], v[180:183], v[188:191], v[114:117]
	v_mfma_f32_16x16x32_bf16 v[102:105], v[172:175], v[196:199], v[102:105]
	v_mfma_f32_16x16x32_bf16 v[98:101], v[180:183], v[196:199], v[98:101]
	v_mfma_f32_16x16x32_bf16 v[86:89], v[172:175], v[204:207], v[86:89]
	v_mfma_f32_16x16x32_bf16 v[82:85], v[180:183], v[204:207], v[82:85]
	v_mfma_f32_16x16x32_bf16 v[70:73], v[172:175], v[212:215], v[70:73]
	v_mfma_f32_16x16x32_bf16 v[66:69], v[180:183], v[212:215], v[66:69]
	v_mfma_f32_16x16x32_bf16 v[118:121], v[176:179], v[192:195], v[118:121]
	v_mfma_f32_16x16x32_bf16 v[114:117], v[184:187], v[192:195], v[114:117]
	v_mfma_f32_16x16x32_bf16 v[102:105], v[176:179], v[200:203], v[102:105]
	v_mfma_f32_16x16x32_bf16 v[98:101], v[184:187], v[200:203], v[98:101]
	v_mfma_f32_16x16x32_bf16 v[86:89], v[176:179], v[208:211], v[86:89]
	v_mfma_f32_16x16x32_bf16 v[82:85], v[184:187], v[208:211], v[82:85]
	v_mfma_f32_16x16x32_bf16 v[70:73], v[176:179], v[216:219], v[70:73]
	v_mfma_f32_16x16x32_bf16 v[66:69], v[184:187], v[216:219], v[66:69]
	s_setprio 0
	s_barrier
	s_add_i32 s36, s56, s40
	v_lshl_add_u64 v[160:161], v[160:161], 0, s[10:11]
	s_mov_b32 m0, s36
	ds_read_b128 v[188:191], v158 offset:49152
	ds_read_b128 v[192:195], v158 offset:50176
	ds_read_b128 v[196:199], v158 offset:51200
	ds_read_b128 v[200:203], v158 offset:52224
	ds_read_b128 v[204:207], v158 offset:53248
	ds_read_b128 v[208:211], v158 offset:54272
	ds_read_b128 v[212:215], v158 offset:55296
	ds_read_b128 v[216:219], v158 offset:56320
	global_load_lds_dwordx4 v[160:161], off
	s_add_i32 m0, s36, 0x2000
	s_add_u32 s34, s34, 0x100080
	v_lshl_add_u64 v[160:161], v[220:221], 0, s[10:11]
	s_addc_u32 s35, s35, 0
	s_add_i32 s36, s57, s40
	global_load_lds_dwordx4 v[160:161], off
	s_mov_b32 m0, s36
	s_nop 0
	global_load_lds_dwordx4 v132, s[34:35]
	s_add_i32 m0, s36, 0x2000
	s_nop 0
	global_load_lds_dwordx4 v136, s[34:35]
	v_lshl_add_u64 v[222:223], v[222:223], 0, s[10:11]
	v_lshl_add_u64 v[224:225], v[224:225], 0, s[10:11]
	s_waitcnt vmcnt(6)
	s_waitcnt lgkmcnt(0)
	s_setprio 1
	s_barrier
	v_mfma_f32_16x16x32_bf16 v[62:65], v[146:149], v[188:191], v[62:65]
	v_mfma_f32_16x16x32_bf16 v[58:61], v[164:167], v[188:191], v[58:61]
	v_mfma_f32_16x16x32_bf16 v[46:49], v[146:149], v[196:199], v[46:49]
	v_mfma_f32_16x16x32_bf16 v[42:45], v[164:167], v[196:199], v[42:45]
	v_mfma_f32_16x16x32_bf16 v[30:33], v[146:149], v[204:207], v[30:33]
	v_mfma_f32_16x16x32_bf16 v[26:29], v[164:167], v[204:207], v[26:29]
	v_mfma_f32_16x16x32_bf16 v[14:17], v[146:149], v[212:215], v[14:17]
	v_mfma_f32_16x16x32_bf16 v[10:13], v[164:167], v[212:215], v[10:13]
	v_mfma_f32_16x16x32_bf16 v[62:65], v[150:153], v[192:195], v[62:65]
	v_mfma_f32_16x16x32_bf16 v[58:61], v[168:171], v[192:195], v[58:61]
	v_mfma_f32_16x16x32_bf16 v[46:49], v[150:153], v[200:203], v[46:49]
	v_mfma_f32_16x16x32_bf16 v[42:45], v[168:171], v[200:203], v[42:45]
	v_mfma_f32_16x16x32_bf16 v[30:33], v[150:153], v[208:211], v[30:33]
	v_mfma_f32_16x16x32_bf16 v[26:29], v[168:171], v[208:211], v[26:29]
	v_mfma_f32_16x16x32_bf16 v[14:17], v[150:153], v[216:219], v[14:17]
	v_mfma_f32_16x16x32_bf16 v[10:13], v[168:171], v[216:219], v[10:13]
	v_mfma_f32_16x16x32_bf16 v[54:57], v[172:175], v[188:191], v[54:57]
	v_mfma_f32_16x16x32_bf16 v[50:53], v[180:183], v[188:191], v[50:53]
	v_mfma_f32_16x16x32_bf16 v[38:41], v[172:175], v[196:199], v[38:41]
	v_mfma_f32_16x16x32_bf16 v[34:37], v[180:183], v[196:199], v[34:37]
	v_mfma_f32_16x16x32_bf16 v[22:25], v[172:175], v[204:207], v[22:25]
	v_mfma_f32_16x16x32_bf16 v[18:21], v[180:183], v[204:207], v[18:21]
	v_mfma_f32_16x16x32_bf16 v[6:9], v[172:175], v[212:215], v[6:9]
	v_mfma_f32_16x16x32_bf16 v[2:5], v[180:183], v[212:215], v[2:5]
	v_mfma_f32_16x16x32_bf16 v[54:57], v[176:179], v[192:195], v[54:57]
	v_mfma_f32_16x16x32_bf16 v[50:53], v[184:187], v[192:195], v[50:53]
	v_mfma_f32_16x16x32_bf16 v[38:41], v[176:179], v[200:203], v[38:41]
	v_mfma_f32_16x16x32_bf16 v[34:37], v[184:187], v[200:203], v[34:37]
	v_mfma_f32_16x16x32_bf16 v[22:25], v[176:179], v[208:211], v[22:25]
	v_mfma_f32_16x16x32_bf16 v[18:21], v[184:187], v[208:211], v[18:21]
	v_mfma_f32_16x16x32_bf16 v[6:9], v[176:179], v[216:219], v[6:9]
	v_mfma_f32_16x16x32_bf16 v[2:5], v[184:187], v[216:219], v[2:5]
	s_setprio 0
	s_barrier
	s_add_i32 s55, s55, 2
	s_mov_b32 s32, 1
	s_add_u32 s30, s30, 0x100
	s_addc_u32 s31, s31, 0
	s_add_u32 s53, s53, 0x100
	s_addc_u32 s54, s54, 0
	s_cmp_gt_u32 s55, 61
	s_cbranch_scc0 .LBB0_1983
	s_and_b64 vcc, exec, s[12:13]
	s_cbranch_vccz .LBB0_1986
	s_barrier
